# stack: packed paired-rcp REG2 epilogue, rstd prefetch, peeled first K iteration, S count prefetch, three XCD-local barriers
# speedup vs baseline: 1.0045x; 1.0030x over previous
.LBB0_190:
	s_lshl_b32 s14, s14, 12
	s_lshl_b32 s21, s15, 13
	s_and_b32 s22, s14, 0x3000
	s_mov_b64 s[14:15], 0x80
	s_add_i32 s61, s5, 0x18000
	v_lshl_add_u64 v[0:1], v[0:1], 0, s[14:15]
	s_mov_b32 m0, s61
	s_add_i32 s62, s5, 0x1a000
	s_waitcnt vmcnt(2)
	s_barrier
	global_load_lds_dwordx4 v[0:1], off
	v_lshl_add_u64 v[0:1], v[2:3], 0, s[14:15]
	s_mov_b32 m0, s62
	s_add_i32 s63, s5, 0x8000
	s_add_i32 s64, s5, 0xa000
	global_load_lds_dwordx4 v[0:1], off
	v_lshl_add_u64 v[0:1], v[6:7], 0, s[14:15]
	s_mov_b32 m0, s63
	s_add_u32 s16, s52, 0x40080
	global_load_lds_dwordx4 v[0:1], off
	v_lshl_add_u64 v[0:1], v[4:5], 0, s[14:15]
	s_mov_b32 m0, s64
	s_addc_u32 s17, s53, 0
	s_add_i32 s65, s5, 0x1c000
	global_load_lds_dwordx4 v[0:1], off
	v_lshl_add_u64 v[0:1], v[72:73], 1, s[16:17]
	s_mov_b32 m0, s65
	s_add_i32 s67, s5, 0x1e000
	global_load_lds_dwordx4 v[0:1], off
	v_lshl_add_u64 v[0:1], v[74:75], 1, s[16:17]
	s_mov_b32 m0, s67
	v_and_b32_e32 v2, 3, v10
	global_load_lds_dwordx4 v[0:1], off
	v_lshlrev_b32_e32 v0, 1, v150
	v_lshrrev_b32_e32 v1, 2, v150
	s_movk_i32 s16, 0xffe0
	v_and_b32_e32 v0, 24, v0
	v_and_b32_e32 v1, 4, v1
	v_and_or_b32 v2, v150, s16, v2
	v_or3_b32 v154, v2, v0, v1
	v_lshlrev_b32_e32 v0, 1, v152
	v_lshrrev_b32_e32 v1, 2, v152
	v_and_b32_e32 v2, 3, v14
	v_and_b32_e32 v0, 24, v0
	v_and_b32_e32 v1, 4, v1
	v_and_or_b32 v2, v152, s16, v2
	v_or3_b32 v155, v2, v0, v1
	v_and_b32_e32 v0, 15, v8
	v_lshlrev_b32_e32 v3, 2, v8
	v_and_b32_e32 v1, 48, v8
	v_lshlrev_b32_e32 v0, 6, v0
	v_and_b32_e32 v3, 32, v3
	v_or_b32_e32 v2, v0, v1
	v_bitop3_b32 v0, v0, v3, v1 bitop3:0x36
	v_or_b32_e32 v5, s22, v0
	v_lshlrev_b32_e32 v0, 13, v9
	v_and_b32_e32 v0, 0xffffc000, v0
	v_lshl_add_u32 v0, v10, 10, v0
	v_or_b32_e32 v0, v0, v11
	v_add_u32_sdwa v0, v0, sext(v13) dst_sel:DWORD dst_unused:UNUSED_PAD src0_sel:DWORD src1_sel:WORD_0
	v_bitop3_b32 v4, v2, s21, v3 bitop3:0xde
	v_ashrrev_i32_e32 v1, 31, v0
	v_mov_b64_e32 v[2:3], 0x40080
	v_lshl_add_u64 v[140:141], v[0:1], 1, v[2:3]
	v_lshlrev_b32_e32 v0, 13, v12
	v_and_b32_e32 v0, 0xffffc000, v0
	v_lshl_add_u32 v0, v14, 10, v0
	v_or_b32_e32 v0, v0, v15
	s_ashr_i32 s68, s28, 31
	s_ashr_i32 s70, s2, 31
	s_ashr_i32 s71, s2, 3
	s_ashr_i32 s72, s28, 3
	s_and_b32 s73, s2, 7
	v_add_u32_sdwa v0, v0, sext(v16) dst_sel:DWORD dst_unused:UNUSED_PAD src0_sel:DWORD src1_sel:WORD_0
	s_waitcnt vmcnt(0)
	s_cmpk_lt_u32 s20, 0x100
	v_ashrrev_i32_e32 v1, 31, v0
	s_cselect_b64 s[16:17], -1, 0
	s_add_u32 s74, s26, 0x1e7e5000
	v_lshl_add_u64 v[142:143], v[0:1], 1, v[2:3]
	v_add_u32_e32 v0, 0, v5
	s_mov_b32 s69, s28
	s_addc_u32 s75, s27, 0
	v_add_u32_e32 v156, 0x10000, v0
	v_add_u32_e32 v157, 0x14000, v0
	v_add_u32_e32 v158, 0, v4
	s_add_i32 s76, s5, 0xc000
	s_add_i32 s77, s5, 0xe000
	v_add_u32_e32 v159, 0x18000, v0
	v_add_u32_e32 v160, 0x1c000, v0
	s_mov_b32 s78, 0x16300000
	s_movk_i32 s79, 0xee00
	v_mov_b32_e32 v145, 0
	v_mov_b64_e32 v[146:147], 0x5ff
	s_mov_b32 s80, 0
	s_barrier
	s_branch .LBB0_193

; template <int REG>
; DI void epi_inproj(const Params& p, f32x4 (&acc)[2][2][4][2], int pm, int pn, LAS unsigned char* shm) {
;     ...
;     const f32x4 q0 = *(const f32x4*)((const float*)(ws + OFF_RSTD1Q) + T0 + (wr * 16 + fr) * 8), q1 = *(const f32x4*)((const float*)(ws + OFF_RSTD1Q) + T0 + (wr * 16 + fr) * 8 + 4);
.LBB0_193:
	s_lshl_b32 s98, s46, 10
	s_add_u32 s98, s74, s98
	s_addc_u32 s99, s75, 0
	v_and_b32_e32 v246, 15, v194
	v_ashrrev_i32_e32 v247, 8, v194
	v_lshlrev_b32_e32 v246, 5, v246
	v_lshl_or_b32 v246, v247, 9, v246
	global_load_dwordx4 v[238:241], v246, s[98:99]
	global_load_dwordx4 v[242:245], v246, s[98:99] offset:16
	s_add_i32 s80, s80, 1
	s_and_b64 vcc, exec, s[34:35]
	s_mov_b64 s[56:57], -1
	s_cbranch_vccz .LBB0_196
	s_mul_i32 s40, s80, s68
	s_mul_hi_u32 s41, s80, s69
	s_add_i32 s41, s41, s40
	s_mul_i32 s40, s80, s69
	s_add_u32 s58, s40, s2
	s_addc_u32 s59, s41, s70
	v_cmp_gt_i64_e32 vcc, s[58:59], v[146:147]
	s_mov_b64 s[56:57], 0
	s_mov_b64 s[40:41], 0
	s_cbranch_vccnz .LBB0_196
	s_mul_i32 s81, s59, 0xaaaaaaab
	s_mul_hi_u32 s82, s58, 0xaaaaaaab
	s_mul_hi_u32 s54, s59, 0xaaaaaaab
	s_add_u32 s81, s81, s82
	s_mul_i32 s41, s58, 0x2aaaaaaa
	s_addc_u32 s54, s54, 0
	s_mul_hi_u32 s40, s58, 0x2aaaaaaa
	s_add_u32 s41, s41, s81
	s_addc_u32 s40, s40, 0
	s_add_u32 s40, s54, s40
	s_addc_u32 s41, 0, 0
	s_mul_i32 s81, s59, 0x2aaaaaaa
	s_mul_hi_u32 s54, s59, 0x2aaaaaaa
	s_add_u32 s40, s81, s40
	s_addc_u32 s41, s54, s41
	s_ashr_i32 s54, s59, 31
	s_mul_i32 s59, s54, 0x2aaaaaaa
	s_mul_hi_u32 s81, s54, 0xaaaaaaab
	s_add_i32 s59, s81, s59
	s_mul_i32 s54, s54, 0xaaaaaaab
	s_add_i32 s59, s59, s54
	s_add_u32 s40, s40, s54
	s_addc_u32 s41, s41, s59
	s_lshr_b32 s54, s41, 31
	s_lshr_b64 s[40:41], s[40:41], 1
	s_add_i32 s54, s40, s54
	s_mul_i32 s40, s54, 12
	s_sub_i32 s81, s58, s40
	s_mov_b64 s[40:41], -1

.LBB0_203:
	s_cmp_eq_u32 s55, 0
	s_cselect_b64 vcc, -1, 0
	v_cndmask_b32_e32 v0, v154, v150, vcc
	v_lshl_add_u32 v161, v0, 10, v151
	v_cndmask_b32_e32 v0, v155, v152, vcc
	v_lshl_add_u32 v162, v0, 10, v153
	s_add_u32 s58, s52, 0x100
	v_mov_b32_e32 v0, 0
	s_mov_b32 s60, s55
	s_addc_u32 s59, s53, 0
	s_mov_b32 s81, -2
	v_mov_b32_e32 v1, v0
	v_mov_b32_e32 v2, v0
	v_mov_b32_e32 v3, v0
	v_mov_b32_e32 v4, v0
	v_mov_b32_e32 v5, v0
	v_mov_b32_e32 v6, v0
	v_mov_b32_e32 v7, v0
	v_mov_b32_e32 v16, v0
	v_mov_b32_e32 v17, v0
	v_mov_b32_e32 v18, v0
	v_mov_b32_e32 v19, v0
	v_mov_b32_e32 v20, v0
	v_mov_b32_e32 v21, v0
	v_mov_b32_e32 v22, v0
	v_mov_b32_e32 v23, v0
	v_mov_b32_e32 v32, v0
	v_mov_b32_e32 v33, v0
	v_mov_b32_e32 v34, v0
	v_mov_b32_e32 v35, v0
	v_mov_b32_e32 v36, v0
	v_mov_b32_e32 v37, v0
	v_mov_b32_e32 v38, v0
	v_mov_b32_e32 v39, v0
	v_mov_b32_e32 v48, v0
	v_mov_b32_e32 v49, v0
	v_mov_b32_e32 v50, v0
	v_mov_b32_e32 v51, v0
	v_mov_b32_e32 v52, v0
	v_mov_b32_e32 v53, v0
	v_mov_b32_e32 v54, v0
	v_mov_b32_e32 v55, v0
	v_mov_b32_e32 v8, v0
	v_mov_b32_e32 v9, v0
	v_mov_b32_e32 v10, v0
	v_mov_b32_e32 v11, v0
	v_mov_b32_e32 v12, v0
	v_mov_b32_e32 v13, v0
	v_mov_b32_e32 v14, v0
	v_mov_b32_e32 v15, v0
	v_mov_b32_e32 v24, v0
	v_mov_b32_e32 v25, v0
	v_mov_b32_e32 v26, v0
	v_mov_b32_e32 v27, v0
	v_mov_b32_e32 v28, v0
	v_mov_b32_e32 v29, v0
	v_mov_b32_e32 v30, v0
	v_mov_b32_e32 v31, v0
	v_mov_b32_e32 v40, v0
	v_mov_b32_e32 v41, v0
	v_mov_b32_e32 v42, v0
	v_mov_b32_e32 v43, v0
	v_mov_b32_e32 v44, v0
	v_mov_b32_e32 v45, v0
	v_mov_b32_e32 v46, v0
	v_mov_b32_e32 v47, v0
	v_mov_b32_e32 v56, v0
	v_mov_b32_e32 v57, v0
	v_mov_b32_e32 v58, v0
	v_mov_b32_e32 v59, v0
	v_mov_b32_e32 v60, v0
	v_mov_b32_e32 v61, v0
	v_mov_b32_e32 v62, v0
	v_mov_b32_e32 v63, v0
	v_mov_b32_e32 v64, v0
	v_mov_b32_e32 v65, v0
	v_mov_b32_e32 v66, v0
	v_mov_b32_e32 v67, v0
	v_mov_b32_e32 v68, v0
	v_mov_b32_e32 v69, v0
	v_mov_b32_e32 v70, v0
	v_mov_b32_e32 v71, v0
	v_mov_b32_e32 v84, v0
	v_mov_b32_e32 v85, v0
	v_mov_b32_e32 v86, v0
	v_mov_b32_e32 v87, v0
	v_mov_b32_e32 v88, v0
	v_mov_b32_e32 v89, v0
	v_mov_b32_e32 v90, v0
	v_mov_b32_e32 v91, v0
	v_mov_b32_e32 v100, v0
	v_mov_b32_e32 v101, v0
	v_mov_b32_e32 v102, v0
	v_mov_b32_e32 v103, v0
	v_mov_b32_e32 v104, v0
	v_mov_b32_e32 v105, v0
	v_mov_b32_e32 v106, v0
	v_mov_b32_e32 v107, v0
	v_mov_b32_e32 v116, v0
	v_mov_b32_e32 v117, v0
	v_mov_b32_e32 v118, v0
	v_mov_b32_e32 v119, v0
	v_mov_b32_e32 v120, v0
	v_mov_b32_e32 v121, v0
	v_mov_b32_e32 v122, v0
	v_mov_b32_e32 v123, v0
	v_mov_b32_e32 v76, v0
	v_mov_b32_e32 v77, v0
	v_mov_b32_e32 v78, v0
	v_mov_b32_e32 v79, v0
	v_mov_b32_e32 v80, v0
	v_mov_b32_e32 v81, v0
	v_mov_b32_e32 v82, v0
	v_mov_b32_e32 v83, v0
	v_mov_b32_e32 v92, v0
	v_mov_b32_e32 v93, v0
	v_mov_b32_e32 v94, v0
	v_mov_b32_e32 v95, v0
	v_mov_b32_e32 v96, v0
	v_mov_b32_e32 v97, v0
	v_mov_b32_e32 v98, v0
	v_mov_b32_e32 v99, v0
	v_mov_b32_e32 v108, v0
	v_mov_b32_e32 v109, v0
	v_mov_b32_e32 v110, v0
	v_mov_b32_e32 v111, v0
	v_mov_b32_e32 v112, v0
	v_mov_b32_e32 v113, v0
	v_mov_b32_e32 v114, v0
	v_mov_b32_e32 v115, v0
	v_mov_b32_e32 v124, v0
	v_mov_b32_e32 v125, v0
	v_mov_b32_e32 v126, v0
	v_mov_b32_e32 v127, v0
	v_mov_b32_e32 v128, v0
	v_mov_b32_e32 v129, v0
	v_mov_b32_e32 v130, v0
	v_mov_b32_e32 v131, v0
	ds_read_b128 v[132:135], v156
	ds_read_b128 v[164:167], v156 offset:1024
	ds_read_b128 v[168:171], v156 offset:2048
	ds_read_b128 v[172:175], v156 offset:3072
	ds_read_b128 v[176:179], v157
	ds_read_b128 v[180:183], v157 offset:1024
	ds_read_b128 v[184:187], v157 offset:2048
	ds_read_b128 v[188:191], v157 offset:3072
	s_add_u32 s52, s50, 0x100
	s_addc_u32 s53, s51, 0
	s_cmp_eq_u32 s81, 12
	s_cselect_b64 vcc, -1, 0
	s_and_b64 s[54:55], vcc, exec
	v_cndmask_b32_e32 v148, v74, v162, vcc
	s_cselect_b32 s57, s23, s53
	s_cselect_b32 s56, s22, s52
	v_cndmask_b32_e32 v192, v72, v161, vcc
	s_cselect_b32 s55, s39, s59
	s_cselect_b32 s54, s38, s58
	s_mov_b32 m0, s76
	v_lshl_add_u64 v[228:229], s[50:51], 0, v[140:141]
	ds_read_b128 v[196:199], v158
	ds_read_b128 v[200:203], v158 offset:1024
	ds_read_b128 v[204:207], v158 offset:2048
	ds_read_b128 v[208:211], v158 offset:3072
	ds_read_b128 v[212:215], v158 offset:4096
	ds_read_b128 v[216:219], v158 offset:5120
	ds_read_b128 v[220:223], v158 offset:6144
	ds_read_b128 v[224:227], v158 offset:7168
	global_load_lds_dwordx4 v[228:229], off
	v_lshl_add_u64 v[228:229], s[50:51], 0, v[142:143]
	s_mov_b32 m0, s77
	s_nop 0
	global_load_lds_dwordx4 v[228:229], off
	s_waitcnt lgkmcnt(0)
	s_barrier
	s_setprio 1
	s_waitcnt lgkmcnt(0)
	v_mfma_f32_16x16x32_bf16 v[128:131], v[132:135], v[196:199], v[128:131]
	v_mfma_f32_16x16x32_bf16 v[124:127], v[168:171], v[196:199], v[124:127]
	v_mfma_f32_16x16x32_bf16 v[112:115], v[132:135], v[204:207], v[112:115]
	v_mfma_f32_16x16x32_bf16 v[108:111], v[168:171], v[204:207], v[108:111]
	v_mfma_f32_16x16x32_bf16 v[96:99], v[132:135], v[212:215], v[96:99]
	v_mfma_f32_16x16x32_bf16 v[92:95], v[168:171], v[212:215], v[92:95]
	v_mfma_f32_16x16x32_bf16 v[80:83], v[132:135], v[220:223], v[80:83]
	v_mfma_f32_16x16x32_bf16 v[76:79], v[168:171], v[220:223], v[76:79]
	v_mfma_f32_16x16x32_bf16 v[128:131], v[164:167], v[200:203], v[128:131]
	v_mfma_f32_16x16x32_bf16 v[124:127], v[172:175], v[200:203], v[124:127]
	v_mfma_f32_16x16x32_bf16 v[112:115], v[164:167], v[208:211], v[112:115]
	v_mfma_f32_16x16x32_bf16 v[108:111], v[172:175], v[208:211], v[108:111]
	v_mfma_f32_16x16x32_bf16 v[96:99], v[164:167], v[216:219], v[96:99]
	v_mfma_f32_16x16x32_bf16 v[92:95], v[172:175], v[216:219], v[92:95]
	v_mfma_f32_16x16x32_bf16 v[80:83], v[164:167], v[224:227], v[80:83]
	v_mfma_f32_16x16x32_bf16 v[76:79], v[172:175], v[224:227], v[76:79]
	s_setprio 0
	s_setprio 1
	v_mfma_f32_16x16x32_bf16 v[120:123], v[176:179], v[196:199], v[120:123]
	v_mfma_f32_16x16x32_bf16 v[116:119], v[184:187], v[196:199], v[116:119]
	v_mfma_f32_16x16x32_bf16 v[104:107], v[176:179], v[204:207], v[104:107]
	v_mfma_f32_16x16x32_bf16 v[100:103], v[184:187], v[204:207], v[100:103]
	v_mfma_f32_16x16x32_bf16 v[88:91], v[176:179], v[212:215], v[88:91]
	v_mfma_f32_16x16x32_bf16 v[84:87], v[184:187], v[212:215], v[84:87]
	v_mfma_f32_16x16x32_bf16 v[68:71], v[176:179], v[220:223], v[68:71]
	v_mfma_f32_16x16x32_bf16 v[64:67], v[184:187], v[220:223], v[64:67]
	v_mfma_f32_16x16x32_bf16 v[120:123], v[180:183], v[200:203], v[120:123]
	v_mfma_f32_16x16x32_bf16 v[116:119], v[188:191], v[200:203], v[116:119]
	v_mfma_f32_16x16x32_bf16 v[104:107], v[180:183], v[208:211], v[104:107]
	v_mfma_f32_16x16x32_bf16 v[100:103], v[188:191], v[208:211], v[100:103]
	v_mfma_f32_16x16x32_bf16 v[88:91], v[180:183], v[216:219], v[88:91]
	v_mfma_f32_16x16x32_bf16 v[84:87], v[188:191], v[216:219], v[84:87]
	v_mfma_f32_16x16x32_bf16 v[68:71], v[180:183], v[224:227], v[68:71]
	v_mfma_f32_16x16x32_bf16 v[64:67], v[188:191], v[224:227], v[64:67]
	s_setprio 0
	s_barrier
	v_ashrrev_i32_e32 v193, 31, v192
	v_lshlrev_b64 v[192:193], 1, v[192:193]
	v_ashrrev_i32_e32 v149, 31, v148
	s_mov_b32 m0, s7
	v_lshl_add_u64 v[228:229], s[54:55], 0, v[192:193]
	v_lshlrev_b64 v[148:149], 1, v[148:149]
	s_add_u32 s50, s54, 0x40000
	ds_read_b128 v[196:199], v158 offset:16384
	ds_read_b128 v[200:203], v158 offset:17408
	ds_read_b128 v[204:207], v158 offset:18432
	ds_read_b128 v[208:211], v158 offset:19456
	ds_read_b128 v[212:215], v158 offset:20480
	ds_read_b128 v[216:219], v158 offset:21504
	ds_read_b128 v[220:223], v158 offset:22528
	ds_read_b128 v[224:227], v158 offset:23552
	global_load_lds_dwordx4 v[228:229], off
	v_lshl_add_u64 v[230:231], s[54:55], 0, v[148:149]
	s_mov_b32 m0, s18
	s_addc_u32 s51, s55, 0
	global_load_lds_dwordx4 v[230:231], off
	v_lshl_add_u64 v[232:233], s[50:51], 0, v[192:193]
	s_mov_b32 m0, s19
	v_lshl_add_u64 v[234:235], s[56:57], 0, v[138:139]
	global_load_lds_dwordx4 v[232:233], off
	v_lshl_add_u64 v[232:233], s[50:51], 0, v[148:149]
	s_mov_b32 m0, s30
	s_nop 0
	global_load_lds_dwordx4 v[232:233], off
	v_lshl_add_u64 v[232:233], s[56:57], 0, v[136:137]
	s_mov_b32 m0, s5
	s_nop 0
	global_load_lds_dwordx4 v[232:233], off
	s_mov_b32 m0, s31
	s_nop 0
	global_load_lds_dwordx4 v[234:235], off
	s_waitcnt lgkmcnt(0)
	s_barrier
	s_setprio 1
	s_waitcnt lgkmcnt(0)
	v_mfma_f32_16x16x32_bf16 v[60:63], v[132:135], v[196:199], v[60:63]
	v_mfma_f32_16x16x32_bf16 v[56:59], v[168:171], v[196:199], v[56:59]
	v_mfma_f32_16x16x32_bf16 v[44:47], v[132:135], v[204:207], v[44:47]
	v_mfma_f32_16x16x32_bf16 v[40:43], v[168:171], v[204:207], v[40:43]
	v_mfma_f32_16x16x32_bf16 v[28:31], v[132:135], v[212:215], v[28:31]
	v_mfma_f32_16x16x32_bf16 v[24:27], v[168:171], v[212:215], v[24:27]
	v_mfma_f32_16x16x32_bf16 v[12:15], v[132:135], v[220:223], v[12:15]
	v_mfma_f32_16x16x32_bf16 v[8:11], v[168:171], v[220:223], v[8:11]
	v_mfma_f32_16x16x32_bf16 v[60:63], v[164:167], v[200:203], v[60:63]
	v_mfma_f32_16x16x32_bf16 v[56:59], v[172:175], v[200:203], v[56:59]
	v_mfma_f32_16x16x32_bf16 v[44:47], v[164:167], v[208:211], v[44:47]
	v_mfma_f32_16x16x32_bf16 v[40:43], v[172:175], v[208:211], v[40:43]
	v_mfma_f32_16x16x32_bf16 v[28:31], v[164:167], v[216:219], v[28:31]
	v_mfma_f32_16x16x32_bf16 v[24:27], v[172:175], v[216:219], v[24:27]
	v_mfma_f32_16x16x32_bf16 v[12:15], v[164:167], v[224:227], v[12:15]
	v_mfma_f32_16x16x32_bf16 v[8:11], v[172:175], v[224:227], v[8:11]
	s_setprio 0
	s_setprio 1
	v_mfma_f32_16x16x32_bf16 v[52:55], v[176:179], v[196:199], v[52:55]
	v_mfma_f32_16x16x32_bf16 v[48:51], v[184:187], v[196:199], v[48:51]
	v_mfma_f32_16x16x32_bf16 v[36:39], v[176:179], v[204:207], v[36:39]
	v_mfma_f32_16x16x32_bf16 v[32:35], v[184:187], v[204:207], v[32:35]
	v_mfma_f32_16x16x32_bf16 v[20:23], v[176:179], v[212:215], v[20:23]
	v_mfma_f32_16x16x32_bf16 v[16:19], v[184:187], v[212:215], v[16:19]
	v_mfma_f32_16x16x32_bf16 v[4:7], v[176:179], v[220:223], v[4:7]
	v_mfma_f32_16x16x32_bf16 v[0:3], v[184:187], v[220:223], v[0:3]
	v_mfma_f32_16x16x32_bf16 v[52:55], v[180:183], v[200:203], v[52:55]
	v_mfma_f32_16x16x32_bf16 v[48:51], v[188:191], v[200:203], v[48:51]
	v_mfma_f32_16x16x32_bf16 v[36:39], v[180:183], v[208:211], v[36:39]
	v_mfma_f32_16x16x32_bf16 v[32:35], v[188:191], v[208:211], v[32:35]
	v_mfma_f32_16x16x32_bf16 v[20:23], v[180:183], v[216:219], v[20:23]
	v_mfma_f32_16x16x32_bf16 v[16:19], v[188:191], v[216:219], v[16:19]
	v_mfma_f32_16x16x32_bf16 v[4:7], v[180:183], v[224:227], v[4:7]
	v_mfma_f32_16x16x32_bf16 v[0:3], v[188:191], v[224:227], v[0:3]
	s_setprio 0
	s_barrier
	ds_read_b128 v[132:135], v159
	ds_read_b128 v[164:167], v159 offset:1024
	ds_read_b128 v[168:171], v159 offset:2048
	ds_read_b128 v[172:175], v159 offset:3072
	ds_read_b128 v[176:179], v160
	ds_read_b128 v[180:183], v160 offset:1024
	ds_read_b128 v[184:187], v160 offset:2048
	ds_read_b128 v[188:191], v160 offset:3072
	s_add_u32 s50, s56, 0x40000
	s_addc_u32 s51, s57, 0
	s_mov_b32 m0, s47
	v_lshl_add_u64 v[236:237], s[50:51], 0, v[136:137]
	ds_read_b128 v[196:199], v158 offset:32768
	ds_read_b128 v[200:203], v158 offset:33792
	ds_read_b128 v[204:207], v158 offset:34816
	ds_read_b128 v[208:211], v158 offset:35840
	ds_read_b128 v[212:215], v158 offset:36864
	ds_read_b128 v[216:219], v158 offset:37888
	ds_read_b128 v[220:223], v158 offset:38912
	ds_read_b128 v[224:227], v158 offset:39936
	global_load_lds_dwordx4 v[236:237], off
	v_lshl_add_u64 v[236:237], s[50:51], 0, v[138:139]
	s_mov_b32 m0, s49
	s_nop 0
	global_load_lds_dwordx4 v[236:237], off
	s_waitcnt vmcnt(8)
	s_waitcnt lgkmcnt(0)
	s_barrier
	s_setprio 1
	s_waitcnt lgkmcnt(0)
	v_mfma_f32_16x16x32_bf16 v[128:131], v[132:135], v[196:199], v[128:131]
	v_mfma_f32_16x16x32_bf16 v[124:127], v[168:171], v[196:199], v[124:127]
	v_mfma_f32_16x16x32_bf16 v[112:115], v[132:135], v[204:207], v[112:115]
	v_mfma_f32_16x16x32_bf16 v[108:111], v[168:171], v[204:207], v[108:111]
	v_mfma_f32_16x16x32_bf16 v[96:99], v[132:135], v[212:215], v[96:99]
	v_mfma_f32_16x16x32_bf16 v[92:95], v[168:171], v[212:215], v[92:95]
	v_mfma_f32_16x16x32_bf16 v[80:83], v[132:135], v[220:223], v[80:83]
	v_mfma_f32_16x16x32_bf16 v[76:79], v[168:171], v[220:223], v[76:79]
	v_mfma_f32_16x16x32_bf16 v[128:131], v[164:167], v[200:203], v[128:131]
	v_mfma_f32_16x16x32_bf16 v[124:127], v[172:175], v[200:203], v[124:127]
	v_mfma_f32_16x16x32_bf16 v[112:115], v[164:167], v[208:211], v[112:115]
	v_mfma_f32_16x16x32_bf16 v[108:111], v[172:175], v[208:211], v[108:111]
	v_mfma_f32_16x16x32_bf16 v[96:99], v[164:167], v[216:219], v[96:99]
	v_mfma_f32_16x16x32_bf16 v[92:95], v[172:175], v[216:219], v[92:95]
	v_mfma_f32_16x16x32_bf16 v[80:83], v[164:167], v[224:227], v[80:83]
	v_mfma_f32_16x16x32_bf16 v[76:79], v[172:175], v[224:227], v[76:79]
	s_setprio 0
	s_setprio 1
	v_mfma_f32_16x16x32_bf16 v[120:123], v[176:179], v[196:199], v[120:123]
	v_mfma_f32_16x16x32_bf16 v[116:119], v[184:187], v[196:199], v[116:119]
	v_mfma_f32_16x16x32_bf16 v[104:107], v[176:179], v[204:207], v[104:107]
	v_mfma_f32_16x16x32_bf16 v[100:103], v[184:187], v[204:207], v[100:103]
	v_mfma_f32_16x16x32_bf16 v[88:91], v[176:179], v[212:215], v[88:91]
	v_mfma_f32_16x16x32_bf16 v[84:87], v[184:187], v[212:215], v[84:87]
	v_mfma_f32_16x16x32_bf16 v[68:71], v[176:179], v[220:223], v[68:71]
	v_mfma_f32_16x16x32_bf16 v[64:67], v[184:187], v[220:223], v[64:67]
	v_mfma_f32_16x16x32_bf16 v[120:123], v[180:183], v[200:203], v[120:123]
	v_mfma_f32_16x16x32_bf16 v[116:119], v[188:191], v[200:203], v[116:119]
	v_mfma_f32_16x16x32_bf16 v[104:107], v[180:183], v[208:211], v[104:107]
	v_mfma_f32_16x16x32_bf16 v[100:103], v[188:191], v[208:211], v[100:103]
	v_mfma_f32_16x16x32_bf16 v[88:91], v[180:183], v[216:219], v[88:91]
	v_mfma_f32_16x16x32_bf16 v[84:87], v[188:191], v[216:219], v[84:87]
	v_mfma_f32_16x16x32_bf16 v[68:71], v[180:183], v[224:227], v[68:71]
	v_mfma_f32_16x16x32_bf16 v[64:67], v[188:191], v[224:227], v[64:67]
	s_setprio 0
	s_barrier
	s_mov_b32 m0, s61
	v_lshl_add_u64 v[228:229], v[228:229], 0, s[14:15]
	s_add_u32 s50, s54, 0x40080
	ds_read_b128 v[196:199], v158 offset:49152
	ds_read_b128 v[200:203], v158 offset:50176
	ds_read_b128 v[204:207], v158 offset:51200
	ds_read_b128 v[208:211], v158 offset:52224
	ds_read_b128 v[212:215], v158 offset:53248
	ds_read_b128 v[216:219], v158 offset:54272
	ds_read_b128 v[220:223], v158 offset:55296
	ds_read_b128 v[224:227], v158 offset:56320
	global_load_lds_dwordx4 v[228:229], off
	v_lshl_add_u64 v[228:229], v[230:231], 0, s[14:15]
	s_mov_b32 m0, s62
	s_addc_u32 s51, s55, 0
	global_load_lds_dwordx4 v[228:229], off
	v_lshl_add_u64 v[192:193], s[50:51], 0, v[192:193]
	s_mov_b32 m0, s65
	v_lshl_add_u64 v[148:149], s[50:51], 0, v[148:149]
	global_load_lds_dwordx4 v[192:193], off
	s_mov_b32 m0, s67
	s_nop 0
	global_load_lds_dwordx4 v[148:149], off
	v_lshl_add_u64 v[148:149], v[232:233], 0, s[14:15]
	s_mov_b32 m0, s63
	s_nop 0
	global_load_lds_dwordx4 v[148:149], off
	v_lshl_add_u64 v[148:149], v[234:235], 0, s[14:15]
	s_mov_b32 m0, s64
	s_nop 0
	global_load_lds_dwordx4 v[148:149], off
	s_waitcnt vmcnt(8)
	s_waitcnt lgkmcnt(0)
	s_barrier
	s_setprio 1
	s_waitcnt lgkmcnt(0)
	v_mfma_f32_16x16x32_bf16 v[60:63], v[132:135], v[196:199], v[60:63]
	v_mfma_f32_16x16x32_bf16 v[56:59], v[168:171], v[196:199], v[56:59]
	v_mfma_f32_16x16x32_bf16 v[44:47], v[132:135], v[204:207], v[44:47]
	v_mfma_f32_16x16x32_bf16 v[40:43], v[168:171], v[204:207], v[40:43]
	v_mfma_f32_16x16x32_bf16 v[28:31], v[132:135], v[212:215], v[28:31]
	v_mfma_f32_16x16x32_bf16 v[24:27], v[168:171], v[212:215], v[24:27]
	v_mfma_f32_16x16x32_bf16 v[12:15], v[132:135], v[220:223], v[12:15]
	v_mfma_f32_16x16x32_bf16 v[8:11], v[168:171], v[220:223], v[8:11]
	v_mfma_f32_16x16x32_bf16 v[60:63], v[164:167], v[200:203], v[60:63]
	v_mfma_f32_16x16x32_bf16 v[56:59], v[172:175], v[200:203], v[56:59]
	v_mfma_f32_16x16x32_bf16 v[44:47], v[164:167], v[208:211], v[44:47]
	v_mfma_f32_16x16x32_bf16 v[40:43], v[172:175], v[208:211], v[40:43]
	v_mfma_f32_16x16x32_bf16 v[28:31], v[164:167], v[216:219], v[28:31]
	v_mfma_f32_16x16x32_bf16 v[24:27], v[172:175], v[216:219], v[24:27]
	v_mfma_f32_16x16x32_bf16 v[12:15], v[164:167], v[224:227], v[12:15]
	v_mfma_f32_16x16x32_bf16 v[8:11], v[172:175], v[224:227], v[8:11]
	s_setprio 0
	s_setprio 1
	v_mfma_f32_16x16x32_bf16 v[52:55], v[176:179], v[196:199], v[52:55]
	v_mfma_f32_16x16x32_bf16 v[48:51], v[184:187], v[196:199], v[48:51]
	v_mfma_f32_16x16x32_bf16 v[36:39], v[176:179], v[204:207], v[36:39]
	v_mfma_f32_16x16x32_bf16 v[32:35], v[184:187], v[204:207], v[32:35]
	v_mfma_f32_16x16x32_bf16 v[20:23], v[176:179], v[212:215], v[20:23]
	v_mfma_f32_16x16x32_bf16 v[16:19], v[184:187], v[212:215], v[16:19]
	v_mfma_f32_16x16x32_bf16 v[4:7], v[176:179], v[220:223], v[4:7]
	v_mfma_f32_16x16x32_bf16 v[0:3], v[184:187], v[220:223], v[0:3]
	v_mfma_f32_16x16x32_bf16 v[52:55], v[180:183], v[200:203], v[52:55]
	v_mfma_f32_16x16x32_bf16 v[48:51], v[188:191], v[200:203], v[48:51]
	v_mfma_f32_16x16x32_bf16 v[36:39], v[180:183], v[208:211], v[36:39]
	v_mfma_f32_16x16x32_bf16 v[32:35], v[188:191], v[208:211], v[32:35]
	v_mfma_f32_16x16x32_bf16 v[20:23], v[180:183], v[216:219], v[20:23]
	v_mfma_f32_16x16x32_bf16 v[16:19], v[188:191], v[216:219], v[16:19]
	v_mfma_f32_16x16x32_bf16 v[4:7], v[180:183], v[224:227], v[4:7]
	v_mfma_f32_16x16x32_bf16 v[0:3], v[188:191], v[224:227], v[0:3]
	s_setprio 0
	s_barrier
	s_add_i32 s81, s81, 2
	s_add_u32 s58, s58, 0x100
	s_addc_u32 s59, s59, 0
	s_cmp_gt_u32 s81, 13
	s_mov_b64 s[50:51], s[52:53]

; DI u32x2 pk4(f32x4 v) { u32x2 r; r.x = pk2(v[0], v[1]); r.y = pk2(v[2], v[3]); return r; }
; DI float fast_exp2(float x) { return __builtin_amdgcn_exp2f(x); }
; DI float sigmoidf_(float v) { return __builtin_amdgcn_rcpf(1.f + fast_exp2(-1.4426950408889634f * v)); }
; template <int REG>
; DI void epi_inproj(const Params& p, f32x4 (&acc)[2][2][4][2], int pm, int pn, LAS unsigned char* shm) {
;     ...
;     bf16_t* dstb; int cb;
;     if (pn < 12) { dstb = (bf16_t*)(ws + OFF_G); cb = (pn - 8) * 256; }
;     else if (pn < 22) { dstb = (bf16_t*)(ws + OFF_GA); cb = (pn - 18) * 256; }
;     else { dstb = (bf16_t*)(ws + OFF_GB); cb = (pn - 22) * 256; }
;     const bool silu = pn < 12;
; #pragma unroll
;     for (int ai = 0; ai < 2; ++ai)
; #pragma unroll
;       for (int m = 0; m < 4; ++m) { asm volatile("" ::: "memory");
;         const int r = 128 * ai + 64 * wr + 16 * m + fr;
;         const float rs = rsr[ai][m];
; #pragma unroll
;         for (int bj = 0; bj < 2; ++bj) {
;           u32x2 h[2];
; #pragma unroll
;           for (int n = 0; n < 2; ++n) {
;             f32x4 v = acc[ai][bj][m][n] * rs, o;
; #pragma unroll
;             for (int j = 0; j < 4; ++j) { const float sg = sigmoidf_(v[j]); o[j] = silu ? v[j] * sg : sg; }
;             h[n] = pk4(o);
;           }
;           *(u32x4*)(dstb + (long)(T0 + r) * 1024 + cb + 128 * bj + 32 * wc + 8 * fq) = (u32x4){h[0].x, h[0].y, h[1].x, h[1].y};
;         }
.LBB0_207:
	v_mov_b32_e32 v163, v194
	s_lshl_b32 s50, s46, 8
	s_ashr_i32 s51, s50, 31
	v_and_b32_e32 v148, 15, v163
	v_ashrrev_i32_e32 v149, 8, v163
	s_lshl_b64 s[52:53], s[50:51], 2
	v_lshlrev_b32_e32 v72, 3, v148
	s_add_u32 s52, s74, s52
	v_lshl_or_b32 v72, v149, 7, v72
	s_addc_u32 s53, s75, s53
	v_ashrrev_i32_e32 v73, 31, v72
	v_lshl_add_u64 v[72:73], v[72:73], 2, s[52:53]
	v_pk_mov_b32 v[132:133], v[238:239], v[238:239] op_sel:[0,1]
	v_pk_mov_b32 v[134:135], v[240:241], v[240:241] op_sel:[0,1]
	s_nop 0
	v_pk_mov_b32 v[72:73], v[242:243], v[242:243] op_sel:[0,1]
	v_pk_mov_b32 v[74:75], v[244:245], v[244:245] op_sel:[0,1]
	v_or_b32_e32 v148, s50, v148
	s_lshl_b32 s46, s48, 8
	v_lshl_add_u32 v148, v149, 6, v148
	s_cmp_lt_u32 s48, 22
	v_ashrrev_i32_e32 v149, 31, v148
	s_cselect_b64 s[50:51], -1, 0
	v_lshlrev_b64 v[164:165], 11, v[148:149]
	s_and_b64 s[50:51], s[50:51], exec
	s_cselect_b32 s52, s78, 0x1a300000
	s_cselect_b32 s53, s79, 0xffffea00
	s_cmp_lt_i32 s48, 12
	s_cselect_b64 vcc, -1, 0
	s_and_b64 s[50:51], vcc, exec
	s_cselect_b32 s48, 0xc300000, s52
	s_cselect_b32 s50, 0xfffff800, s53
	s_add_u32 s48, s26, s48
	s_addc_u32 s52, s27, 0
	s_add_i32 s50, s50, s46
	s_ashr_i32 s51, s50, 31
	s_lshl_b64 s[50:51], s[50:51], 1
	s_add_u32 s50, s48, s50
	v_and_b32_e32 v144, 0xc0, v163
	s_addc_u32 s51, s52, s51
	s_waitcnt vmcnt(0)
	v_lshl_add_u64 v[164:165], v[164:165], 0, s[50:51]
	v_lshl_add_u64 v[164:165], v[164:165], 0, v[144:145]
	v_and_b32_e32 v144, 48, v163
	v_lshl_add_u64 v[164:165], v[164:165], 0, v[144:145]
	s_mov_b32 s98, 0x8000
	s_mov_b32 s99, 0
	s_mov_b32 s100, 0x28000
	s_mov_b32 s101, 0
	v_mov_b32_e32 v166, 0xbfb8aa3b
	v_mov_b32_e32 v167, 0xbfb8aa3b
	s_cbranch_vccnz .Lr2_silu
	v_pk_mul_f32 v[238:239], v[132:133], v[166:167]
	v_pk_mul_f32 v[240:241], v[134:135], v[166:167]
	v_pk_mul_f32 v[242:243], v[72:73], v[166:167]
	v_pk_mul_f32 v[244:245], v[74:75], v[166:167]
	v_pk_mul_f32 v[128:129], v[128:129], v[238:239] op_sel_hi:[1,0]
	v_pk_mul_f32 v[130:131], v[130:131], v[238:239] op_sel_hi:[1,0]
	v_pk_mul_f32 v[124:125], v[124:125], v[238:239] op_sel_hi:[1,0]
	v_pk_mul_f32 v[126:127], v[126:127], v[238:239] op_sel_hi:[1,0]
	v_min_f32_e32 v128, 0x42700000, v128
	v_min_f32_e32 v129, 0x42700000, v129
	v_min_f32_e32 v130, 0x42700000, v130
	v_min_f32_e32 v131, 0x42700000, v131
	v_min_f32_e32 v124, 0x42700000, v124
	v_min_f32_e32 v125, 0x42700000, v125
	v_min_f32_e32 v126, 0x42700000, v126
	v_min_f32_e32 v127, 0x42700000, v127
	v_exp_f32_e32 v128, v128
	v_exp_f32_e32 v129, v129
	v_exp_f32_e32 v130, v130
	v_exp_f32_e32 v131, v131
	v_exp_f32_e32 v124, v124
	v_exp_f32_e32 v125, v125
	v_exp_f32_e32 v126, v126
	v_exp_f32_e32 v127, v127
	v_pk_add_f32 v[128:129], v[128:129], 1.0 op_sel_hi:[1,0]
	v_pk_add_f32 v[130:131], v[130:131], 1.0 op_sel_hi:[1,0]
	v_pk_add_f32 v[124:125], v[124:125], 1.0 op_sel_hi:[1,0]
	v_pk_add_f32 v[126:127], v[126:127], 1.0 op_sel_hi:[1,0]
	v_mul_f32_e32 v168, v128, v129
	v_mul_f32_e32 v170, v130, v131
	v_mul_f32_e32 v172, v124, v125
	v_mul_f32_e32 v174, v126, v127
	v_rcp_f32_e32 v168, v168
	v_rcp_f32_e32 v170, v170
	v_rcp_f32_e32 v172, v172
	v_rcp_f32_e32 v174, v174
	v_pk_mul_f32 v[128:129], v[168:169], v[128:129] op_sel:[0,1] op_sel_hi:[0,0]
	v_pk_mul_f32 v[130:131], v[170:171], v[130:131] op_sel:[0,1] op_sel_hi:[0,0]
	v_pk_mul_f32 v[124:125], v[172:173], v[124:125] op_sel:[0,1] op_sel_hi:[0,0]
	v_pk_mul_f32 v[126:127], v[174:175], v[126:127] op_sel:[0,1] op_sel_hi:[0,0]
	v_cvt_pk_bf16_f32 v128, v128, v129
	v_cvt_pk_bf16_f32 v129, v130, v131
	v_cvt_pk_bf16_f32 v130, v124, v125
	v_cvt_pk_bf16_f32 v131, v126, v127
	global_store_dwordx4 v[164:165], v[128:131], off nt
	v_pk_mul_f32 v[120:121], v[120:121], v[238:239] op_sel_hi:[1,0]
	v_pk_mul_f32 v[122:123], v[122:123], v[238:239] op_sel_hi:[1,0]
	v_pk_mul_f32 v[116:117], v[116:117], v[238:239] op_sel_hi:[1,0]
	v_pk_mul_f32 v[118:119], v[118:119], v[238:239] op_sel_hi:[1,0]
	v_min_f32_e32 v120, 0x42700000, v120
	v_min_f32_e32 v121, 0x42700000, v121
	v_min_f32_e32 v122, 0x42700000, v122
	v_min_f32_e32 v123, 0x42700000, v123
	v_min_f32_e32 v116, 0x42700000, v116
	v_min_f32_e32 v117, 0x42700000, v117
	v_min_f32_e32 v118, 0x42700000, v118
	v_min_f32_e32 v119, 0x42700000, v119
	v_exp_f32_e32 v120, v120
	v_exp_f32_e32 v121, v121
	v_exp_f32_e32 v122, v122
	v_exp_f32_e32 v123, v123
	v_exp_f32_e32 v116, v116
	v_exp_f32_e32 v117, v117
	v_exp_f32_e32 v118, v118
	v_exp_f32_e32 v119, v119
	v_pk_add_f32 v[120:121], v[120:121], 1.0 op_sel_hi:[1,0]
	v_pk_add_f32 v[122:123], v[122:123], 1.0 op_sel_hi:[1,0]
	v_pk_add_f32 v[116:117], v[116:117], 1.0 op_sel_hi:[1,0]
	v_pk_add_f32 v[118:119], v[118:119], 1.0 op_sel_hi:[1,0]
	v_mul_f32_e32 v168, v120, v121
	v_mul_f32_e32 v170, v122, v123
	v_mul_f32_e32 v172, v116, v117
	v_mul_f32_e32 v174, v118, v119
	v_rcp_f32_e32 v168, v168
	v_rcp_f32_e32 v170, v170
	v_rcp_f32_e32 v172, v172
	v_rcp_f32_e32 v174, v174
	v_pk_mul_f32 v[120:121], v[168:169], v[120:121] op_sel:[0,1] op_sel_hi:[0,0]
	v_pk_mul_f32 v[122:123], v[170:171], v[122:123] op_sel:[0,1] op_sel_hi:[0,0]
	v_pk_mul_f32 v[116:117], v[172:173], v[116:117] op_sel:[0,1] op_sel_hi:[0,0]
	v_pk_mul_f32 v[118:119], v[174:175], v[118:119] op_sel:[0,1] op_sel_hi:[0,0]
	v_cvt_pk_bf16_f32 v120, v120, v121
	v_cvt_pk_bf16_f32 v121, v122, v123
	v_cvt_pk_bf16_f32 v122, v116, v117
	v_cvt_pk_bf16_f32 v123, v118, v119
	global_store_dwordx4 v[164:165], v[120:123], off offset:256 nt
	v_lshl_add_u64 v[164:165], v[164:165], 0, s[98:99]
	v_pk_mul_f32 v[112:113], v[112:113], v[238:239] op_sel:[0,1]
	v_pk_mul_f32 v[114:115], v[114:115], v[238:239] op_sel:[0,1]
	v_pk_mul_f32 v[108:109], v[108:109], v[238:239] op_sel:[0,1]
; DI u32x2 pk4(f32x4 v) { u32x2 r; r.x = pk2(v[0], v[1]); r.y = pk2(v[2], v[3]); return r; }
; DI float fast_exp2(float x) { return __builtin_amdgcn_exp2f(x); }
; DI float sigmoidf_(float v) { return __builtin_amdgcn_rcpf(1.f + fast_exp2(-1.4426950408889634f * v)); }
; template <int REG>
; DI void epi_inproj(const Params& p, f32x4 (&acc)[2][2][4][2], int pm, int pn, LAS unsigned char* shm) {
;     ...
; #pragma unroll
;     for (int ai = 0; ai < 2; ++ai)
; #pragma unroll
;       for (int m = 0; m < 4; ++m) { asm volatile("" ::: "memory");
;         const int r = 128 * ai + 64 * wr + 16 * m + fr;
;         const float rs = rsr[ai][m];
; #pragma unroll
;         for (int bj = 0; bj < 2; ++bj) {
;           u32x2 h[2];
; #pragma unroll
;           for (int n = 0; n < 2; ++n) {
;             f32x4 v = acc[ai][bj][m][n] * rs, o;
; #pragma unroll
;             for (int j = 0; j < 4; ++j) { const float sg = sigmoidf_(v[j]); o[j] = silu ? v[j] * sg : sg; }
;             h[n] = pk4(o);
;           }
;           *(u32x4*)(dstb + (long)(T0 + r) * 1024 + cb + 128 * bj + 32 * wc + 8 * fq) = (u32x4){h[0].x, h[0].y, h[1].x, h[1].y};
;         }
	v_pk_mul_f32 v[110:111], v[110:111], v[238:239] op_sel:[0,1]
	v_min_f32_e32 v112, 0x42700000, v112
	v_min_f32_e32 v113, 0x42700000, v113
	v_min_f32_e32 v114, 0x42700000, v114
	v_min_f32_e32 v115, 0x42700000, v115
	v_min_f32_e32 v108, 0x42700000, v108
	v_min_f32_e32 v109, 0x42700000, v109
	v_min_f32_e32 v110, 0x42700000, v110
	v_min_f32_e32 v111, 0x42700000, v111
	v_exp_f32_e32 v112, v112
	v_exp_f32_e32 v113, v113
	v_exp_f32_e32 v114, v114
	v_exp_f32_e32 v115, v115
	v_exp_f32_e32 v108, v108
	v_exp_f32_e32 v109, v109
	v_exp_f32_e32 v110, v110
	v_exp_f32_e32 v111, v111
	v_pk_add_f32 v[112:113], v[112:113], 1.0 op_sel_hi:[1,0]
	v_pk_add_f32 v[114:115], v[114:115], 1.0 op_sel_hi:[1,0]
	v_pk_add_f32 v[108:109], v[108:109], 1.0 op_sel_hi:[1,0]
	v_pk_add_f32 v[110:111], v[110:111], 1.0 op_sel_hi:[1,0]
	v_mul_f32_e32 v168, v112, v113
	v_mul_f32_e32 v170, v114, v115
	v_mul_f32_e32 v172, v108, v109
	v_mul_f32_e32 v174, v110, v111
	v_rcp_f32_e32 v168, v168
	v_rcp_f32_e32 v170, v170
	v_rcp_f32_e32 v172, v172
	v_rcp_f32_e32 v174, v174
	v_pk_mul_f32 v[112:113], v[168:169], v[112:113] op_sel:[0,1] op_sel_hi:[0,0]
	v_pk_mul_f32 v[114:115], v[170:171], v[114:115] op_sel:[0,1] op_sel_hi:[0,0]
	v_pk_mul_f32 v[108:109], v[172:173], v[108:109] op_sel:[0,1] op_sel_hi:[0,0]
	v_pk_mul_f32 v[110:111], v[174:175], v[110:111] op_sel:[0,1] op_sel_hi:[0,0]
	v_cvt_pk_bf16_f32 v112, v112, v113
	v_cvt_pk_bf16_f32 v113, v114, v115
	v_cvt_pk_bf16_f32 v114, v108, v109
	v_cvt_pk_bf16_f32 v115, v110, v111
	global_store_dwordx4 v[164:165], v[112:115], off nt
	v_pk_mul_f32 v[104:105], v[104:105], v[238:239] op_sel:[0,1]
	v_pk_mul_f32 v[106:107], v[106:107], v[238:239] op_sel:[0,1]
	v_pk_mul_f32 v[100:101], v[100:101], v[238:239] op_sel:[0,1]
	v_pk_mul_f32 v[102:103], v[102:103], v[238:239] op_sel:[0,1]
	v_min_f32_e32 v104, 0x42700000, v104
	v_min_f32_e32 v105, 0x42700000, v105
	v_min_f32_e32 v106, 0x42700000, v106
	v_min_f32_e32 v107, 0x42700000, v107
	v_min_f32_e32 v100, 0x42700000, v100
	v_min_f32_e32 v101, 0x42700000, v101
	v_min_f32_e32 v102, 0x42700000, v102
	v_min_f32_e32 v103, 0x42700000, v103
	v_exp_f32_e32 v104, v104
	v_exp_f32_e32 v105, v105
	v_exp_f32_e32 v106, v106
	v_exp_f32_e32 v107, v107
	v_exp_f32_e32 v100, v100
	v_exp_f32_e32 v101, v101
	v_exp_f32_e32 v102, v102
	v_exp_f32_e32 v103, v103
	v_pk_add_f32 v[104:105], v[104:105], 1.0 op_sel_hi:[1,0]
	v_pk_add_f32 v[106:107], v[106:107], 1.0 op_sel_hi:[1,0]
	v_pk_add_f32 v[100:101], v[100:101], 1.0 op_sel_hi:[1,0]
	v_pk_add_f32 v[102:103], v[102:103], 1.0 op_sel_hi:[1,0]
	v_mul_f32_e32 v168, v104, v105
	v_mul_f32_e32 v170, v106, v107
	v_mul_f32_e32 v172, v100, v101
	v_mul_f32_e32 v174, v102, v103
	v_rcp_f32_e32 v168, v168
	v_rcp_f32_e32 v170, v170
	v_rcp_f32_e32 v172, v172
	v_rcp_f32_e32 v174, v174
	v_pk_mul_f32 v[104:105], v[168:169], v[104:105] op_sel:[0,1] op_sel_hi:[0,0]
	v_pk_mul_f32 v[106:107], v[170:171], v[106:107] op_sel:[0,1] op_sel_hi:[0,0]
	v_pk_mul_f32 v[100:101], v[172:173], v[100:101] op_sel:[0,1] op_sel_hi:[0,0]
	v_pk_mul_f32 v[102:103], v[174:175], v[102:103] op_sel:[0,1] op_sel_hi:[0,0]
	v_cvt_pk_bf16_f32 v104, v104, v105
	v_cvt_pk_bf16_f32 v105, v106, v107
	v_cvt_pk_bf16_f32 v106, v100, v101
	v_cvt_pk_bf16_f32 v107, v102, v103
	global_store_dwordx4 v[164:165], v[104:107], off offset:256 nt
	v_lshl_add_u64 v[164:165], v[164:165], 0, s[98:99]
	v_pk_mul_f32 v[96:97], v[96:97], v[240:241] op_sel_hi:[1,0]
	v_pk_mul_f32 v[98:99], v[98:99], v[240:241] op_sel_hi:[1,0]
	v_pk_mul_f32 v[92:93], v[92:93], v[240:241] op_sel_hi:[1,0]
	v_pk_mul_f32 v[94:95], v[94:95], v[240:241] op_sel_hi:[1,0]
	v_min_f32_e32 v96, 0x42700000, v96
	v_min_f32_e32 v97, 0x42700000, v97
	v_min_f32_e32 v98, 0x42700000, v98
	v_min_f32_e32 v99, 0x42700000, v99
	v_min_f32_e32 v92, 0x42700000, v92
	v_min_f32_e32 v93, 0x42700000, v93
	v_min_f32_e32 v94, 0x42700000, v94
	v_min_f32_e32 v95, 0x42700000, v95
	v_exp_f32_e32 v96, v96
	v_exp_f32_e32 v97, v97
	v_exp_f32_e32 v98, v98
	v_exp_f32_e32 v99, v99
	v_exp_f32_e32 v92, v92
	v_exp_f32_e32 v93, v93
	v_exp_f32_e32 v94, v94
	v_exp_f32_e32 v95, v95
	v_pk_add_f32 v[96:97], v[96:97], 1.0 op_sel_hi:[1,0]
	v_pk_add_f32 v[98:99], v[98:99], 1.0 op_sel_hi:[1,0]
	v_pk_add_f32 v[92:93], v[92:93], 1.0 op_sel_hi:[1,0]
	v_pk_add_f32 v[94:95], v[94:95], 1.0 op_sel_hi:[1,0]
	v_mul_f32_e32 v168, v96, v97
	v_mul_f32_e32 v170, v98, v99
	v_mul_f32_e32 v172, v92, v93
	v_mul_f32_e32 v174, v94, v95
	v_rcp_f32_e32 v168, v168
	v_rcp_f32_e32 v170, v170
	v_rcp_f32_e32 v172, v172
	v_rcp_f32_e32 v174, v174
	v_pk_mul_f32 v[96:97], v[168:169], v[96:97] op_sel:[0,1] op_sel_hi:[0,0]
	v_pk_mul_f32 v[98:99], v[170:171], v[98:99] op_sel:[0,1] op_sel_hi:[0,0]
	v_pk_mul_f32 v[92:93], v[172:173], v[92:93] op_sel:[0,1] op_sel_hi:[0,0]
	v_pk_mul_f32 v[94:95], v[174:175], v[94:95] op_sel:[0,1] op_sel_hi:[0,0]
	v_cvt_pk_bf16_f32 v96, v96, v97
	v_cvt_pk_bf16_f32 v97, v98, v99
	v_cvt_pk_bf16_f32 v98, v92, v93
	v_cvt_pk_bf16_f32 v99, v94, v95
	global_store_dwordx4 v[164:165], v[96:99], off nt
	v_pk_mul_f32 v[88:89], v[88:89], v[240:241] op_sel_hi:[1,0]
	v_pk_mul_f32 v[90:91], v[90:91], v[240:241] op_sel_hi:[1,0]
	v_pk_mul_f32 v[84:85], v[84:85], v[240:241] op_sel_hi:[1,0]
	v_pk_mul_f32 v[86:87], v[86:87], v[240:241] op_sel_hi:[1,0]
	v_min_f32_e32 v88, 0x42700000, v88
	v_min_f32_e32 v89, 0x42700000, v89
	v_min_f32_e32 v90, 0x42700000, v90
	v_min_f32_e32 v91, 0x42700000, v91
	v_min_f32_e32 v84, 0x42700000, v84
	v_min_f32_e32 v85, 0x42700000, v85
	v_min_f32_e32 v86, 0x42700000, v86
	v_min_f32_e32 v87, 0x42700000, v87
	v_exp_f32_e32 v88, v88
	v_exp_f32_e32 v89, v89
	v_exp_f32_e32 v90, v90
	v_exp_f32_e32 v91, v91
	v_exp_f32_e32 v84, v84
; DI u32x2 pk4(f32x4 v) { u32x2 r; r.x = pk2(v[0], v[1]); r.y = pk2(v[2], v[3]); return r; }
; DI float fast_exp2(float x) { return __builtin_amdgcn_exp2f(x); }
; DI float sigmoidf_(float v) { return __builtin_amdgcn_rcpf(1.f + fast_exp2(-1.4426950408889634f * v)); }
; template <int REG>
; DI void epi_inproj(const Params& p, f32x4 (&acc)[2][2][4][2], int pm, int pn, LAS unsigned char* shm) {
;     ...
; #pragma unroll
;     for (int ai = 0; ai < 2; ++ai)
; #pragma unroll
;       for (int m = 0; m < 4; ++m) { asm volatile("" ::: "memory");
;         const int r = 128 * ai + 64 * wr + 16 * m + fr;
;         const float rs = rsr[ai][m];
; #pragma unroll
;         for (int bj = 0; bj < 2; ++bj) {
;           u32x2 h[2];
; #pragma unroll
;           for (int n = 0; n < 2; ++n) {
;             f32x4 v = acc[ai][bj][m][n] * rs, o;
; #pragma unroll
;             for (int j = 0; j < 4; ++j) { const float sg = sigmoidf_(v[j]); o[j] = silu ? v[j] * sg : sg; }
;             h[n] = pk4(o);
;           }
;           *(u32x4*)(dstb + (long)(T0 + r) * 1024 + cb + 128 * bj + 32 * wc + 8 * fq) = (u32x4){h[0].x, h[0].y, h[1].x, h[1].y};
;         }
	v_exp_f32_e32 v85, v85
	v_exp_f32_e32 v86, v86
	v_exp_f32_e32 v87, v87
	v_pk_add_f32 v[88:89], v[88:89], 1.0 op_sel_hi:[1,0]
	v_pk_add_f32 v[90:91], v[90:91], 1.0 op_sel_hi:[1,0]
	v_pk_add_f32 v[84:85], v[84:85], 1.0 op_sel_hi:[1,0]
	v_pk_add_f32 v[86:87], v[86:87], 1.0 op_sel_hi:[1,0]
	v_mul_f32_e32 v168, v88, v89
	v_mul_f32_e32 v170, v90, v91
	v_mul_f32_e32 v172, v84, v85
	v_mul_f32_e32 v174, v86, v87
	v_rcp_f32_e32 v168, v168
	v_rcp_f32_e32 v170, v170
	v_rcp_f32_e32 v172, v172
	v_rcp_f32_e32 v174, v174
	v_pk_mul_f32 v[88:89], v[168:169], v[88:89] op_sel:[0,1] op_sel_hi:[0,0]
	v_pk_mul_f32 v[90:91], v[170:171], v[90:91] op_sel:[0,1] op_sel_hi:[0,0]
	v_pk_mul_f32 v[84:85], v[172:173], v[84:85] op_sel:[0,1] op_sel_hi:[0,0]
	v_pk_mul_f32 v[86:87], v[174:175], v[86:87] op_sel:[0,1] op_sel_hi:[0,0]
	v_cvt_pk_bf16_f32 v88, v88, v89
	v_cvt_pk_bf16_f32 v89, v90, v91
	v_cvt_pk_bf16_f32 v90, v84, v85
	v_cvt_pk_bf16_f32 v91, v86, v87
	global_store_dwordx4 v[164:165], v[88:91], off offset:256 nt
	v_lshl_add_u64 v[164:165], v[164:165], 0, s[98:99]
	v_pk_mul_f32 v[80:81], v[80:81], v[240:241] op_sel:[0,1]
	v_pk_mul_f32 v[82:83], v[82:83], v[240:241] op_sel:[0,1]
	v_pk_mul_f32 v[76:77], v[76:77], v[240:241] op_sel:[0,1]
	v_pk_mul_f32 v[78:79], v[78:79], v[240:241] op_sel:[0,1]
	v_min_f32_e32 v80, 0x42700000, v80
	v_min_f32_e32 v81, 0x42700000, v81
	v_min_f32_e32 v82, 0x42700000, v82
	v_min_f32_e32 v83, 0x42700000, v83
	v_min_f32_e32 v76, 0x42700000, v76
	v_min_f32_e32 v77, 0x42700000, v77
	v_min_f32_e32 v78, 0x42700000, v78
	v_min_f32_e32 v79, 0x42700000, v79
	v_exp_f32_e32 v80, v80
	v_exp_f32_e32 v81, v81
	v_exp_f32_e32 v82, v82
	v_exp_f32_e32 v83, v83
	v_exp_f32_e32 v76, v76
	v_exp_f32_e32 v77, v77
	v_exp_f32_e32 v78, v78
	v_exp_f32_e32 v79, v79
	v_pk_add_f32 v[80:81], v[80:81], 1.0 op_sel_hi:[1,0]
	v_pk_add_f32 v[82:83], v[82:83], 1.0 op_sel_hi:[1,0]
	v_pk_add_f32 v[76:77], v[76:77], 1.0 op_sel_hi:[1,0]
	v_pk_add_f32 v[78:79], v[78:79], 1.0 op_sel_hi:[1,0]
	v_mul_f32_e32 v168, v80, v81
	v_mul_f32_e32 v170, v82, v83
	v_mul_f32_e32 v172, v76, v77
	v_mul_f32_e32 v174, v78, v79
	v_rcp_f32_e32 v168, v168
	v_rcp_f32_e32 v170, v170
	v_rcp_f32_e32 v172, v172
	v_rcp_f32_e32 v174, v174
	v_pk_mul_f32 v[80:81], v[168:169], v[80:81] op_sel:[0,1] op_sel_hi:[0,0]
	v_pk_mul_f32 v[82:83], v[170:171], v[82:83] op_sel:[0,1] op_sel_hi:[0,0]
	v_pk_mul_f32 v[76:77], v[172:173], v[76:77] op_sel:[0,1] op_sel_hi:[0,0]
	v_pk_mul_f32 v[78:79], v[174:175], v[78:79] op_sel:[0,1] op_sel_hi:[0,0]
	v_cvt_pk_bf16_f32 v80, v80, v81
	v_cvt_pk_bf16_f32 v81, v82, v83
	v_cvt_pk_bf16_f32 v82, v76, v77
	v_cvt_pk_bf16_f32 v83, v78, v79
	global_store_dwordx4 v[164:165], v[80:83], off nt
	v_pk_mul_f32 v[68:69], v[68:69], v[240:241] op_sel:[0,1]
	v_pk_mul_f32 v[70:71], v[70:71], v[240:241] op_sel:[0,1]
	v_pk_mul_f32 v[64:65], v[64:65], v[240:241] op_sel:[0,1]
	v_pk_mul_f32 v[66:67], v[66:67], v[240:241] op_sel:[0,1]
	v_min_f32_e32 v68, 0x42700000, v68
	v_min_f32_e32 v69, 0x42700000, v69
	v_min_f32_e32 v70, 0x42700000, v70
	v_min_f32_e32 v71, 0x42700000, v71
	v_min_f32_e32 v64, 0x42700000, v64
	v_min_f32_e32 v65, 0x42700000, v65
	v_min_f32_e32 v66, 0x42700000, v66
	v_min_f32_e32 v67, 0x42700000, v67
	v_exp_f32_e32 v68, v68
	v_exp_f32_e32 v69, v69
	v_exp_f32_e32 v70, v70
	v_exp_f32_e32 v71, v71
	v_exp_f32_e32 v64, v64
	v_exp_f32_e32 v65, v65
	v_exp_f32_e32 v66, v66
	v_exp_f32_e32 v67, v67
	v_pk_add_f32 v[68:69], v[68:69], 1.0 op_sel_hi:[1,0]
	v_pk_add_f32 v[70:71], v[70:71], 1.0 op_sel_hi:[1,0]
	v_pk_add_f32 v[64:65], v[64:65], 1.0 op_sel_hi:[1,0]
	v_pk_add_f32 v[66:67], v[66:67], 1.0 op_sel_hi:[1,0]
	v_mul_f32_e32 v168, v68, v69
	v_mul_f32_e32 v170, v70, v71
	v_mul_f32_e32 v172, v64, v65
	v_mul_f32_e32 v174, v66, v67
	v_rcp_f32_e32 v168, v168
	v_rcp_f32_e32 v170, v170
	v_rcp_f32_e32 v172, v172
	v_rcp_f32_e32 v174, v174
	v_pk_mul_f32 v[68:69], v[168:169], v[68:69] op_sel:[0,1] op_sel_hi:[0,0]
	v_pk_mul_f32 v[70:71], v[170:171], v[70:71] op_sel:[0,1] op_sel_hi:[0,0]
	v_pk_mul_f32 v[64:65], v[172:173], v[64:65] op_sel:[0,1] op_sel_hi:[0,0]
	v_pk_mul_f32 v[66:67], v[174:175], v[66:67] op_sel:[0,1] op_sel_hi:[0,0]
	v_cvt_pk_bf16_f32 v68, v68, v69
	v_cvt_pk_bf16_f32 v69, v70, v71
	v_cvt_pk_bf16_f32 v70, v64, v65
	v_cvt_pk_bf16_f32 v71, v66, v67
	global_store_dwordx4 v[164:165], v[68:71], off offset:256 nt
	v_lshl_add_u64 v[164:165], v[164:165], 0, s[100:101]
	v_pk_mul_f32 v[60:61], v[60:61], v[242:243] op_sel_hi:[1,0]
	v_pk_mul_f32 v[62:63], v[62:63], v[242:243] op_sel_hi:[1,0]
	v_pk_mul_f32 v[56:57], v[56:57], v[242:243] op_sel_hi:[1,0]
	v_pk_mul_f32 v[58:59], v[58:59], v[242:243] op_sel_hi:[1,0]
	v_min_f32_e32 v60, 0x42700000, v60
	v_min_f32_e32 v61, 0x42700000, v61
	v_min_f32_e32 v62, 0x42700000, v62
	v_min_f32_e32 v63, 0x42700000, v63
	v_min_f32_e32 v56, 0x42700000, v56
	v_min_f32_e32 v57, 0x42700000, v57
	v_min_f32_e32 v58, 0x42700000, v58
	v_min_f32_e32 v59, 0x42700000, v59
	v_exp_f32_e32 v60, v60
	v_exp_f32_e32 v61, v61
	v_exp_f32_e32 v62, v62
	v_exp_f32_e32 v63, v63
	v_exp_f32_e32 v56, v56
	v_exp_f32_e32 v57, v57
	v_exp_f32_e32 v58, v58
	v_exp_f32_e32 v59, v59
	v_pk_add_f32 v[60:61], v[60:61], 1.0 op_sel_hi:[1,0]
	v_pk_add_f32 v[62:63], v[62:63], 1.0 op_sel_hi:[1,0]
	v_pk_add_f32 v[56:57], v[56:57], 1.0 op_sel_hi:[1,0]
	v_pk_add_f32 v[58:59], v[58:59], 1.0 op_sel_hi:[1,0]
	v_mul_f32_e32 v168, v60, v61
	v_mul_f32_e32 v170, v62, v63
	v_mul_f32_e32 v172, v56, v57
	v_mul_f32_e32 v174, v58, v59
	v_rcp_f32_e32 v168, v168
	v_rcp_f32_e32 v170, v170
	v_rcp_f32_e32 v172, v172
	v_rcp_f32_e32 v174, v174
	v_pk_mul_f32 v[60:61], v[168:169], v[60:61] op_sel:[0,1] op_sel_hi:[0,0]
; DI u32x2 pk4(f32x4 v) { u32x2 r; r.x = pk2(v[0], v[1]); r.y = pk2(v[2], v[3]); return r; }
; DI float fast_exp2(float x) { return __builtin_amdgcn_exp2f(x); }
; DI float sigmoidf_(float v) { return __builtin_amdgcn_rcpf(1.f + fast_exp2(-1.4426950408889634f * v)); }
; template <int REG>
; DI void epi_inproj(const Params& p, f32x4 (&acc)[2][2][4][2], int pm, int pn, LAS unsigned char* shm) {
;     ...
; #pragma unroll
;     for (int ai = 0; ai < 2; ++ai)
; #pragma unroll
;       for (int m = 0; m < 4; ++m) { asm volatile("" ::: "memory");
;         const int r = 128 * ai + 64 * wr + 16 * m + fr;
;         const float rs = rsr[ai][m];
; #pragma unroll
;         for (int bj = 0; bj < 2; ++bj) {
;           u32x2 h[2];
; #pragma unroll
;           for (int n = 0; n < 2; ++n) {
;             f32x4 v = acc[ai][bj][m][n] * rs, o;
; #pragma unroll
;             for (int j = 0; j < 4; ++j) { const float sg = sigmoidf_(v[j]); o[j] = silu ? v[j] * sg : sg; }
;             h[n] = pk4(o);
;           }
;           *(u32x4*)(dstb + (long)(T0 + r) * 1024 + cb + 128 * bj + 32 * wc + 8 * fq) = (u32x4){h[0].x, h[0].y, h[1].x, h[1].y};
;         }
	v_pk_mul_f32 v[62:63], v[170:171], v[62:63] op_sel:[0,1] op_sel_hi:[0,0]
	v_pk_mul_f32 v[56:57], v[172:173], v[56:57] op_sel:[0,1] op_sel_hi:[0,0]
	v_pk_mul_f32 v[58:59], v[174:175], v[58:59] op_sel:[0,1] op_sel_hi:[0,0]
	v_cvt_pk_bf16_f32 v60, v60, v61
	v_cvt_pk_bf16_f32 v61, v62, v63
	v_cvt_pk_bf16_f32 v62, v56, v57
	v_cvt_pk_bf16_f32 v63, v58, v59
	global_store_dwordx4 v[164:165], v[60:63], off nt
	v_pk_mul_f32 v[52:53], v[52:53], v[242:243] op_sel_hi:[1,0]
	v_pk_mul_f32 v[54:55], v[54:55], v[242:243] op_sel_hi:[1,0]
	v_pk_mul_f32 v[48:49], v[48:49], v[242:243] op_sel_hi:[1,0]
	v_pk_mul_f32 v[50:51], v[50:51], v[242:243] op_sel_hi:[1,0]
	v_min_f32_e32 v52, 0x42700000, v52
	v_min_f32_e32 v53, 0x42700000, v53
	v_min_f32_e32 v54, 0x42700000, v54
	v_min_f32_e32 v55, 0x42700000, v55
	v_min_f32_e32 v48, 0x42700000, v48
	v_min_f32_e32 v49, 0x42700000, v49
	v_min_f32_e32 v50, 0x42700000, v50
	v_min_f32_e32 v51, 0x42700000, v51
	v_exp_f32_e32 v52, v52
	v_exp_f32_e32 v53, v53
	v_exp_f32_e32 v54, v54
	v_exp_f32_e32 v55, v55
	v_exp_f32_e32 v48, v48
	v_exp_f32_e32 v49, v49
	v_exp_f32_e32 v50, v50
	v_exp_f32_e32 v51, v51
	v_pk_add_f32 v[52:53], v[52:53], 1.0 op_sel_hi:[1,0]
	v_pk_add_f32 v[54:55], v[54:55], 1.0 op_sel_hi:[1,0]
	v_pk_add_f32 v[48:49], v[48:49], 1.0 op_sel_hi:[1,0]
	v_pk_add_f32 v[50:51], v[50:51], 1.0 op_sel_hi:[1,0]
	v_mul_f32_e32 v168, v52, v53
	v_mul_f32_e32 v170, v54, v55
	v_mul_f32_e32 v172, v48, v49
	v_mul_f32_e32 v174, v50, v51
	v_rcp_f32_e32 v168, v168
	v_rcp_f32_e32 v170, v170
	v_rcp_f32_e32 v172, v172
	v_rcp_f32_e32 v174, v174
	v_pk_mul_f32 v[52:53], v[168:169], v[52:53] op_sel:[0,1] op_sel_hi:[0,0]
	v_pk_mul_f32 v[54:55], v[170:171], v[54:55] op_sel:[0,1] op_sel_hi:[0,0]
	v_pk_mul_f32 v[48:49], v[172:173], v[48:49] op_sel:[0,1] op_sel_hi:[0,0]
	v_pk_mul_f32 v[50:51], v[174:175], v[50:51] op_sel:[0,1] op_sel_hi:[0,0]
	v_cvt_pk_bf16_f32 v52, v52, v53
	v_cvt_pk_bf16_f32 v53, v54, v55
	v_cvt_pk_bf16_f32 v54, v48, v49
	v_cvt_pk_bf16_f32 v55, v50, v51
	global_store_dwordx4 v[164:165], v[52:55], off offset:256 nt
	v_lshl_add_u64 v[164:165], v[164:165], 0, s[98:99]
	v_pk_mul_f32 v[44:45], v[44:45], v[242:243] op_sel:[0,1]
	v_pk_mul_f32 v[46:47], v[46:47], v[242:243] op_sel:[0,1]
	v_pk_mul_f32 v[40:41], v[40:41], v[242:243] op_sel:[0,1]
	v_pk_mul_f32 v[42:43], v[42:43], v[242:243] op_sel:[0,1]
	v_min_f32_e32 v44, 0x42700000, v44
	v_min_f32_e32 v45, 0x42700000, v45
	v_min_f32_e32 v46, 0x42700000, v46
	v_min_f32_e32 v47, 0x42700000, v47
	v_min_f32_e32 v40, 0x42700000, v40
	v_min_f32_e32 v41, 0x42700000, v41
	v_min_f32_e32 v42, 0x42700000, v42
	v_min_f32_e32 v43, 0x42700000, v43
	v_exp_f32_e32 v44, v44
	v_exp_f32_e32 v45, v45
	v_exp_f32_e32 v46, v46
	v_exp_f32_e32 v47, v47
	v_exp_f32_e32 v40, v40
	v_exp_f32_e32 v41, v41
	v_exp_f32_e32 v42, v42
	v_exp_f32_e32 v43, v43
	v_pk_add_f32 v[44:45], v[44:45], 1.0 op_sel_hi:[1,0]
	v_pk_add_f32 v[46:47], v[46:47], 1.0 op_sel_hi:[1,0]
	v_pk_add_f32 v[40:41], v[40:41], 1.0 op_sel_hi:[1,0]
	v_pk_add_f32 v[42:43], v[42:43], 1.0 op_sel_hi:[1,0]
	v_mul_f32_e32 v168, v44, v45
	v_mul_f32_e32 v170, v46, v47
	v_mul_f32_e32 v172, v40, v41
	v_mul_f32_e32 v174, v42, v43
	v_rcp_f32_e32 v168, v168
	v_rcp_f32_e32 v170, v170
	v_rcp_f32_e32 v172, v172
	v_rcp_f32_e32 v174, v174
	v_pk_mul_f32 v[44:45], v[168:169], v[44:45] op_sel:[0,1] op_sel_hi:[0,0]
	v_pk_mul_f32 v[46:47], v[170:171], v[46:47] op_sel:[0,1] op_sel_hi:[0,0]
	v_pk_mul_f32 v[40:41], v[172:173], v[40:41] op_sel:[0,1] op_sel_hi:[0,0]
	v_pk_mul_f32 v[42:43], v[174:175], v[42:43] op_sel:[0,1] op_sel_hi:[0,0]
	v_cvt_pk_bf16_f32 v44, v44, v45
	v_cvt_pk_bf16_f32 v45, v46, v47
	v_cvt_pk_bf16_f32 v46, v40, v41
	v_cvt_pk_bf16_f32 v47, v42, v43
	global_store_dwordx4 v[164:165], v[44:47], off nt
	v_pk_mul_f32 v[36:37], v[36:37], v[242:243] op_sel:[0,1]
	v_pk_mul_f32 v[38:39], v[38:39], v[242:243] op_sel:[0,1]
	v_pk_mul_f32 v[32:33], v[32:33], v[242:243] op_sel:[0,1]
	v_pk_mul_f32 v[34:35], v[34:35], v[242:243] op_sel:[0,1]
	v_min_f32_e32 v36, 0x42700000, v36
	v_min_f32_e32 v37, 0x42700000, v37
	v_min_f32_e32 v38, 0x42700000, v38
	v_min_f32_e32 v39, 0x42700000, v39
	v_min_f32_e32 v32, 0x42700000, v32
	v_min_f32_e32 v33, 0x42700000, v33
	v_min_f32_e32 v34, 0x42700000, v34
	v_min_f32_e32 v35, 0x42700000, v35
	v_exp_f32_e32 v36, v36
	v_exp_f32_e32 v37, v37
	v_exp_f32_e32 v38, v38
	v_exp_f32_e32 v39, v39
	v_exp_f32_e32 v32, v32
	v_exp_f32_e32 v33, v33
	v_exp_f32_e32 v34, v34
	v_exp_f32_e32 v35, v35
	v_pk_add_f32 v[36:37], v[36:37], 1.0 op_sel_hi:[1,0]
	v_pk_add_f32 v[38:39], v[38:39], 1.0 op_sel_hi:[1,0]
	v_pk_add_f32 v[32:33], v[32:33], 1.0 op_sel_hi:[1,0]
	v_pk_add_f32 v[34:35], v[34:35], 1.0 op_sel_hi:[1,0]
	v_mul_f32_e32 v168, v36, v37
	v_mul_f32_e32 v170, v38, v39
	v_mul_f32_e32 v172, v32, v33
	v_mul_f32_e32 v174, v34, v35
	v_rcp_f32_e32 v168, v168
	v_rcp_f32_e32 v170, v170
	v_rcp_f32_e32 v172, v172
	v_rcp_f32_e32 v174, v174
	v_pk_mul_f32 v[36:37], v[168:169], v[36:37] op_sel:[0,1] op_sel_hi:[0,0]
	v_pk_mul_f32 v[38:39], v[170:171], v[38:39] op_sel:[0,1] op_sel_hi:[0,0]
	v_pk_mul_f32 v[32:33], v[172:173], v[32:33] op_sel:[0,1] op_sel_hi:[0,0]
	v_pk_mul_f32 v[34:35], v[174:175], v[34:35] op_sel:[0,1] op_sel_hi:[0,0]
	v_cvt_pk_bf16_f32 v36, v36, v37
	v_cvt_pk_bf16_f32 v37, v38, v39
	v_cvt_pk_bf16_f32 v38, v32, v33
	v_cvt_pk_bf16_f32 v39, v34, v35
	global_store_dwordx4 v[164:165], v[36:39], off offset:256 nt
	v_lshl_add_u64 v[164:165], v[164:165], 0, s[98:99]
	v_pk_mul_f32 v[28:29], v[28:29], v[244:245] op_sel_hi:[1,0]
	v_pk_mul_f32 v[30:31], v[30:31], v[244:245] op_sel_hi:[1,0]
	v_pk_mul_f32 v[24:25], v[24:25], v[244:245] op_sel_hi:[1,0]
; DI u32x2 pk4(f32x4 v) { u32x2 r; r.x = pk2(v[0], v[1]); r.y = pk2(v[2], v[3]); return r; }
; DI float fast_exp2(float x) { return __builtin_amdgcn_exp2f(x); }
; DI float sigmoidf_(float v) { return __builtin_amdgcn_rcpf(1.f + fast_exp2(-1.4426950408889634f * v)); }
; template <int REG>
; DI void epi_inproj(const Params& p, f32x4 (&acc)[2][2][4][2], int pm, int pn, LAS unsigned char* shm) {
;     ...
; #pragma unroll
;     for (int ai = 0; ai < 2; ++ai)
; #pragma unroll
;       for (int m = 0; m < 4; ++m) { asm volatile("" ::: "memory");
;         const int r = 128 * ai + 64 * wr + 16 * m + fr;
;         const float rs = rsr[ai][m];
; #pragma unroll
;         for (int bj = 0; bj < 2; ++bj) {
;           u32x2 h[2];
; #pragma unroll
;           for (int n = 0; n < 2; ++n) {
;             f32x4 v = acc[ai][bj][m][n] * rs, o;
; #pragma unroll
;             for (int j = 0; j < 4; ++j) { const float sg = sigmoidf_(v[j]); o[j] = silu ? v[j] * sg : sg; }
;             h[n] = pk4(o);
;           }
;           *(u32x4*)(dstb + (long)(T0 + r) * 1024 + cb + 128 * bj + 32 * wc + 8 * fq) = (u32x4){h[0].x, h[0].y, h[1].x, h[1].y};
;         }
	v_pk_mul_f32 v[26:27], v[26:27], v[244:245] op_sel_hi:[1,0]
	v_min_f32_e32 v28, 0x42700000, v28
	v_min_f32_e32 v29, 0x42700000, v29
	v_min_f32_e32 v30, 0x42700000, v30
	v_min_f32_e32 v31, 0x42700000, v31
	v_min_f32_e32 v24, 0x42700000, v24
	v_min_f32_e32 v25, 0x42700000, v25
	v_min_f32_e32 v26, 0x42700000, v26
	v_min_f32_e32 v27, 0x42700000, v27
	v_exp_f32_e32 v28, v28
	v_exp_f32_e32 v29, v29
	v_exp_f32_e32 v30, v30
	v_exp_f32_e32 v31, v31
	v_exp_f32_e32 v24, v24
	v_exp_f32_e32 v25, v25
	v_exp_f32_e32 v26, v26
	v_exp_f32_e32 v27, v27
	v_pk_add_f32 v[28:29], v[28:29], 1.0 op_sel_hi:[1,0]
	v_pk_add_f32 v[30:31], v[30:31], 1.0 op_sel_hi:[1,0]
	v_pk_add_f32 v[24:25], v[24:25], 1.0 op_sel_hi:[1,0]
	v_pk_add_f32 v[26:27], v[26:27], 1.0 op_sel_hi:[1,0]
	v_mul_f32_e32 v168, v28, v29
	v_mul_f32_e32 v170, v30, v31
	v_mul_f32_e32 v172, v24, v25
	v_mul_f32_e32 v174, v26, v27
	v_rcp_f32_e32 v168, v168
	v_rcp_f32_e32 v170, v170
	v_rcp_f32_e32 v172, v172
	v_rcp_f32_e32 v174, v174
	v_pk_mul_f32 v[28:29], v[168:169], v[28:29] op_sel:[0,1] op_sel_hi:[0,0]
	v_pk_mul_f32 v[30:31], v[170:171], v[30:31] op_sel:[0,1] op_sel_hi:[0,0]
	v_pk_mul_f32 v[24:25], v[172:173], v[24:25] op_sel:[0,1] op_sel_hi:[0,0]
	v_pk_mul_f32 v[26:27], v[174:175], v[26:27] op_sel:[0,1] op_sel_hi:[0,0]
	v_cvt_pk_bf16_f32 v28, v28, v29
	v_cvt_pk_bf16_f32 v29, v30, v31
	v_cvt_pk_bf16_f32 v30, v24, v25
	v_cvt_pk_bf16_f32 v31, v26, v27
	global_store_dwordx4 v[164:165], v[28:31], off nt
	v_pk_mul_f32 v[20:21], v[20:21], v[244:245] op_sel_hi:[1,0]
	v_pk_mul_f32 v[22:23], v[22:23], v[244:245] op_sel_hi:[1,0]
	v_pk_mul_f32 v[16:17], v[16:17], v[244:245] op_sel_hi:[1,0]
	v_pk_mul_f32 v[18:19], v[18:19], v[244:245] op_sel_hi:[1,0]
	v_min_f32_e32 v20, 0x42700000, v20
	v_min_f32_e32 v21, 0x42700000, v21
	v_min_f32_e32 v22, 0x42700000, v22
	v_min_f32_e32 v23, 0x42700000, v23
	v_min_f32_e32 v16, 0x42700000, v16
	v_min_f32_e32 v17, 0x42700000, v17
	v_min_f32_e32 v18, 0x42700000, v18
	v_min_f32_e32 v19, 0x42700000, v19
	v_exp_f32_e32 v20, v20
	v_exp_f32_e32 v21, v21
	v_exp_f32_e32 v22, v22
	v_exp_f32_e32 v23, v23
	v_exp_f32_e32 v16, v16
	v_exp_f32_e32 v17, v17
	v_exp_f32_e32 v18, v18
	v_exp_f32_e32 v19, v19
	v_pk_add_f32 v[20:21], v[20:21], 1.0 op_sel_hi:[1,0]
	v_pk_add_f32 v[22:23], v[22:23], 1.0 op_sel_hi:[1,0]
	v_pk_add_f32 v[16:17], v[16:17], 1.0 op_sel_hi:[1,0]
	v_pk_add_f32 v[18:19], v[18:19], 1.0 op_sel_hi:[1,0]
	v_mul_f32_e32 v168, v20, v21
	v_mul_f32_e32 v170, v22, v23
	v_mul_f32_e32 v172, v16, v17
	v_mul_f32_e32 v174, v18, v19
	v_rcp_f32_e32 v168, v168
	v_rcp_f32_e32 v170, v170
	v_rcp_f32_e32 v172, v172
	v_rcp_f32_e32 v174, v174
	v_pk_mul_f32 v[20:21], v[168:169], v[20:21] op_sel:[0,1] op_sel_hi:[0,0]
	v_pk_mul_f32 v[22:23], v[170:171], v[22:23] op_sel:[0,1] op_sel_hi:[0,0]
	v_pk_mul_f32 v[16:17], v[172:173], v[16:17] op_sel:[0,1] op_sel_hi:[0,0]
	v_pk_mul_f32 v[18:19], v[174:175], v[18:19] op_sel:[0,1] op_sel_hi:[0,0]
	v_cvt_pk_bf16_f32 v20, v20, v21
	v_cvt_pk_bf16_f32 v21, v22, v23
	v_cvt_pk_bf16_f32 v22, v16, v17
	v_cvt_pk_bf16_f32 v23, v18, v19
	global_store_dwordx4 v[164:165], v[20:23], off offset:256 nt
	v_lshl_add_u64 v[164:165], v[164:165], 0, s[98:99]
	v_pk_mul_f32 v[12:13], v[12:13], v[244:245] op_sel:[0,1]
	v_pk_mul_f32 v[14:15], v[14:15], v[244:245] op_sel:[0,1]
	v_pk_mul_f32 v[8:9], v[8:9], v[244:245] op_sel:[0,1]
	v_pk_mul_f32 v[10:11], v[10:11], v[244:245] op_sel:[0,1]
	v_min_f32_e32 v12, 0x42700000, v12
	v_min_f32_e32 v13, 0x42700000, v13
	v_min_f32_e32 v14, 0x42700000, v14
	v_min_f32_e32 v15, 0x42700000, v15
	v_min_f32_e32 v8, 0x42700000, v8
	v_min_f32_e32 v9, 0x42700000, v9
	v_min_f32_e32 v10, 0x42700000, v10
	v_min_f32_e32 v11, 0x42700000, v11
	v_exp_f32_e32 v12, v12
	v_exp_f32_e32 v13, v13
	v_exp_f32_e32 v14, v14
	v_exp_f32_e32 v15, v15
	v_exp_f32_e32 v8, v8
	v_exp_f32_e32 v9, v9
	v_exp_f32_e32 v10, v10
	v_exp_f32_e32 v11, v11
	v_pk_add_f32 v[12:13], v[12:13], 1.0 op_sel_hi:[1,0]
	v_pk_add_f32 v[14:15], v[14:15], 1.0 op_sel_hi:[1,0]
	v_pk_add_f32 v[8:9], v[8:9], 1.0 op_sel_hi:[1,0]
	v_pk_add_f32 v[10:11], v[10:11], 1.0 op_sel_hi:[1,0]
	v_mul_f32_e32 v168, v12, v13
	v_mul_f32_e32 v170, v14, v15
	v_mul_f32_e32 v172, v8, v9
	v_mul_f32_e32 v174, v10, v11
	v_rcp_f32_e32 v168, v168
	v_rcp_f32_e32 v170, v170
	v_rcp_f32_e32 v172, v172
	v_rcp_f32_e32 v174, v174
	v_pk_mul_f32 v[12:13], v[168:169], v[12:13] op_sel:[0,1] op_sel_hi:[0,0]
	v_pk_mul_f32 v[14:15], v[170:171], v[14:15] op_sel:[0,1] op_sel_hi:[0,0]
	v_pk_mul_f32 v[8:9], v[172:173], v[8:9] op_sel:[0,1] op_sel_hi:[0,0]
	v_pk_mul_f32 v[10:11], v[174:175], v[10:11] op_sel:[0,1] op_sel_hi:[0,0]
	v_cvt_pk_bf16_f32 v12, v12, v13
	v_cvt_pk_bf16_f32 v13, v14, v15
	v_cvt_pk_bf16_f32 v14, v8, v9
	v_cvt_pk_bf16_f32 v15, v10, v11
	global_store_dwordx4 v[164:165], v[12:15], off nt
	v_pk_mul_f32 v[4:5], v[4:5], v[244:245] op_sel:[0,1]
	v_pk_mul_f32 v[6:7], v[6:7], v[244:245] op_sel:[0,1]
	v_pk_mul_f32 v[0:1], v[0:1], v[244:245] op_sel:[0,1]
	v_pk_mul_f32 v[2:3], v[2:3], v[244:245] op_sel:[0,1]
	v_min_f32_e32 v4, 0x42700000, v4
	v_min_f32_e32 v5, 0x42700000, v5
	v_min_f32_e32 v6, 0x42700000, v6
	v_min_f32_e32 v7, 0x42700000, v7
	v_min_f32_e32 v0, 0x42700000, v0
	v_min_f32_e32 v1, 0x42700000, v1
	v_min_f32_e32 v2, 0x42700000, v2
	v_min_f32_e32 v3, 0x42700000, v3
	v_exp_f32_e32 v4, v4
	v_exp_f32_e32 v5, v5
	v_exp_f32_e32 v6, v6
	v_exp_f32_e32 v7, v7
	v_exp_f32_e32 v0, v0
	v_exp_f32_e32 v1, v1
	v_exp_f32_e32 v2, v2
	v_exp_f32_e32 v3, v3
	v_pk_add_f32 v[4:5], v[4:5], 1.0 op_sel_hi:[1,0]
	v_pk_add_f32 v[6:7], v[6:7], 1.0 op_sel_hi:[1,0]
	v_pk_add_f32 v[0:1], v[0:1], 1.0 op_sel_hi:[1,0]
	v_pk_add_f32 v[2:3], v[2:3], 1.0 op_sel_hi:[1,0]
	v_mul_f32_e32 v168, v4, v5
	v_mul_f32_e32 v170, v6, v7
	v_mul_f32_e32 v172, v0, v1
	v_mul_f32_e32 v174, v2, v3
	v_rcp_f32_e32 v168, v168
	v_rcp_f32_e32 v170, v170
	v_rcp_f32_e32 v172, v172
	v_rcp_f32_e32 v174, v174
	v_pk_mul_f32 v[4:5], v[168:169], v[4:5] op_sel:[0,1] op_sel_hi:[0,0]
	v_pk_mul_f32 v[6:7], v[170:171], v[6:7] op_sel:[0,1] op_sel_hi:[0,0]
	v_pk_mul_f32 v[0:1], v[172:173], v[0:1] op_sel:[0,1] op_sel_hi:[0,0]
	v_pk_mul_f32 v[2:3], v[174:175], v[2:3] op_sel:[0,1] op_sel_hi:[0,0]
	v_cvt_pk_bf16_f32 v4, v4, v5
	v_cvt_pk_bf16_f32 v5, v6, v7
	v_cvt_pk_bf16_f32 v6, v0, v1
	v_cvt_pk_bf16_f32 v7, v2, v3
	global_store_dwordx4 v[164:165], v[4:7], off offset:256 nt
	s_branch .Lr2_done
; DI u32x2 pk4(f32x4 v) { u32x2 r; r.x = pk2(v[0], v[1]); r.y = pk2(v[2], v[3]); return r; }
; DI float fast_exp2(float x) { return __builtin_amdgcn_exp2f(x); }
; DI float sigmoidf_(float v) { return __builtin_amdgcn_rcpf(1.f + fast_exp2(-1.4426950408889634f * v)); }
; template <int REG>
; DI void epi_inproj(const Params& p, f32x4 (&acc)[2][2][4][2], int pm, int pn, LAS unsigned char* shm) {
;     ...
; #pragma unroll
;     for (int ai = 0; ai < 2; ++ai)
; #pragma unroll
;       for (int m = 0; m < 4; ++m) { asm volatile("" ::: "memory");
;         const int r = 128 * ai + 64 * wr + 16 * m + fr;
;         const float rs = rsr[ai][m];
; #pragma unroll
;         for (int bj = 0; bj < 2; ++bj) {
;           u32x2 h[2];
; #pragma unroll
;           for (int n = 0; n < 2; ++n) {
;             f32x4 v = acc[ai][bj][m][n] * rs, o;
; #pragma unroll
;             for (int j = 0; j < 4; ++j) { const float sg = sigmoidf_(v[j]); o[j] = silu ? v[j] * sg : sg; }
;             h[n] = pk4(o);
;           }
;           *(u32x4*)(dstb + (long)(T0 + r) * 1024 + cb + 128 * bj + 32 * wc + 8 * fq) = (u32x4){h[0].x, h[0].y, h[1].x, h[1].y};
;         }
.Lr2_silu:
	v_pk_mul_f32 v[128:129], v[128:129], v[132:133] op_sel_hi:[1,0]
	v_pk_mul_f32 v[130:131], v[130:131], v[132:133] op_sel_hi:[1,0]
	v_pk_mul_f32 v[124:125], v[124:125], v[132:133] op_sel_hi:[1,0]
	v_pk_mul_f32 v[126:127], v[126:127], v[132:133] op_sel_hi:[1,0]
	v_pk_mul_f32 v[246:247], v[128:129], v[166:167]
	v_pk_mul_f32 v[248:249], v[130:131], v[166:167]
	v_pk_mul_f32 v[252:253], v[124:125], v[166:167]
	v_pk_mul_f32 v[254:255], v[126:127], v[166:167]
	v_min_f32_e32 v246, 0x42700000, v246
	v_min_f32_e32 v247, 0x42700000, v247
	v_min_f32_e32 v248, 0x42700000, v248
	v_min_f32_e32 v249, 0x42700000, v249
	v_min_f32_e32 v252, 0x42700000, v252
	v_min_f32_e32 v253, 0x42700000, v253
	v_min_f32_e32 v254, 0x42700000, v254
	v_min_f32_e32 v255, 0x42700000, v255
	v_exp_f32_e32 v246, v246
	v_exp_f32_e32 v247, v247
	v_exp_f32_e32 v248, v248
	v_exp_f32_e32 v249, v249
	v_exp_f32_e32 v252, v252
	v_exp_f32_e32 v253, v253
	v_exp_f32_e32 v254, v254
	v_exp_f32_e32 v255, v255
	v_pk_add_f32 v[246:247], v[246:247], 1.0 op_sel_hi:[1,0]
	v_pk_add_f32 v[248:249], v[248:249], 1.0 op_sel_hi:[1,0]
	v_pk_add_f32 v[252:253], v[252:253], 1.0 op_sel_hi:[1,0]
	v_pk_add_f32 v[254:255], v[254:255], 1.0 op_sel_hi:[1,0]
	v_mul_f32_e32 v168, v246, v247
	v_mul_f32_e32 v170, v248, v249
	v_mul_f32_e32 v172, v252, v253
	v_mul_f32_e32 v174, v254, v255
	v_rcp_f32_e32 v168, v168
	v_rcp_f32_e32 v170, v170
	v_rcp_f32_e32 v172, v172
	v_rcp_f32_e32 v174, v174
	v_pk_mul_f32 v[246:247], v[168:169], v[246:247] op_sel:[0,1] op_sel_hi:[0,0]
	v_pk_mul_f32 v[248:249], v[170:171], v[248:249] op_sel:[0,1] op_sel_hi:[0,0]
	v_pk_mul_f32 v[252:253], v[172:173], v[252:253] op_sel:[0,1] op_sel_hi:[0,0]
	v_pk_mul_f32 v[254:255], v[174:175], v[254:255] op_sel:[0,1] op_sel_hi:[0,0]
	v_pk_mul_f32 v[128:129], v[128:129], v[246:247]
	v_pk_mul_f32 v[130:131], v[130:131], v[248:249]
	v_pk_mul_f32 v[124:125], v[124:125], v[252:253]
	v_pk_mul_f32 v[126:127], v[126:127], v[254:255]
	v_cvt_pk_bf16_f32 v128, v128, v129
	v_cvt_pk_bf16_f32 v129, v130, v131
	v_cvt_pk_bf16_f32 v130, v124, v125
	v_cvt_pk_bf16_f32 v131, v126, v127
	global_store_dwordx4 v[164:165], v[128:131], off nt
	v_pk_mul_f32 v[120:121], v[120:121], v[132:133] op_sel_hi:[1,0]
	v_pk_mul_f32 v[122:123], v[122:123], v[132:133] op_sel_hi:[1,0]
	v_pk_mul_f32 v[116:117], v[116:117], v[132:133] op_sel_hi:[1,0]
	v_pk_mul_f32 v[118:119], v[118:119], v[132:133] op_sel_hi:[1,0]
	v_pk_mul_f32 v[246:247], v[120:121], v[166:167]
	v_pk_mul_f32 v[248:249], v[122:123], v[166:167]
	v_pk_mul_f32 v[252:253], v[116:117], v[166:167]
	v_pk_mul_f32 v[254:255], v[118:119], v[166:167]
	v_min_f32_e32 v246, 0x42700000, v246
	v_min_f32_e32 v247, 0x42700000, v247
	v_min_f32_e32 v248, 0x42700000, v248
	v_min_f32_e32 v249, 0x42700000, v249
	v_min_f32_e32 v252, 0x42700000, v252
	v_min_f32_e32 v253, 0x42700000, v253
	v_min_f32_e32 v254, 0x42700000, v254
	v_min_f32_e32 v255, 0x42700000, v255
	v_exp_f32_e32 v246, v246
	v_exp_f32_e32 v247, v247
	v_exp_f32_e32 v248, v248
	v_exp_f32_e32 v249, v249
	v_exp_f32_e32 v252, v252
	v_exp_f32_e32 v253, v253
	v_exp_f32_e32 v254, v254
	v_exp_f32_e32 v255, v255
	v_pk_add_f32 v[246:247], v[246:247], 1.0 op_sel_hi:[1,0]
	v_pk_add_f32 v[248:249], v[248:249], 1.0 op_sel_hi:[1,0]
	v_pk_add_f32 v[252:253], v[252:253], 1.0 op_sel_hi:[1,0]
	v_pk_add_f32 v[254:255], v[254:255], 1.0 op_sel_hi:[1,0]
	v_mul_f32_e32 v168, v246, v247
	v_mul_f32_e32 v170, v248, v249
	v_mul_f32_e32 v172, v252, v253
	v_mul_f32_e32 v174, v254, v255
	v_rcp_f32_e32 v168, v168
	v_rcp_f32_e32 v170, v170
	v_rcp_f32_e32 v172, v172
	v_rcp_f32_e32 v174, v174
	v_pk_mul_f32 v[246:247], v[168:169], v[246:247] op_sel:[0,1] op_sel_hi:[0,0]
	v_pk_mul_f32 v[248:249], v[170:171], v[248:249] op_sel:[0,1] op_sel_hi:[0,0]
	v_pk_mul_f32 v[252:253], v[172:173], v[252:253] op_sel:[0,1] op_sel_hi:[0,0]
	v_pk_mul_f32 v[254:255], v[174:175], v[254:255] op_sel:[0,1] op_sel_hi:[0,0]
	v_pk_mul_f32 v[120:121], v[120:121], v[246:247]
	v_pk_mul_f32 v[122:123], v[122:123], v[248:249]
	v_pk_mul_f32 v[116:117], v[116:117], v[252:253]
	v_pk_mul_f32 v[118:119], v[118:119], v[254:255]
	v_cvt_pk_bf16_f32 v120, v120, v121
	v_cvt_pk_bf16_f32 v121, v122, v123
	v_cvt_pk_bf16_f32 v122, v116, v117
	v_cvt_pk_bf16_f32 v123, v118, v119
	global_store_dwordx4 v[164:165], v[120:123], off offset:256 nt
	v_lshl_add_u64 v[164:165], v[164:165], 0, s[98:99]
	v_pk_mul_f32 v[112:113], v[112:113], v[132:133] op_sel:[0,1]
	v_pk_mul_f32 v[114:115], v[114:115], v[132:133] op_sel:[0,1]
	v_pk_mul_f32 v[108:109], v[108:109], v[132:133] op_sel:[0,1]
	v_pk_mul_f32 v[110:111], v[110:111], v[132:133] op_sel:[0,1]
	v_pk_mul_f32 v[246:247], v[112:113], v[166:167]
	v_pk_mul_f32 v[248:249], v[114:115], v[166:167]
	v_pk_mul_f32 v[252:253], v[108:109], v[166:167]
	v_pk_mul_f32 v[254:255], v[110:111], v[166:167]
	v_min_f32_e32 v246, 0x42700000, v246
	v_min_f32_e32 v247, 0x42700000, v247
	v_min_f32_e32 v248, 0x42700000, v248
	v_min_f32_e32 v249, 0x42700000, v249
	v_min_f32_e32 v252, 0x42700000, v252
	v_min_f32_e32 v253, 0x42700000, v253
	v_min_f32_e32 v254, 0x42700000, v254
	v_min_f32_e32 v255, 0x42700000, v255
	v_exp_f32_e32 v246, v246
	v_exp_f32_e32 v247, v247
	v_exp_f32_e32 v248, v248
	v_exp_f32_e32 v249, v249
	v_exp_f32_e32 v252, v252
	v_exp_f32_e32 v253, v253
	v_exp_f32_e32 v254, v254
	v_exp_f32_e32 v255, v255
	v_pk_add_f32 v[246:247], v[246:247], 1.0 op_sel_hi:[1,0]
	v_pk_add_f32 v[248:249], v[248:249], 1.0 op_sel_hi:[1,0]
	v_pk_add_f32 v[252:253], v[252:253], 1.0 op_sel_hi:[1,0]
	v_pk_add_f32 v[254:255], v[254:255], 1.0 op_sel_hi:[1,0]
	v_mul_f32_e32 v168, v246, v247
	v_mul_f32_e32 v170, v248, v249
	v_mul_f32_e32 v172, v252, v253
; DI u32x2 pk4(f32x4 v) { u32x2 r; r.x = pk2(v[0], v[1]); r.y = pk2(v[2], v[3]); return r; }
; DI float fast_exp2(float x) { return __builtin_amdgcn_exp2f(x); }
; DI float sigmoidf_(float v) { return __builtin_amdgcn_rcpf(1.f + fast_exp2(-1.4426950408889634f * v)); }
; template <int REG>
; DI void epi_inproj(const Params& p, f32x4 (&acc)[2][2][4][2], int pm, int pn, LAS unsigned char* shm) {
;     ...
; #pragma unroll
;     for (int ai = 0; ai < 2; ++ai)
; #pragma unroll
;       for (int m = 0; m < 4; ++m) { asm volatile("" ::: "memory");
;         const int r = 128 * ai + 64 * wr + 16 * m + fr;
;         const float rs = rsr[ai][m];
; #pragma unroll
;         for (int bj = 0; bj < 2; ++bj) {
;           u32x2 h[2];
; #pragma unroll
;           for (int n = 0; n < 2; ++n) {
;             f32x4 v = acc[ai][bj][m][n] * rs, o;
; #pragma unroll
;             for (int j = 0; j < 4; ++j) { const float sg = sigmoidf_(v[j]); o[j] = silu ? v[j] * sg : sg; }
;             h[n] = pk4(o);
;           }
;           *(u32x4*)(dstb + (long)(T0 + r) * 1024 + cb + 128 * bj + 32 * wc + 8 * fq) = (u32x4){h[0].x, h[0].y, h[1].x, h[1].y};
;         }
	v_mul_f32_e32 v174, v254, v255
	v_rcp_f32_e32 v168, v168
	v_rcp_f32_e32 v170, v170
	v_rcp_f32_e32 v172, v172
	v_rcp_f32_e32 v174, v174
	v_pk_mul_f32 v[246:247], v[168:169], v[246:247] op_sel:[0,1] op_sel_hi:[0,0]
	v_pk_mul_f32 v[248:249], v[170:171], v[248:249] op_sel:[0,1] op_sel_hi:[0,0]
	v_pk_mul_f32 v[252:253], v[172:173], v[252:253] op_sel:[0,1] op_sel_hi:[0,0]
	v_pk_mul_f32 v[254:255], v[174:175], v[254:255] op_sel:[0,1] op_sel_hi:[0,0]
	v_pk_mul_f32 v[112:113], v[112:113], v[246:247]
	v_pk_mul_f32 v[114:115], v[114:115], v[248:249]
	v_pk_mul_f32 v[108:109], v[108:109], v[252:253]
	v_pk_mul_f32 v[110:111], v[110:111], v[254:255]
	v_cvt_pk_bf16_f32 v112, v112, v113
	v_cvt_pk_bf16_f32 v113, v114, v115
	v_cvt_pk_bf16_f32 v114, v108, v109
	v_cvt_pk_bf16_f32 v115, v110, v111
	global_store_dwordx4 v[164:165], v[112:115], off nt
	v_pk_mul_f32 v[104:105], v[104:105], v[132:133] op_sel:[0,1]
	v_pk_mul_f32 v[106:107], v[106:107], v[132:133] op_sel:[0,1]
	v_pk_mul_f32 v[100:101], v[100:101], v[132:133] op_sel:[0,1]
	v_pk_mul_f32 v[102:103], v[102:103], v[132:133] op_sel:[0,1]
	v_pk_mul_f32 v[246:247], v[104:105], v[166:167]
	v_pk_mul_f32 v[248:249], v[106:107], v[166:167]
	v_pk_mul_f32 v[252:253], v[100:101], v[166:167]
	v_pk_mul_f32 v[254:255], v[102:103], v[166:167]
	v_min_f32_e32 v246, 0x42700000, v246
	v_min_f32_e32 v247, 0x42700000, v247
	v_min_f32_e32 v248, 0x42700000, v248
	v_min_f32_e32 v249, 0x42700000, v249
	v_min_f32_e32 v252, 0x42700000, v252
	v_min_f32_e32 v253, 0x42700000, v253
	v_min_f32_e32 v254, 0x42700000, v254
	v_min_f32_e32 v255, 0x42700000, v255
	v_exp_f32_e32 v246, v246
	v_exp_f32_e32 v247, v247
	v_exp_f32_e32 v248, v248
	v_exp_f32_e32 v249, v249
	v_exp_f32_e32 v252, v252
	v_exp_f32_e32 v253, v253
	v_exp_f32_e32 v254, v254
	v_exp_f32_e32 v255, v255
	v_pk_add_f32 v[246:247], v[246:247], 1.0 op_sel_hi:[1,0]
	v_pk_add_f32 v[248:249], v[248:249], 1.0 op_sel_hi:[1,0]
	v_pk_add_f32 v[252:253], v[252:253], 1.0 op_sel_hi:[1,0]
	v_pk_add_f32 v[254:255], v[254:255], 1.0 op_sel_hi:[1,0]
	v_mul_f32_e32 v168, v246, v247
	v_mul_f32_e32 v170, v248, v249
	v_mul_f32_e32 v172, v252, v253
	v_mul_f32_e32 v174, v254, v255
	v_rcp_f32_e32 v168, v168
	v_rcp_f32_e32 v170, v170
	v_rcp_f32_e32 v172, v172
	v_rcp_f32_e32 v174, v174
	v_pk_mul_f32 v[246:247], v[168:169], v[246:247] op_sel:[0,1] op_sel_hi:[0,0]
	v_pk_mul_f32 v[248:249], v[170:171], v[248:249] op_sel:[0,1] op_sel_hi:[0,0]
	v_pk_mul_f32 v[252:253], v[172:173], v[252:253] op_sel:[0,1] op_sel_hi:[0,0]
	v_pk_mul_f32 v[254:255], v[174:175], v[254:255] op_sel:[0,1] op_sel_hi:[0,0]
	v_pk_mul_f32 v[104:105], v[104:105], v[246:247]
	v_pk_mul_f32 v[106:107], v[106:107], v[248:249]
	v_pk_mul_f32 v[100:101], v[100:101], v[252:253]
	v_pk_mul_f32 v[102:103], v[102:103], v[254:255]
	v_cvt_pk_bf16_f32 v104, v104, v105
	v_cvt_pk_bf16_f32 v105, v106, v107
	v_cvt_pk_bf16_f32 v106, v100, v101
	v_cvt_pk_bf16_f32 v107, v102, v103
	global_store_dwordx4 v[164:165], v[104:107], off offset:256 nt
	v_lshl_add_u64 v[164:165], v[164:165], 0, s[98:99]
	v_pk_mul_f32 v[96:97], v[96:97], v[134:135] op_sel_hi:[1,0]
	v_pk_mul_f32 v[98:99], v[98:99], v[134:135] op_sel_hi:[1,0]
	v_pk_mul_f32 v[92:93], v[92:93], v[134:135] op_sel_hi:[1,0]
	v_pk_mul_f32 v[94:95], v[94:95], v[134:135] op_sel_hi:[1,0]
	v_pk_mul_f32 v[246:247], v[96:97], v[166:167]
	v_pk_mul_f32 v[248:249], v[98:99], v[166:167]
	v_pk_mul_f32 v[252:253], v[92:93], v[166:167]
	v_pk_mul_f32 v[254:255], v[94:95], v[166:167]
	v_min_f32_e32 v246, 0x42700000, v246
	v_min_f32_e32 v247, 0x42700000, v247
	v_min_f32_e32 v248, 0x42700000, v248
	v_min_f32_e32 v249, 0x42700000, v249
	v_min_f32_e32 v252, 0x42700000, v252
	v_min_f32_e32 v253, 0x42700000, v253
	v_min_f32_e32 v254, 0x42700000, v254
	v_min_f32_e32 v255, 0x42700000, v255
	v_exp_f32_e32 v246, v246
	v_exp_f32_e32 v247, v247
	v_exp_f32_e32 v248, v248
	v_exp_f32_e32 v249, v249
	v_exp_f32_e32 v252, v252
	v_exp_f32_e32 v253, v253
	v_exp_f32_e32 v254, v254
	v_exp_f32_e32 v255, v255
	v_pk_add_f32 v[246:247], v[246:247], 1.0 op_sel_hi:[1,0]
	v_pk_add_f32 v[248:249], v[248:249], 1.0 op_sel_hi:[1,0]
	v_pk_add_f32 v[252:253], v[252:253], 1.0 op_sel_hi:[1,0]
	v_pk_add_f32 v[254:255], v[254:255], 1.0 op_sel_hi:[1,0]
	v_mul_f32_e32 v168, v246, v247
	v_mul_f32_e32 v170, v248, v249
	v_mul_f32_e32 v172, v252, v253
	v_mul_f32_e32 v174, v254, v255
	v_rcp_f32_e32 v168, v168
	v_rcp_f32_e32 v170, v170
	v_rcp_f32_e32 v172, v172
	v_rcp_f32_e32 v174, v174
	v_pk_mul_f32 v[246:247], v[168:169], v[246:247] op_sel:[0,1] op_sel_hi:[0,0]
	v_pk_mul_f32 v[248:249], v[170:171], v[248:249] op_sel:[0,1] op_sel_hi:[0,0]
	v_pk_mul_f32 v[252:253], v[172:173], v[252:253] op_sel:[0,1] op_sel_hi:[0,0]
	v_pk_mul_f32 v[254:255], v[174:175], v[254:255] op_sel:[0,1] op_sel_hi:[0,0]
	v_pk_mul_f32 v[96:97], v[96:97], v[246:247]
	v_pk_mul_f32 v[98:99], v[98:99], v[248:249]
	v_pk_mul_f32 v[92:93], v[92:93], v[252:253]
	v_pk_mul_f32 v[94:95], v[94:95], v[254:255]
	v_cvt_pk_bf16_f32 v96, v96, v97
	v_cvt_pk_bf16_f32 v97, v98, v99
	v_cvt_pk_bf16_f32 v98, v92, v93
	v_cvt_pk_bf16_f32 v99, v94, v95
	global_store_dwordx4 v[164:165], v[96:99], off nt
	v_pk_mul_f32 v[88:89], v[88:89], v[134:135] op_sel_hi:[1,0]
	v_pk_mul_f32 v[90:91], v[90:91], v[134:135] op_sel_hi:[1,0]
	v_pk_mul_f32 v[84:85], v[84:85], v[134:135] op_sel_hi:[1,0]
	v_pk_mul_f32 v[86:87], v[86:87], v[134:135] op_sel_hi:[1,0]
	v_pk_mul_f32 v[246:247], v[88:89], v[166:167]
	v_pk_mul_f32 v[248:249], v[90:91], v[166:167]
	v_pk_mul_f32 v[252:253], v[84:85], v[166:167]
	v_pk_mul_f32 v[254:255], v[86:87], v[166:167]
	v_min_f32_e32 v246, 0x42700000, v246
	v_min_f32_e32 v247, 0x42700000, v247
	v_min_f32_e32 v248, 0x42700000, v248
; DI u32x2 pk4(f32x4 v) { u32x2 r; r.x = pk2(v[0], v[1]); r.y = pk2(v[2], v[3]); return r; }
; DI float fast_exp2(float x) { return __builtin_amdgcn_exp2f(x); }
; DI float sigmoidf_(float v) { return __builtin_amdgcn_rcpf(1.f + fast_exp2(-1.4426950408889634f * v)); }
; template <int REG>
; DI void epi_inproj(const Params& p, f32x4 (&acc)[2][2][4][2], int pm, int pn, LAS unsigned char* shm) {
;     ...
; #pragma unroll
;     for (int ai = 0; ai < 2; ++ai)
; #pragma unroll
;       for (int m = 0; m < 4; ++m) { asm volatile("" ::: "memory");
;         const int r = 128 * ai + 64 * wr + 16 * m + fr;
;         const float rs = rsr[ai][m];
; #pragma unroll
;         for (int bj = 0; bj < 2; ++bj) {
;           u32x2 h[2];
; #pragma unroll
;           for (int n = 0; n < 2; ++n) {
;             f32x4 v = acc[ai][bj][m][n] * rs, o;
; #pragma unroll
;             for (int j = 0; j < 4; ++j) { const float sg = sigmoidf_(v[j]); o[j] = silu ? v[j] * sg : sg; }
;             h[n] = pk4(o);
;           }
;           *(u32x4*)(dstb + (long)(T0 + r) * 1024 + cb + 128 * bj + 32 * wc + 8 * fq) = (u32x4){h[0].x, h[0].y, h[1].x, h[1].y};
;         }
	v_min_f32_e32 v249, 0x42700000, v249
	v_min_f32_e32 v252, 0x42700000, v252
	v_min_f32_e32 v253, 0x42700000, v253
	v_min_f32_e32 v254, 0x42700000, v254
	v_min_f32_e32 v255, 0x42700000, v255
	v_exp_f32_e32 v246, v246
	v_exp_f32_e32 v247, v247
	v_exp_f32_e32 v248, v248
	v_exp_f32_e32 v249, v249
	v_exp_f32_e32 v252, v252
	v_exp_f32_e32 v253, v253
	v_exp_f32_e32 v254, v254
	v_exp_f32_e32 v255, v255
	v_pk_add_f32 v[246:247], v[246:247], 1.0 op_sel_hi:[1,0]
	v_pk_add_f32 v[248:249], v[248:249], 1.0 op_sel_hi:[1,0]
	v_pk_add_f32 v[252:253], v[252:253], 1.0 op_sel_hi:[1,0]
	v_pk_add_f32 v[254:255], v[254:255], 1.0 op_sel_hi:[1,0]
	v_mul_f32_e32 v168, v246, v247
	v_mul_f32_e32 v170, v248, v249
	v_mul_f32_e32 v172, v252, v253
	v_mul_f32_e32 v174, v254, v255
	v_rcp_f32_e32 v168, v168
	v_rcp_f32_e32 v170, v170
	v_rcp_f32_e32 v172, v172
	v_rcp_f32_e32 v174, v174
	v_pk_mul_f32 v[246:247], v[168:169], v[246:247] op_sel:[0,1] op_sel_hi:[0,0]
	v_pk_mul_f32 v[248:249], v[170:171], v[248:249] op_sel:[0,1] op_sel_hi:[0,0]
	v_pk_mul_f32 v[252:253], v[172:173], v[252:253] op_sel:[0,1] op_sel_hi:[0,0]
	v_pk_mul_f32 v[254:255], v[174:175], v[254:255] op_sel:[0,1] op_sel_hi:[0,0]
	v_pk_mul_f32 v[88:89], v[88:89], v[246:247]
	v_pk_mul_f32 v[90:91], v[90:91], v[248:249]
	v_pk_mul_f32 v[84:85], v[84:85], v[252:253]
	v_pk_mul_f32 v[86:87], v[86:87], v[254:255]
	v_cvt_pk_bf16_f32 v88, v88, v89
	v_cvt_pk_bf16_f32 v89, v90, v91
	v_cvt_pk_bf16_f32 v90, v84, v85
	v_cvt_pk_bf16_f32 v91, v86, v87
	global_store_dwordx4 v[164:165], v[88:91], off offset:256 nt
	v_lshl_add_u64 v[164:165], v[164:165], 0, s[98:99]
	v_pk_mul_f32 v[80:81], v[80:81], v[134:135] op_sel:[0,1]
	v_pk_mul_f32 v[82:83], v[82:83], v[134:135] op_sel:[0,1]
	v_pk_mul_f32 v[76:77], v[76:77], v[134:135] op_sel:[0,1]
	v_pk_mul_f32 v[78:79], v[78:79], v[134:135] op_sel:[0,1]
	v_pk_mul_f32 v[246:247], v[80:81], v[166:167]
	v_pk_mul_f32 v[248:249], v[82:83], v[166:167]
	v_pk_mul_f32 v[252:253], v[76:77], v[166:167]
	v_pk_mul_f32 v[254:255], v[78:79], v[166:167]
	v_min_f32_e32 v246, 0x42700000, v246
	v_min_f32_e32 v247, 0x42700000, v247
	v_min_f32_e32 v248, 0x42700000, v248
	v_min_f32_e32 v249, 0x42700000, v249
	v_min_f32_e32 v252, 0x42700000, v252
	v_min_f32_e32 v253, 0x42700000, v253
	v_min_f32_e32 v254, 0x42700000, v254
	v_min_f32_e32 v255, 0x42700000, v255
	v_exp_f32_e32 v246, v246
	v_exp_f32_e32 v247, v247
	v_exp_f32_e32 v248, v248
	v_exp_f32_e32 v249, v249
	v_exp_f32_e32 v252, v252
	v_exp_f32_e32 v253, v253
	v_exp_f32_e32 v254, v254
	v_exp_f32_e32 v255, v255
	v_pk_add_f32 v[246:247], v[246:247], 1.0 op_sel_hi:[1,0]
	v_pk_add_f32 v[248:249], v[248:249], 1.0 op_sel_hi:[1,0]
	v_pk_add_f32 v[252:253], v[252:253], 1.0 op_sel_hi:[1,0]
	v_pk_add_f32 v[254:255], v[254:255], 1.0 op_sel_hi:[1,0]
	v_mul_f32_e32 v168, v246, v247
	v_mul_f32_e32 v170, v248, v249
	v_mul_f32_e32 v172, v252, v253
	v_mul_f32_e32 v174, v254, v255
	v_rcp_f32_e32 v168, v168
	v_rcp_f32_e32 v170, v170
	v_rcp_f32_e32 v172, v172
	v_rcp_f32_e32 v174, v174
	v_pk_mul_f32 v[246:247], v[168:169], v[246:247] op_sel:[0,1] op_sel_hi:[0,0]
	v_pk_mul_f32 v[248:249], v[170:171], v[248:249] op_sel:[0,1] op_sel_hi:[0,0]
	v_pk_mul_f32 v[252:253], v[172:173], v[252:253] op_sel:[0,1] op_sel_hi:[0,0]
	v_pk_mul_f32 v[254:255], v[174:175], v[254:255] op_sel:[0,1] op_sel_hi:[0,0]
	v_pk_mul_f32 v[80:81], v[80:81], v[246:247]
	v_pk_mul_f32 v[82:83], v[82:83], v[248:249]
	v_pk_mul_f32 v[76:77], v[76:77], v[252:253]
	v_pk_mul_f32 v[78:79], v[78:79], v[254:255]
	v_cvt_pk_bf16_f32 v80, v80, v81
	v_cvt_pk_bf16_f32 v81, v82, v83
	v_cvt_pk_bf16_f32 v82, v76, v77
	v_cvt_pk_bf16_f32 v83, v78, v79
	global_store_dwordx4 v[164:165], v[80:83], off nt
	v_pk_mul_f32 v[68:69], v[68:69], v[134:135] op_sel:[0,1]
	v_pk_mul_f32 v[70:71], v[70:71], v[134:135] op_sel:[0,1]
	v_pk_mul_f32 v[64:65], v[64:65], v[134:135] op_sel:[0,1]
	v_pk_mul_f32 v[66:67], v[66:67], v[134:135] op_sel:[0,1]
	v_pk_mul_f32 v[246:247], v[68:69], v[166:167]
	v_pk_mul_f32 v[248:249], v[70:71], v[166:167]
	v_pk_mul_f32 v[252:253], v[64:65], v[166:167]
	v_pk_mul_f32 v[254:255], v[66:67], v[166:167]
	v_min_f32_e32 v246, 0x42700000, v246
	v_min_f32_e32 v247, 0x42700000, v247
	v_min_f32_e32 v248, 0x42700000, v248
	v_min_f32_e32 v249, 0x42700000, v249
	v_min_f32_e32 v252, 0x42700000, v252
	v_min_f32_e32 v253, 0x42700000, v253
	v_min_f32_e32 v254, 0x42700000, v254
	v_min_f32_e32 v255, 0x42700000, v255
	v_exp_f32_e32 v246, v246
	v_exp_f32_e32 v247, v247
	v_exp_f32_e32 v248, v248
	v_exp_f32_e32 v249, v249
	v_exp_f32_e32 v252, v252
	v_exp_f32_e32 v253, v253
	v_exp_f32_e32 v254, v254
	v_exp_f32_e32 v255, v255
	v_pk_add_f32 v[246:247], v[246:247], 1.0 op_sel_hi:[1,0]
	v_pk_add_f32 v[248:249], v[248:249], 1.0 op_sel_hi:[1,0]
	v_pk_add_f32 v[252:253], v[252:253], 1.0 op_sel_hi:[1,0]
	v_pk_add_f32 v[254:255], v[254:255], 1.0 op_sel_hi:[1,0]
	v_mul_f32_e32 v168, v246, v247
	v_mul_f32_e32 v170, v248, v249
	v_mul_f32_e32 v172, v252, v253
	v_mul_f32_e32 v174, v254, v255
	v_rcp_f32_e32 v168, v168
	v_rcp_f32_e32 v170, v170
	v_rcp_f32_e32 v172, v172
	v_rcp_f32_e32 v174, v174
	v_pk_mul_f32 v[246:247], v[168:169], v[246:247] op_sel:[0,1] op_sel_hi:[0,0]
	v_pk_mul_f32 v[248:249], v[170:171], v[248:249] op_sel:[0,1] op_sel_hi:[0,0]
	v_pk_mul_f32 v[252:253], v[172:173], v[252:253] op_sel:[0,1] op_sel_hi:[0,0]
	v_pk_mul_f32 v[254:255], v[174:175], v[254:255] op_sel:[0,1] op_sel_hi:[0,0]
	v_pk_mul_f32 v[68:69], v[68:69], v[246:247]
	v_pk_mul_f32 v[70:71], v[70:71], v[248:249]
	v_pk_mul_f32 v[64:65], v[64:65], v[252:253]
	v_pk_mul_f32 v[66:67], v[66:67], v[254:255]
	v_cvt_pk_bf16_f32 v68, v68, v69
	v_cvt_pk_bf16_f32 v69, v70, v71
; DI u32x2 pk4(f32x4 v) { u32x2 r; r.x = pk2(v[0], v[1]); r.y = pk2(v[2], v[3]); return r; }
; DI float fast_exp2(float x) { return __builtin_amdgcn_exp2f(x); }
; DI float sigmoidf_(float v) { return __builtin_amdgcn_rcpf(1.f + fast_exp2(-1.4426950408889634f * v)); }
; template <int REG>
; DI void epi_inproj(const Params& p, f32x4 (&acc)[2][2][4][2], int pm, int pn, LAS unsigned char* shm) {
;     ...
; #pragma unroll
;     for (int ai = 0; ai < 2; ++ai)
; #pragma unroll
;       for (int m = 0; m < 4; ++m) { asm volatile("" ::: "memory");
;         const int r = 128 * ai + 64 * wr + 16 * m + fr;
;         const float rs = rsr[ai][m];
; #pragma unroll
;         for (int bj = 0; bj < 2; ++bj) {
;           u32x2 h[2];
; #pragma unroll
;           for (int n = 0; n < 2; ++n) {
;             f32x4 v = acc[ai][bj][m][n] * rs, o;
; #pragma unroll
;             for (int j = 0; j < 4; ++j) { const float sg = sigmoidf_(v[j]); o[j] = silu ? v[j] * sg : sg; }
;             h[n] = pk4(o);
;           }
;           *(u32x4*)(dstb + (long)(T0 + r) * 1024 + cb + 128 * bj + 32 * wc + 8 * fq) = (u32x4){h[0].x, h[0].y, h[1].x, h[1].y};
;         }
	v_cvt_pk_bf16_f32 v70, v64, v65
	v_cvt_pk_bf16_f32 v71, v66, v67
	global_store_dwordx4 v[164:165], v[68:71], off offset:256 nt
	v_lshl_add_u64 v[164:165], v[164:165], 0, s[100:101]
	v_pk_mul_f32 v[60:61], v[60:61], v[72:73] op_sel_hi:[1,0]
	v_pk_mul_f32 v[62:63], v[62:63], v[72:73] op_sel_hi:[1,0]
	v_pk_mul_f32 v[56:57], v[56:57], v[72:73] op_sel_hi:[1,0]
	v_pk_mul_f32 v[58:59], v[58:59], v[72:73] op_sel_hi:[1,0]
	v_pk_mul_f32 v[246:247], v[60:61], v[166:167]
	v_pk_mul_f32 v[248:249], v[62:63], v[166:167]
	v_pk_mul_f32 v[252:253], v[56:57], v[166:167]
	v_pk_mul_f32 v[254:255], v[58:59], v[166:167]
	v_min_f32_e32 v246, 0x42700000, v246
	v_min_f32_e32 v247, 0x42700000, v247
	v_min_f32_e32 v248, 0x42700000, v248
	v_min_f32_e32 v249, 0x42700000, v249
	v_min_f32_e32 v252, 0x42700000, v252
	v_min_f32_e32 v253, 0x42700000, v253
	v_min_f32_e32 v254, 0x42700000, v254
	v_min_f32_e32 v255, 0x42700000, v255
	v_exp_f32_e32 v246, v246
	v_exp_f32_e32 v247, v247
	v_exp_f32_e32 v248, v248
	v_exp_f32_e32 v249, v249
	v_exp_f32_e32 v252, v252
	v_exp_f32_e32 v253, v253
	v_exp_f32_e32 v254, v254
	v_exp_f32_e32 v255, v255
	v_pk_add_f32 v[246:247], v[246:247], 1.0 op_sel_hi:[1,0]
	v_pk_add_f32 v[248:249], v[248:249], 1.0 op_sel_hi:[1,0]
	v_pk_add_f32 v[252:253], v[252:253], 1.0 op_sel_hi:[1,0]
	v_pk_add_f32 v[254:255], v[254:255], 1.0 op_sel_hi:[1,0]
	v_mul_f32_e32 v168, v246, v247
	v_mul_f32_e32 v170, v248, v249
	v_mul_f32_e32 v172, v252, v253
	v_mul_f32_e32 v174, v254, v255
	v_rcp_f32_e32 v168, v168
	v_rcp_f32_e32 v170, v170
	v_rcp_f32_e32 v172, v172
	v_rcp_f32_e32 v174, v174
	v_pk_mul_f32 v[246:247], v[168:169], v[246:247] op_sel:[0,1] op_sel_hi:[0,0]
	v_pk_mul_f32 v[248:249], v[170:171], v[248:249] op_sel:[0,1] op_sel_hi:[0,0]
	v_pk_mul_f32 v[252:253], v[172:173], v[252:253] op_sel:[0,1] op_sel_hi:[0,0]
	v_pk_mul_f32 v[254:255], v[174:175], v[254:255] op_sel:[0,1] op_sel_hi:[0,0]
	v_pk_mul_f32 v[60:61], v[60:61], v[246:247]
	v_pk_mul_f32 v[62:63], v[62:63], v[248:249]
	v_pk_mul_f32 v[56:57], v[56:57], v[252:253]
	v_pk_mul_f32 v[58:59], v[58:59], v[254:255]
	v_cvt_pk_bf16_f32 v60, v60, v61
	v_cvt_pk_bf16_f32 v61, v62, v63
	v_cvt_pk_bf16_f32 v62, v56, v57
	v_cvt_pk_bf16_f32 v63, v58, v59
	global_store_dwordx4 v[164:165], v[60:63], off nt
	v_pk_mul_f32 v[52:53], v[52:53], v[72:73] op_sel_hi:[1,0]
	v_pk_mul_f32 v[54:55], v[54:55], v[72:73] op_sel_hi:[1,0]
	v_pk_mul_f32 v[48:49], v[48:49], v[72:73] op_sel_hi:[1,0]
	v_pk_mul_f32 v[50:51], v[50:51], v[72:73] op_sel_hi:[1,0]
	v_pk_mul_f32 v[246:247], v[52:53], v[166:167]
	v_pk_mul_f32 v[248:249], v[54:55], v[166:167]
	v_pk_mul_f32 v[252:253], v[48:49], v[166:167]
	v_pk_mul_f32 v[254:255], v[50:51], v[166:167]
	v_min_f32_e32 v246, 0x42700000, v246
	v_min_f32_e32 v247, 0x42700000, v247
	v_min_f32_e32 v248, 0x42700000, v248
	v_min_f32_e32 v249, 0x42700000, v249
	v_min_f32_e32 v252, 0x42700000, v252
	v_min_f32_e32 v253, 0x42700000, v253
	v_min_f32_e32 v254, 0x42700000, v254
	v_min_f32_e32 v255, 0x42700000, v255
	v_exp_f32_e32 v246, v246
	v_exp_f32_e32 v247, v247
	v_exp_f32_e32 v248, v248
	v_exp_f32_e32 v249, v249
	v_exp_f32_e32 v252, v252
	v_exp_f32_e32 v253, v253
	v_exp_f32_e32 v254, v254
	v_exp_f32_e32 v255, v255
	v_pk_add_f32 v[246:247], v[246:247], 1.0 op_sel_hi:[1,0]
	v_pk_add_f32 v[248:249], v[248:249], 1.0 op_sel_hi:[1,0]
	v_pk_add_f32 v[252:253], v[252:253], 1.0 op_sel_hi:[1,0]
	v_pk_add_f32 v[254:255], v[254:255], 1.0 op_sel_hi:[1,0]
	v_mul_f32_e32 v168, v246, v247
	v_mul_f32_e32 v170, v248, v249
	v_mul_f32_e32 v172, v252, v253
	v_mul_f32_e32 v174, v254, v255
	v_rcp_f32_e32 v168, v168
	v_rcp_f32_e32 v170, v170
	v_rcp_f32_e32 v172, v172
	v_rcp_f32_e32 v174, v174
	v_pk_mul_f32 v[246:247], v[168:169], v[246:247] op_sel:[0,1] op_sel_hi:[0,0]
	v_pk_mul_f32 v[248:249], v[170:171], v[248:249] op_sel:[0,1] op_sel_hi:[0,0]
	v_pk_mul_f32 v[252:253], v[172:173], v[252:253] op_sel:[0,1] op_sel_hi:[0,0]
	v_pk_mul_f32 v[254:255], v[174:175], v[254:255] op_sel:[0,1] op_sel_hi:[0,0]
	v_pk_mul_f32 v[52:53], v[52:53], v[246:247]
	v_pk_mul_f32 v[54:55], v[54:55], v[248:249]
	v_pk_mul_f32 v[48:49], v[48:49], v[252:253]
	v_pk_mul_f32 v[50:51], v[50:51], v[254:255]
	v_cvt_pk_bf16_f32 v52, v52, v53
	v_cvt_pk_bf16_f32 v53, v54, v55
	v_cvt_pk_bf16_f32 v54, v48, v49
	v_cvt_pk_bf16_f32 v55, v50, v51
	global_store_dwordx4 v[164:165], v[52:55], off offset:256 nt
	v_lshl_add_u64 v[164:165], v[164:165], 0, s[98:99]
	v_pk_mul_f32 v[44:45], v[44:45], v[72:73] op_sel:[0,1]
	v_pk_mul_f32 v[46:47], v[46:47], v[72:73] op_sel:[0,1]
	v_pk_mul_f32 v[40:41], v[40:41], v[72:73] op_sel:[0,1]
	v_pk_mul_f32 v[42:43], v[42:43], v[72:73] op_sel:[0,1]
	v_pk_mul_f32 v[246:247], v[44:45], v[166:167]
	v_pk_mul_f32 v[248:249], v[46:47], v[166:167]
	v_pk_mul_f32 v[252:253], v[40:41], v[166:167]
	v_pk_mul_f32 v[254:255], v[42:43], v[166:167]
	v_min_f32_e32 v246, 0x42700000, v246
	v_min_f32_e32 v247, 0x42700000, v247
	v_min_f32_e32 v248, 0x42700000, v248
	v_min_f32_e32 v249, 0x42700000, v249
	v_min_f32_e32 v252, 0x42700000, v252
	v_min_f32_e32 v253, 0x42700000, v253
	v_min_f32_e32 v254, 0x42700000, v254
	v_min_f32_e32 v255, 0x42700000, v255
	v_exp_f32_e32 v246, v246
	v_exp_f32_e32 v247, v247
	v_exp_f32_e32 v248, v248
	v_exp_f32_e32 v249, v249
	v_exp_f32_e32 v252, v252
	v_exp_f32_e32 v253, v253
	v_exp_f32_e32 v254, v254
	v_exp_f32_e32 v255, v255
	v_pk_add_f32 v[246:247], v[246:247], 1.0 op_sel_hi:[1,0]
	v_pk_add_f32 v[248:249], v[248:249], 1.0 op_sel_hi:[1,0]
	v_pk_add_f32 v[252:253], v[252:253], 1.0 op_sel_hi:[1,0]
	v_pk_add_f32 v[254:255], v[254:255], 1.0 op_sel_hi:[1,0]
	v_mul_f32_e32 v168, v246, v247
	v_mul_f32_e32 v170, v248, v249
	v_mul_f32_e32 v172, v252, v253
; DI u32x2 pk4(f32x4 v) { u32x2 r; r.x = pk2(v[0], v[1]); r.y = pk2(v[2], v[3]); return r; }
; DI float fast_exp2(float x) { return __builtin_amdgcn_exp2f(x); }
; DI float sigmoidf_(float v) { return __builtin_amdgcn_rcpf(1.f + fast_exp2(-1.4426950408889634f * v)); }
; template <int REG>
; DI void epi_inproj(const Params& p, f32x4 (&acc)[2][2][4][2], int pm, int pn, LAS unsigned char* shm) {
;     ...
; #pragma unroll
;     for (int ai = 0; ai < 2; ++ai)
; #pragma unroll
;       for (int m = 0; m < 4; ++m) { asm volatile("" ::: "memory");
;         const int r = 128 * ai + 64 * wr + 16 * m + fr;
;         const float rs = rsr[ai][m];
; #pragma unroll
;         for (int bj = 0; bj < 2; ++bj) {
;           u32x2 h[2];
; #pragma unroll
;           for (int n = 0; n < 2; ++n) {
;             f32x4 v = acc[ai][bj][m][n] * rs, o;
; #pragma unroll
;             for (int j = 0; j < 4; ++j) { const float sg = sigmoidf_(v[j]); o[j] = silu ? v[j] * sg : sg; }
;             h[n] = pk4(o);
;           }
;           *(u32x4*)(dstb + (long)(T0 + r) * 1024 + cb + 128 * bj + 32 * wc + 8 * fq) = (u32x4){h[0].x, h[0].y, h[1].x, h[1].y};
;         }
	v_mul_f32_e32 v174, v254, v255
	v_rcp_f32_e32 v168, v168
	v_rcp_f32_e32 v170, v170
	v_rcp_f32_e32 v172, v172
	v_rcp_f32_e32 v174, v174
	v_pk_mul_f32 v[246:247], v[168:169], v[246:247] op_sel:[0,1] op_sel_hi:[0,0]
	v_pk_mul_f32 v[248:249], v[170:171], v[248:249] op_sel:[0,1] op_sel_hi:[0,0]
	v_pk_mul_f32 v[252:253], v[172:173], v[252:253] op_sel:[0,1] op_sel_hi:[0,0]
	v_pk_mul_f32 v[254:255], v[174:175], v[254:255] op_sel:[0,1] op_sel_hi:[0,0]
	v_pk_mul_f32 v[44:45], v[44:45], v[246:247]
	v_pk_mul_f32 v[46:47], v[46:47], v[248:249]
	v_pk_mul_f32 v[40:41], v[40:41], v[252:253]
	v_pk_mul_f32 v[42:43], v[42:43], v[254:255]
	v_cvt_pk_bf16_f32 v44, v44, v45
	v_cvt_pk_bf16_f32 v45, v46, v47
	v_cvt_pk_bf16_f32 v46, v40, v41
	v_cvt_pk_bf16_f32 v47, v42, v43
	global_store_dwordx4 v[164:165], v[44:47], off nt
	v_pk_mul_f32 v[36:37], v[36:37], v[72:73] op_sel:[0,1]
	v_pk_mul_f32 v[38:39], v[38:39], v[72:73] op_sel:[0,1]
	v_pk_mul_f32 v[32:33], v[32:33], v[72:73] op_sel:[0,1]
	v_pk_mul_f32 v[34:35], v[34:35], v[72:73] op_sel:[0,1]
	v_pk_mul_f32 v[246:247], v[36:37], v[166:167]
	v_pk_mul_f32 v[248:249], v[38:39], v[166:167]
	v_pk_mul_f32 v[252:253], v[32:33], v[166:167]
	v_pk_mul_f32 v[254:255], v[34:35], v[166:167]
	v_min_f32_e32 v246, 0x42700000, v246
	v_min_f32_e32 v247, 0x42700000, v247
	v_min_f32_e32 v248, 0x42700000, v248
	v_min_f32_e32 v249, 0x42700000, v249
	v_min_f32_e32 v252, 0x42700000, v252
	v_min_f32_e32 v253, 0x42700000, v253
	v_min_f32_e32 v254, 0x42700000, v254
	v_min_f32_e32 v255, 0x42700000, v255
	v_exp_f32_e32 v246, v246
	v_exp_f32_e32 v247, v247
	v_exp_f32_e32 v248, v248
	v_exp_f32_e32 v249, v249
	v_exp_f32_e32 v252, v252
	v_exp_f32_e32 v253, v253
	v_exp_f32_e32 v254, v254
	v_exp_f32_e32 v255, v255
	v_pk_add_f32 v[246:247], v[246:247], 1.0 op_sel_hi:[1,0]
	v_pk_add_f32 v[248:249], v[248:249], 1.0 op_sel_hi:[1,0]
	v_pk_add_f32 v[252:253], v[252:253], 1.0 op_sel_hi:[1,0]
	v_pk_add_f32 v[254:255], v[254:255], 1.0 op_sel_hi:[1,0]
	v_mul_f32_e32 v168, v246, v247
	v_mul_f32_e32 v170, v248, v249
	v_mul_f32_e32 v172, v252, v253
	v_mul_f32_e32 v174, v254, v255
	v_rcp_f32_e32 v168, v168
	v_rcp_f32_e32 v170, v170
	v_rcp_f32_e32 v172, v172
	v_rcp_f32_e32 v174, v174
	v_pk_mul_f32 v[246:247], v[168:169], v[246:247] op_sel:[0,1] op_sel_hi:[0,0]
	v_pk_mul_f32 v[248:249], v[170:171], v[248:249] op_sel:[0,1] op_sel_hi:[0,0]
	v_pk_mul_f32 v[252:253], v[172:173], v[252:253] op_sel:[0,1] op_sel_hi:[0,0]
	v_pk_mul_f32 v[254:255], v[174:175], v[254:255] op_sel:[0,1] op_sel_hi:[0,0]
	v_pk_mul_f32 v[36:37], v[36:37], v[246:247]
	v_pk_mul_f32 v[38:39], v[38:39], v[248:249]
	v_pk_mul_f32 v[32:33], v[32:33], v[252:253]
	v_pk_mul_f32 v[34:35], v[34:35], v[254:255]
	v_cvt_pk_bf16_f32 v36, v36, v37
	v_cvt_pk_bf16_f32 v37, v38, v39
	v_cvt_pk_bf16_f32 v38, v32, v33
	v_cvt_pk_bf16_f32 v39, v34, v35
	global_store_dwordx4 v[164:165], v[36:39], off offset:256 nt
	v_lshl_add_u64 v[164:165], v[164:165], 0, s[98:99]
	v_pk_mul_f32 v[28:29], v[28:29], v[74:75] op_sel_hi:[1,0]
	v_pk_mul_f32 v[30:31], v[30:31], v[74:75] op_sel_hi:[1,0]
	v_pk_mul_f32 v[24:25], v[24:25], v[74:75] op_sel_hi:[1,0]
	v_pk_mul_f32 v[26:27], v[26:27], v[74:75] op_sel_hi:[1,0]
	v_pk_mul_f32 v[246:247], v[28:29], v[166:167]
	v_pk_mul_f32 v[248:249], v[30:31], v[166:167]
	v_pk_mul_f32 v[252:253], v[24:25], v[166:167]
	v_pk_mul_f32 v[254:255], v[26:27], v[166:167]
	v_min_f32_e32 v246, 0x42700000, v246
	v_min_f32_e32 v247, 0x42700000, v247
	v_min_f32_e32 v248, 0x42700000, v248
	v_min_f32_e32 v249, 0x42700000, v249
	v_min_f32_e32 v252, 0x42700000, v252
	v_min_f32_e32 v253, 0x42700000, v253
	v_min_f32_e32 v254, 0x42700000, v254
	v_min_f32_e32 v255, 0x42700000, v255
	v_exp_f32_e32 v246, v246
	v_exp_f32_e32 v247, v247
	v_exp_f32_e32 v248, v248
	v_exp_f32_e32 v249, v249
	v_exp_f32_e32 v252, v252
	v_exp_f32_e32 v253, v253
	v_exp_f32_e32 v254, v254
	v_exp_f32_e32 v255, v255
	v_pk_add_f32 v[246:247], v[246:247], 1.0 op_sel_hi:[1,0]
	v_pk_add_f32 v[248:249], v[248:249], 1.0 op_sel_hi:[1,0]
	v_pk_add_f32 v[252:253], v[252:253], 1.0 op_sel_hi:[1,0]
	v_pk_add_f32 v[254:255], v[254:255], 1.0 op_sel_hi:[1,0]
	v_mul_f32_e32 v168, v246, v247
	v_mul_f32_e32 v170, v248, v249
	v_mul_f32_e32 v172, v252, v253
	v_mul_f32_e32 v174, v254, v255
	v_rcp_f32_e32 v168, v168
	v_rcp_f32_e32 v170, v170
	v_rcp_f32_e32 v172, v172
	v_rcp_f32_e32 v174, v174
	v_pk_mul_f32 v[246:247], v[168:169], v[246:247] op_sel:[0,1] op_sel_hi:[0,0]
	v_pk_mul_f32 v[248:249], v[170:171], v[248:249] op_sel:[0,1] op_sel_hi:[0,0]
	v_pk_mul_f32 v[252:253], v[172:173], v[252:253] op_sel:[0,1] op_sel_hi:[0,0]
	v_pk_mul_f32 v[254:255], v[174:175], v[254:255] op_sel:[0,1] op_sel_hi:[0,0]
	v_pk_mul_f32 v[28:29], v[28:29], v[246:247]
	v_pk_mul_f32 v[30:31], v[30:31], v[248:249]
	v_pk_mul_f32 v[24:25], v[24:25], v[252:253]
	v_pk_mul_f32 v[26:27], v[26:27], v[254:255]
	v_cvt_pk_bf16_f32 v28, v28, v29
	v_cvt_pk_bf16_f32 v29, v30, v31
	v_cvt_pk_bf16_f32 v30, v24, v25
	v_cvt_pk_bf16_f32 v31, v26, v27
	global_store_dwordx4 v[164:165], v[28:31], off nt
	v_pk_mul_f32 v[20:21], v[20:21], v[74:75] op_sel_hi:[1,0]
	v_pk_mul_f32 v[22:23], v[22:23], v[74:75] op_sel_hi:[1,0]
	v_pk_mul_f32 v[16:17], v[16:17], v[74:75] op_sel_hi:[1,0]
	v_pk_mul_f32 v[18:19], v[18:19], v[74:75] op_sel_hi:[1,0]
	v_pk_mul_f32 v[246:247], v[20:21], v[166:167]
	v_pk_mul_f32 v[248:249], v[22:23], v[166:167]
	v_pk_mul_f32 v[252:253], v[16:17], v[166:167]
	v_pk_mul_f32 v[254:255], v[18:19], v[166:167]
	v_min_f32_e32 v246, 0x42700000, v246
	v_min_f32_e32 v247, 0x42700000, v247
	v_min_f32_e32 v248, 0x42700000, v248
	v_min_f32_e32 v249, 0x42700000, v249
	v_min_f32_e32 v252, 0x42700000, v252
; DI u32x2 pk4(f32x4 v) { u32x2 r; r.x = pk2(v[0], v[1]); r.y = pk2(v[2], v[3]); return r; }
; DI float sigmoidf_(float v) { return __builtin_amdgcn_rcpf(1.f + fast_exp2(-1.4426950408889634f * v)); }
; template <int REG>
; DI void epi_inproj(const Params& p, f32x4 (&acc)[2][2][4][2], int pm, int pn, LAS unsigned char* shm) {
;     ...
; #pragma unroll
;     for (int ai = 0; ai < 2; ++ai)
; #pragma unroll
;       for (int m = 0; m < 4; ++m) { asm volatile("" ::: "memory");
;         const int r = 128 * ai + 64 * wr + 16 * m + fr;
;         const float rs = rsr[ai][m];
; #pragma unroll
;         for (int bj = 0; bj < 2; ++bj) {
;           u32x2 h[2];
; #pragma unroll
;           for (int n = 0; n < 2; ++n) {
;             f32x4 v = acc[ai][bj][m][n] * rs, o;
; #pragma unroll
;             for (int j = 0; j < 4; ++j) { const float sg = sigmoidf_(v[j]); o[j] = silu ? v[j] * sg : sg; }
;             h[n] = pk4(o);
;           }
;           *(u32x4*)(dstb + (long)(T0 + r) * 1024 + cb + 128 * bj + 32 * wc + 8 * fq) = (u32x4){h[0].x, h[0].y, h[1].x, h[1].y};
;         }
	v_min_f32_e32 v253, 0x42700000, v253
	v_min_f32_e32 v254, 0x42700000, v254
	v_min_f32_e32 v255, 0x42700000, v255
	v_exp_f32_e32 v246, v246
	v_exp_f32_e32 v247, v247
	v_exp_f32_e32 v248, v248
	v_exp_f32_e32 v249, v249
	v_exp_f32_e32 v252, v252
	v_exp_f32_e32 v253, v253
	v_exp_f32_e32 v254, v254
	v_exp_f32_e32 v255, v255
	v_pk_add_f32 v[246:247], v[246:247], 1.0 op_sel_hi:[1,0]
	v_pk_add_f32 v[248:249], v[248:249], 1.0 op_sel_hi:[1,0]
	v_pk_add_f32 v[252:253], v[252:253], 1.0 op_sel_hi:[1,0]
	v_pk_add_f32 v[254:255], v[254:255], 1.0 op_sel_hi:[1,0]
	v_mul_f32_e32 v168, v246, v247
	v_mul_f32_e32 v170, v248, v249
	v_mul_f32_e32 v172, v252, v253
	v_mul_f32_e32 v174, v254, v255
	v_rcp_f32_e32 v168, v168
	v_rcp_f32_e32 v170, v170
	v_rcp_f32_e32 v172, v172
	v_rcp_f32_e32 v174, v174
	v_pk_mul_f32 v[246:247], v[168:169], v[246:247] op_sel:[0,1] op_sel_hi:[0,0]
	v_pk_mul_f32 v[248:249], v[170:171], v[248:249] op_sel:[0,1] op_sel_hi:[0,0]
	v_pk_mul_f32 v[252:253], v[172:173], v[252:253] op_sel:[0,1] op_sel_hi:[0,0]
	v_pk_mul_f32 v[254:255], v[174:175], v[254:255] op_sel:[0,1] op_sel_hi:[0,0]
	v_pk_mul_f32 v[20:21], v[20:21], v[246:247]
	v_pk_mul_f32 v[22:23], v[22:23], v[248:249]
	v_pk_mul_f32 v[16:17], v[16:17], v[252:253]
	v_pk_mul_f32 v[18:19], v[18:19], v[254:255]
	v_cvt_pk_bf16_f32 v20, v20, v21
	v_cvt_pk_bf16_f32 v21, v22, v23
	v_cvt_pk_bf16_f32 v22, v16, v17
	v_cvt_pk_bf16_f32 v23, v18, v19
	global_store_dwordx4 v[164:165], v[20:23], off offset:256 nt
	v_lshl_add_u64 v[164:165], v[164:165], 0, s[98:99]
	v_pk_mul_f32 v[12:13], v[12:13], v[74:75] op_sel:[0,1]
	v_pk_mul_f32 v[14:15], v[14:15], v[74:75] op_sel:[0,1]
	v_pk_mul_f32 v[8:9], v[8:9], v[74:75] op_sel:[0,1]
	v_pk_mul_f32 v[10:11], v[10:11], v[74:75] op_sel:[0,1]
	v_pk_mul_f32 v[246:247], v[12:13], v[166:167]
	v_pk_mul_f32 v[248:249], v[14:15], v[166:167]
	v_pk_mul_f32 v[252:253], v[8:9], v[166:167]
	v_pk_mul_f32 v[254:255], v[10:11], v[166:167]
	v_min_f32_e32 v246, 0x42700000, v246
	v_min_f32_e32 v247, 0x42700000, v247
	v_min_f32_e32 v248, 0x42700000, v248
	v_min_f32_e32 v249, 0x42700000, v249
	v_min_f32_e32 v252, 0x42700000, v252
	v_min_f32_e32 v253, 0x42700000, v253
	v_min_f32_e32 v254, 0x42700000, v254
	v_min_f32_e32 v255, 0x42700000, v255
	v_exp_f32_e32 v246, v246
	v_exp_f32_e32 v247, v247
	v_exp_f32_e32 v248, v248
	v_exp_f32_e32 v249, v249
	v_exp_f32_e32 v252, v252
	v_exp_f32_e32 v253, v253
	v_exp_f32_e32 v254, v254
	v_exp_f32_e32 v255, v255
	v_pk_add_f32 v[246:247], v[246:247], 1.0 op_sel_hi:[1,0]
	v_pk_add_f32 v[248:249], v[248:249], 1.0 op_sel_hi:[1,0]
	v_pk_add_f32 v[252:253], v[252:253], 1.0 op_sel_hi:[1,0]
	v_pk_add_f32 v[254:255], v[254:255], 1.0 op_sel_hi:[1,0]
	v_mul_f32_e32 v168, v246, v247
	v_mul_f32_e32 v170, v248, v249
	v_mul_f32_e32 v172, v252, v253
	v_mul_f32_e32 v174, v254, v255
	v_rcp_f32_e32 v168, v168
	v_rcp_f32_e32 v170, v170
	v_rcp_f32_e32 v172, v172
	v_rcp_f32_e32 v174, v174
	v_pk_mul_f32 v[246:247], v[168:169], v[246:247] op_sel:[0,1] op_sel_hi:[0,0]
	v_pk_mul_f32 v[248:249], v[170:171], v[248:249] op_sel:[0,1] op_sel_hi:[0,0]
	v_pk_mul_f32 v[252:253], v[172:173], v[252:253] op_sel:[0,1] op_sel_hi:[0,0]
	v_pk_mul_f32 v[254:255], v[174:175], v[254:255] op_sel:[0,1] op_sel_hi:[0,0]
	v_pk_mul_f32 v[12:13], v[12:13], v[246:247]
	v_pk_mul_f32 v[14:15], v[14:15], v[248:249]
	v_pk_mul_f32 v[8:9], v[8:9], v[252:253]
	v_pk_mul_f32 v[10:11], v[10:11], v[254:255]
	v_cvt_pk_bf16_f32 v12, v12, v13
	v_cvt_pk_bf16_f32 v13, v14, v15
	v_cvt_pk_bf16_f32 v14, v8, v9
	v_cvt_pk_bf16_f32 v15, v10, v11
	global_store_dwordx4 v[164:165], v[12:15], off nt
	v_pk_mul_f32 v[4:5], v[4:5], v[74:75] op_sel:[0,1]
	v_pk_mul_f32 v[6:7], v[6:7], v[74:75] op_sel:[0,1]
	v_pk_mul_f32 v[0:1], v[0:1], v[74:75] op_sel:[0,1]
	v_pk_mul_f32 v[2:3], v[2:3], v[74:75] op_sel:[0,1]
	v_pk_mul_f32 v[246:247], v[4:5], v[166:167]
	v_pk_mul_f32 v[248:249], v[6:7], v[166:167]
	v_pk_mul_f32 v[252:253], v[0:1], v[166:167]
	v_pk_mul_f32 v[254:255], v[2:3], v[166:167]
	v_min_f32_e32 v246, 0x42700000, v246
	v_min_f32_e32 v247, 0x42700000, v247
	v_min_f32_e32 v248, 0x42700000, v248
	v_min_f32_e32 v249, 0x42700000, v249
	v_min_f32_e32 v252, 0x42700000, v252
	v_min_f32_e32 v253, 0x42700000, v253
	v_min_f32_e32 v254, 0x42700000, v254
	v_min_f32_e32 v255, 0x42700000, v255
	v_exp_f32_e32 v246, v246
	v_exp_f32_e32 v247, v247
	v_exp_f32_e32 v248, v248
	v_exp_f32_e32 v249, v249
	v_exp_f32_e32 v252, v252
	v_exp_f32_e32 v253, v253
	v_exp_f32_e32 v254, v254
	v_exp_f32_e32 v255, v255
	v_pk_add_f32 v[246:247], v[246:247], 1.0 op_sel_hi:[1,0]
	v_pk_add_f32 v[248:249], v[248:249], 1.0 op_sel_hi:[1,0]
	v_pk_add_f32 v[252:253], v[252:253], 1.0 op_sel_hi:[1,0]
	v_pk_add_f32 v[254:255], v[254:255], 1.0 op_sel_hi:[1,0]
	v_mul_f32_e32 v168, v246, v247
	v_mul_f32_e32 v170, v248, v249
	v_mul_f32_e32 v172, v252, v253
	v_mul_f32_e32 v174, v254, v255
	v_rcp_f32_e32 v168, v168
	v_rcp_f32_e32 v170, v170
	v_rcp_f32_e32 v172, v172
	v_rcp_f32_e32 v174, v174
	v_pk_mul_f32 v[246:247], v[168:169], v[246:247] op_sel:[0,1] op_sel_hi:[0,0]
	v_pk_mul_f32 v[248:249], v[170:171], v[248:249] op_sel:[0,1] op_sel_hi:[0,0]
	v_pk_mul_f32 v[252:253], v[172:173], v[252:253] op_sel:[0,1] op_sel_hi:[0,0]
	v_pk_mul_f32 v[254:255], v[174:175], v[254:255] op_sel:[0,1] op_sel_hi:[0,0]
	v_pk_mul_f32 v[4:5], v[4:5], v[246:247]
	v_pk_mul_f32 v[6:7], v[6:7], v[248:249]
	v_pk_mul_f32 v[0:1], v[0:1], v[252:253]
	v_pk_mul_f32 v[2:3], v[2:3], v[254:255]
	v_cvt_pk_bf16_f32 v4, v4, v5
	v_cvt_pk_bf16_f32 v5, v6, v7
	v_cvt_pk_bf16_f32 v6, v0, v1
	v_cvt_pk_bf16_f32 v7, v2, v3
	global_store_dwordx4 v[164:165], v[4:7], off offset:256 nt
.Lr2_done:
	s_andn2_b64 vcc, exec, s[40:41]
	s_mov_b64 s[40:41], -1
	s_cbranch_vccnz .LBB0_192
	s_andn2_b64 vcc, exec, s[12:13]
	s_cbranch_vccnz .LBB0_191
	s_barrier
	s_branch .LBB0_191

.LBB0_233:
	s_mov_b64 s[0:1], 0x80
	v_lshl_add_u64 v[4:5], v[4:5], 0, s[0:1]
	s_add_i32 m0, s18, 0x18000
	s_waitcnt vmcnt(2)
	s_barrier
	global_load_lds_dwordx4 v[4:5], off
	v_lshl_add_u64 v[4:5], v[6:7], 0, s[0:1]
	s_add_i32 m0, s18, 0x1a000
	s_nop 0
	global_load_lds_dwordx4 v[4:5], off
	v_lshl_add_u64 v[4:5], v[8:9], 0, s[0:1]
	s_add_i32 m0, s18, 0x8000
	s_nop 0
	global_load_lds_dwordx4 v[4:5], off
	s_add_i32 m0, s18, 0xa000
	v_lshl_add_u64 v[4:5], v[10:11], 0, s[0:1]
	s_add_u32 s0, s58, 0x40080
	s_addc_u32 s1, s59, 0
	global_load_lds_dwordx4 v[4:5], off
	v_lshl_add_u64 v[4:5], v[96:97], 1, s[0:1]
	s_add_i32 m0, s18, 0x1c000
	s_nop 0
	global_load_lds_dwordx4 v[4:5], off
	v_lshl_add_u64 v[4:5], v[98:99], 1, s[0:1]
	s_add_i32 m0, s18, 0x1e000
	s_nop 0
	global_load_lds_dwordx4 v[4:5], off
	s_waitcnt vmcnt(0)
	s_barrier
	s_branch .LBB0_238

.LBB0_251:
	s_cmp_eq_u32 s5, 0
	s_cselect_b64 vcc, -1, 0
	v_cndmask_b32_e32 v0, v160, v156, vcc
	s_add_u32 s4, s60, 0x40080
	s_mov_b32 s89, s5
	v_lshl_add_u32 v167, v0, 10, v157
	v_cndmask_b32_e32 v0, v161, v158, vcc
	s_addc_u32 s5, s61, 0
	v_lshl_add_u32 v168, v0, 10, v159
	s_add_u32 s55, s58, 0x100
	v_mov_b32_e32 v0, 0
	s_addc_u32 s57, s59, 0
	s_mov_b32 s62, -2
	v_mov_b32_e32 v1, v0
	v_mov_b32_e32 v2, v0
	v_mov_b32_e32 v3, v0
	v_mov_b32_e32 v4, v0
	v_mov_b32_e32 v5, v0
	v_mov_b32_e32 v6, v0
	v_mov_b32_e32 v7, v0
	v_mov_b32_e32 v8, v0
	v_mov_b32_e32 v9, v0
	v_mov_b32_e32 v10, v0
	v_mov_b32_e32 v11, v0
	v_mov_b32_e32 v12, v0
	v_mov_b32_e32 v13, v0
	v_mov_b32_e32 v14, v0
	v_mov_b32_e32 v15, v0
	v_mov_b32_e32 v16, v0
	v_mov_b32_e32 v17, v0
	v_mov_b32_e32 v18, v0
	v_mov_b32_e32 v19, v0
	v_mov_b32_e32 v20, v0
	v_mov_b32_e32 v21, v0
	v_mov_b32_e32 v22, v0
	v_mov_b32_e32 v23, v0
	v_mov_b32_e32 v24, v0
	v_mov_b32_e32 v25, v0
	v_mov_b32_e32 v26, v0
	v_mov_b32_e32 v27, v0
	v_mov_b32_e32 v28, v0
	v_mov_b32_e32 v29, v0
	v_mov_b32_e32 v30, v0
	v_mov_b32_e32 v31, v0
	v_mov_b32_e32 v60, v0
	v_mov_b32_e32 v61, v0
	v_mov_b32_e32 v62, v0
	v_mov_b32_e32 v63, v0
	v_mov_b32_e32 v68, v0
	v_mov_b32_e32 v69, v0
	v_mov_b32_e32 v70, v0
	v_mov_b32_e32 v71, v0
	v_mov_b32_e32 v72, v0
	v_mov_b32_e32 v73, v0
	v_mov_b32_e32 v74, v0
	v_mov_b32_e32 v75, v0
	v_mov_b32_e32 v76, v0
	v_mov_b32_e32 v77, v0
	v_mov_b32_e32 v78, v0
	v_mov_b32_e32 v79, v0
	v_mov_b32_e32 v80, v0
	v_mov_b32_e32 v81, v0
	v_mov_b32_e32 v82, v0
	v_mov_b32_e32 v83, v0
	v_mov_b32_e32 v84, v0
	v_mov_b32_e32 v85, v0
	v_mov_b32_e32 v86, v0
	v_mov_b32_e32 v87, v0
	v_mov_b32_e32 v88, v0
	v_mov_b32_e32 v89, v0
	v_mov_b32_e32 v90, v0
	v_mov_b32_e32 v91, v0
	v_mov_b32_e32 v92, v0
	v_mov_b32_e32 v93, v0
	v_mov_b32_e32 v94, v0
	v_mov_b32_e32 v95, v0
	v_mov_b32_e32 v32, v0
	v_mov_b32_e32 v33, v0
	v_mov_b32_e32 v34, v0
	v_mov_b32_e32 v35, v0
	v_mov_b32_e32 v36, v0
	v_mov_b32_e32 v37, v0
	v_mov_b32_e32 v38, v0
	v_mov_b32_e32 v39, v0
	v_mov_b32_e32 v40, v0
	v_mov_b32_e32 v41, v0
	v_mov_b32_e32 v42, v0
	v_mov_b32_e32 v43, v0
	v_mov_b32_e32 v44, v0
	v_mov_b32_e32 v45, v0
	v_mov_b32_e32 v46, v0
	v_mov_b32_e32 v47, v0
	v_mov_b32_e32 v48, v0
	v_mov_b32_e32 v49, v0
	v_mov_b32_e32 v50, v0
	v_mov_b32_e32 v51, v0
	v_mov_b32_e32 v52, v0
	v_mov_b32_e32 v53, v0
	v_mov_b32_e32 v54, v0
	v_mov_b32_e32 v55, v0
	v_mov_b32_e32 v56, v0
	v_mov_b32_e32 v57, v0
	v_mov_b32_e32 v58, v0
	v_mov_b32_e32 v59, v0
	v_mov_b32_e32 v64, v0
	v_mov_b32_e32 v65, v0
	v_mov_b32_e32 v66, v0
	v_mov_b32_e32 v67, v0
	v_mov_b32_e32 v104, v0
	v_mov_b32_e32 v105, v0
	v_mov_b32_e32 v106, v0
	v_mov_b32_e32 v107, v0
	v_mov_b32_e32 v108, v0
	v_mov_b32_e32 v109, v0
	v_mov_b32_e32 v110, v0
	v_mov_b32_e32 v111, v0
	v_mov_b32_e32 v112, v0
	v_mov_b32_e32 v113, v0
	v_mov_b32_e32 v114, v0
	v_mov_b32_e32 v115, v0
	v_mov_b32_e32 v116, v0
	v_mov_b32_e32 v117, v0
	v_mov_b32_e32 v118, v0
	v_mov_b32_e32 v119, v0
	v_mov_b32_e32 v120, v0
	v_mov_b32_e32 v121, v0
	v_mov_b32_e32 v122, v0
	v_mov_b32_e32 v123, v0
	v_mov_b32_e32 v124, v0
	v_mov_b32_e32 v125, v0
	v_mov_b32_e32 v126, v0
	v_mov_b32_e32 v127, v0
	v_mov_b32_e32 v128, v0
	v_mov_b32_e32 v129, v0
	v_mov_b32_e32 v130, v0
	v_mov_b32_e32 v131, v0
	v_mov_b32_e32 v132, v0
	v_mov_b32_e32 v133, v0
	v_mov_b32_e32 v134, v0
	v_mov_b32_e32 v135, v0
	ds_read_b128 v[100:103], v162
	ds_read_b128 v[136:139], v162 offset:1024
	ds_read_b128 v[140:143], v162 offset:2048
	ds_read_b128 v[152:155], v162 offset:3072
	ds_read_b128 v[170:173], v163
	ds_read_b128 v[174:177], v163 offset:1024
	ds_read_b128 v[178:181], v163 offset:2048
	ds_read_b128 v[182:185], v163 offset:3072
	s_add_u32 s60, s4, 0xfffc0080
	s_addc_u32 s61, s5, -1
	s_cmp_eq_u32 s62, 12
	s_cselect_b64 vcc, -1, 0
	s_and_b64 s[58:59], vcc, exec
	v_cndmask_b32_e32 v220, v98, v168, vcc
	s_cselect_b32 s61, s51, s61
	s_cselect_b32 s60, s50, s60
	v_cndmask_b32_e32 v222, v96, v167, vcc
	s_cselect_b32 s59, s49, s57
	s_cselect_b32 s58, s48, s55
	s_mov_b32 m0, s85
	v_lshl_add_u64 v[224:225], s[4:5], 0, v[144:145]
	ds_read_b128 v[186:189], v164
	ds_read_b128 v[190:193], v164 offset:1024
	ds_read_b128 v[196:199], v164 offset:2048
	ds_read_b128 v[200:203], v164 offset:3072
	ds_read_b128 v[204:207], v164 offset:4096
	ds_read_b128 v[208:211], v164 offset:5120
	ds_read_b128 v[212:215], v164 offset:6144
	ds_read_b128 v[216:219], v164 offset:7168
	global_load_lds_dwordx4 v[224:225], off
	v_lshl_add_u64 v[224:225], s[4:5], 0, v[146:147]
	s_mov_b32 m0, s86
	s_nop 0
	global_load_lds_dwordx4 v[224:225], off
	s_waitcnt lgkmcnt(0)
	s_barrier
	s_setprio 1
	s_waitcnt lgkmcnt(0)
	v_mfma_f32_16x16x32_bf16 v[132:135], v[100:103], v[186:189], v[132:135]
	v_mfma_f32_16x16x32_bf16 v[128:131], v[140:143], v[186:189], v[128:131]
	v_mfma_f32_16x16x32_bf16 v[124:127], v[100:103], v[196:199], v[124:127]
	v_mfma_f32_16x16x32_bf16 v[120:123], v[140:143], v[196:199], v[120:123]
	v_mfma_f32_16x16x32_bf16 v[116:119], v[100:103], v[204:207], v[116:119]
	v_mfma_f32_16x16x32_bf16 v[112:115], v[140:143], v[204:207], v[112:115]
	v_mfma_f32_16x16x32_bf16 v[108:111], v[100:103], v[212:215], v[108:111]
	v_mfma_f32_16x16x32_bf16 v[104:107], v[140:143], v[212:215], v[104:107]
	v_mfma_f32_16x16x32_bf16 v[132:135], v[136:139], v[190:193], v[132:135]
	v_mfma_f32_16x16x32_bf16 v[128:131], v[152:155], v[190:193], v[128:131]
	v_mfma_f32_16x16x32_bf16 v[124:127], v[136:139], v[200:203], v[124:127]
	v_mfma_f32_16x16x32_bf16 v[120:123], v[152:155], v[200:203], v[120:123]
	v_mfma_f32_16x16x32_bf16 v[116:119], v[136:139], v[208:211], v[116:119]
	v_mfma_f32_16x16x32_bf16 v[112:115], v[152:155], v[208:211], v[112:115]
	v_mfma_f32_16x16x32_bf16 v[108:111], v[136:139], v[216:219], v[108:111]
	v_mfma_f32_16x16x32_bf16 v[104:107], v[152:155], v[216:219], v[104:107]
	s_setprio 0
	s_setprio 1
	v_mfma_f32_16x16x32_bf16 v[64:67], v[170:173], v[186:189], v[64:67]
	v_mfma_f32_16x16x32_bf16 v[56:59], v[178:181], v[186:189], v[56:59]
	v_mfma_f32_16x16x32_bf16 v[52:55], v[170:173], v[196:199], v[52:55]
	v_mfma_f32_16x16x32_bf16 v[48:51], v[178:181], v[196:199], v[48:51]
	v_mfma_f32_16x16x32_bf16 v[44:47], v[170:173], v[204:207], v[44:47]
	v_mfma_f32_16x16x32_bf16 v[40:43], v[178:181], v[204:207], v[40:43]
	v_mfma_f32_16x16x32_bf16 v[36:39], v[170:173], v[212:215], v[36:39]
	v_mfma_f32_16x16x32_bf16 v[32:35], v[178:181], v[212:215], v[32:35]
	v_mfma_f32_16x16x32_bf16 v[64:67], v[174:177], v[190:193], v[64:67]
	v_mfma_f32_16x16x32_bf16 v[56:59], v[182:185], v[190:193], v[56:59]
	v_mfma_f32_16x16x32_bf16 v[52:55], v[174:177], v[200:203], v[52:55]
	v_mfma_f32_16x16x32_bf16 v[48:51], v[182:185], v[200:203], v[48:51]
	v_mfma_f32_16x16x32_bf16 v[44:47], v[174:177], v[208:211], v[44:47]
	v_mfma_f32_16x16x32_bf16 v[40:43], v[182:185], v[208:211], v[40:43]
	v_mfma_f32_16x16x32_bf16 v[36:39], v[174:177], v[216:219], v[36:39]
	v_mfma_f32_16x16x32_bf16 v[32:35], v[182:185], v[216:219], v[32:35]
	s_setprio 0
	s_barrier
	v_ashrrev_i32_e32 v223, 31, v222
	v_lshlrev_b64 v[222:223], 1, v[222:223]
	v_ashrrev_i32_e32 v221, 31, v220
	s_mov_b32 m0, s74
	v_lshl_add_u64 v[224:225], s[58:59], 0, v[222:223]
	v_lshlrev_b64 v[220:221], 1, v[220:221]
	s_add_u32 s64, s58, 0x40000
	ds_read_b128 v[186:189], v164 offset:16384
	ds_read_b128 v[190:193], v164 offset:17408
	ds_read_b128 v[196:199], v164 offset:18432
	ds_read_b128 v[200:203], v164 offset:19456
	ds_read_b128 v[204:207], v164 offset:20480
	ds_read_b128 v[208:211], v164 offset:21504
	ds_read_b128 v[212:215], v164 offset:22528
	ds_read_b128 v[216:219], v164 offset:23552
	global_load_lds_dwordx4 v[224:225], off
	v_lshl_add_u64 v[226:227], s[58:59], 0, v[220:221]
	s_mov_b32 m0, s75
	s_addc_u32 s65, s59, 0
	global_load_lds_dwordx4 v[226:227], off
	v_lshl_add_u64 v[228:229], s[64:65], 0, v[222:223]
	s_mov_b32 m0, s76
	v_lshl_add_u64 v[230:231], s[60:61], 0, v[146:147]
	global_load_lds_dwordx4 v[228:229], off
	v_lshl_add_u64 v[228:229], s[64:65], 0, v[220:221]
	s_mov_b32 m0, s77
	s_nop 0
	global_load_lds_dwordx4 v[228:229], off
	v_lshl_add_u64 v[228:229], s[60:61], 0, v[144:145]
	s_mov_b32 m0, s18
	s_nop 0
	global_load_lds_dwordx4 v[228:229], off
	s_mov_b32 m0, s87
	s_nop 0
	global_load_lds_dwordx4 v[230:231], off
	s_waitcnt lgkmcnt(0)
	s_barrier
	s_setprio 1
	s_waitcnt lgkmcnt(0)
	v_mfma_f32_16x16x32_bf16 v[92:95], v[100:103], v[186:189], v[92:95]
	v_mfma_f32_16x16x32_bf16 v[88:91], v[140:143], v[186:189], v[88:91]
	v_mfma_f32_16x16x32_bf16 v[84:87], v[100:103], v[196:199], v[84:87]
	v_mfma_f32_16x16x32_bf16 v[80:83], v[140:143], v[196:199], v[80:83]
	v_mfma_f32_16x16x32_bf16 v[76:79], v[100:103], v[204:207], v[76:79]
	v_mfma_f32_16x16x32_bf16 v[72:75], v[140:143], v[204:207], v[72:75]
	v_mfma_f32_16x16x32_bf16 v[68:71], v[100:103], v[212:215], v[68:71]
	v_mfma_f32_16x16x32_bf16 v[60:63], v[140:143], v[212:215], v[60:63]
	v_mfma_f32_16x16x32_bf16 v[92:95], v[136:139], v[190:193], v[92:95]
	v_mfma_f32_16x16x32_bf16 v[88:91], v[152:155], v[190:193], v[88:91]
	v_mfma_f32_16x16x32_bf16 v[84:87], v[136:139], v[200:203], v[84:87]
	v_mfma_f32_16x16x32_bf16 v[80:83], v[152:155], v[200:203], v[80:83]
	v_mfma_f32_16x16x32_bf16 v[76:79], v[136:139], v[208:211], v[76:79]
	v_mfma_f32_16x16x32_bf16 v[72:75], v[152:155], v[208:211], v[72:75]
	v_mfma_f32_16x16x32_bf16 v[68:71], v[136:139], v[216:219], v[68:71]
	v_mfma_f32_16x16x32_bf16 v[60:63], v[152:155], v[216:219], v[60:63]
	s_setprio 0
	s_setprio 1
	v_mfma_f32_16x16x32_bf16 v[28:31], v[170:173], v[186:189], v[28:31]
	v_mfma_f32_16x16x32_bf16 v[24:27], v[178:181], v[186:189], v[24:27]
	v_mfma_f32_16x16x32_bf16 v[20:23], v[170:173], v[196:199], v[20:23]
	v_mfma_f32_16x16x32_bf16 v[16:19], v[178:181], v[196:199], v[16:19]
	v_mfma_f32_16x16x32_bf16 v[12:15], v[170:173], v[204:207], v[12:15]
	v_mfma_f32_16x16x32_bf16 v[8:11], v[178:181], v[204:207], v[8:11]
	v_mfma_f32_16x16x32_bf16 v[4:7], v[170:173], v[212:215], v[4:7]
	v_mfma_f32_16x16x32_bf16 v[0:3], v[178:181], v[212:215], v[0:3]
	v_mfma_f32_16x16x32_bf16 v[28:31], v[174:177], v[190:193], v[28:31]
	v_mfma_f32_16x16x32_bf16 v[24:27], v[182:185], v[190:193], v[24:27]
	v_mfma_f32_16x16x32_bf16 v[20:23], v[174:177], v[200:203], v[20:23]
	v_mfma_f32_16x16x32_bf16 v[16:19], v[182:185], v[200:203], v[16:19]
	v_mfma_f32_16x16x32_bf16 v[12:15], v[174:177], v[208:211], v[12:15]
	v_mfma_f32_16x16x32_bf16 v[8:11], v[182:185], v[208:211], v[8:11]
	v_mfma_f32_16x16x32_bf16 v[4:7], v[174:177], v[216:219], v[4:7]
	v_mfma_f32_16x16x32_bf16 v[0:3], v[182:185], v[216:219], v[0:3]
	s_setprio 0
	s_barrier
	ds_read_b128 v[100:103], v165
	ds_read_b128 v[136:139], v165 offset:1024
	ds_read_b128 v[140:143], v165 offset:2048
	ds_read_b128 v[152:155], v165 offset:3072
	ds_read_b128 v[170:173], v166
	ds_read_b128 v[174:177], v166 offset:1024
	ds_read_b128 v[178:181], v166 offset:2048
	ds_read_b128 v[182:185], v166 offset:3072
	s_add_u32 s60, s60, 0x40000
	s_addc_u32 s61, s61, 0
	s_mov_b32 m0, s88
	v_lshl_add_u64 v[232:233], s[60:61], 0, v[144:145]
	ds_read_b128 v[186:189], v164 offset:32768
	ds_read_b128 v[190:193], v164 offset:33792
	ds_read_b128 v[196:199], v164 offset:34816
	ds_read_b128 v[200:203], v164 offset:35840
	ds_read_b128 v[204:207], v164 offset:36864
	ds_read_b128 v[208:211], v164 offset:37888
	ds_read_b128 v[212:215], v164 offset:38912
	ds_read_b128 v[216:219], v164 offset:39936
	global_load_lds_dwordx4 v[232:233], off
	v_lshl_add_u64 v[232:233], s[60:61], 0, v[146:147]
	s_mov_b32 m0, s90
	s_nop 0
	global_load_lds_dwordx4 v[232:233], off
	s_waitcnt vmcnt(8)
	s_waitcnt lgkmcnt(0)
	s_barrier
	s_setprio 1
	s_waitcnt lgkmcnt(0)
	v_mfma_f32_16x16x32_bf16 v[132:135], v[100:103], v[186:189], v[132:135]
	v_mfma_f32_16x16x32_bf16 v[128:131], v[140:143], v[186:189], v[128:131]
	v_mfma_f32_16x16x32_bf16 v[124:127], v[100:103], v[196:199], v[124:127]
	v_mfma_f32_16x16x32_bf16 v[120:123], v[140:143], v[196:199], v[120:123]
	v_mfma_f32_16x16x32_bf16 v[116:119], v[100:103], v[204:207], v[116:119]
	v_mfma_f32_16x16x32_bf16 v[112:115], v[140:143], v[204:207], v[112:115]
	v_mfma_f32_16x16x32_bf16 v[108:111], v[100:103], v[212:215], v[108:111]
	v_mfma_f32_16x16x32_bf16 v[104:107], v[140:143], v[212:215], v[104:107]
	v_mfma_f32_16x16x32_bf16 v[132:135], v[136:139], v[190:193], v[132:135]
	v_mfma_f32_16x16x32_bf16 v[128:131], v[152:155], v[190:193], v[128:131]
	v_mfma_f32_16x16x32_bf16 v[124:127], v[136:139], v[200:203], v[124:127]
	v_mfma_f32_16x16x32_bf16 v[120:123], v[152:155], v[200:203], v[120:123]
	v_mfma_f32_16x16x32_bf16 v[116:119], v[136:139], v[208:211], v[116:119]
	v_mfma_f32_16x16x32_bf16 v[112:115], v[152:155], v[208:211], v[112:115]
	v_mfma_f32_16x16x32_bf16 v[108:111], v[136:139], v[216:219], v[108:111]
	v_mfma_f32_16x16x32_bf16 v[104:107], v[152:155], v[216:219], v[104:107]
	s_setprio 0
	s_setprio 1
	v_mfma_f32_16x16x32_bf16 v[64:67], v[170:173], v[186:189], v[64:67]
	v_mfma_f32_16x16x32_bf16 v[56:59], v[178:181], v[186:189], v[56:59]
	v_mfma_f32_16x16x32_bf16 v[52:55], v[170:173], v[196:199], v[52:55]
	v_mfma_f32_16x16x32_bf16 v[48:51], v[178:181], v[196:199], v[48:51]
	v_mfma_f32_16x16x32_bf16 v[44:47], v[170:173], v[204:207], v[44:47]
	v_mfma_f32_16x16x32_bf16 v[40:43], v[178:181], v[204:207], v[40:43]
	v_mfma_f32_16x16x32_bf16 v[36:39], v[170:173], v[212:215], v[36:39]
	v_mfma_f32_16x16x32_bf16 v[32:35], v[178:181], v[212:215], v[32:35]
	v_mfma_f32_16x16x32_bf16 v[64:67], v[174:177], v[190:193], v[64:67]
	v_mfma_f32_16x16x32_bf16 v[56:59], v[182:185], v[190:193], v[56:59]
	v_mfma_f32_16x16x32_bf16 v[52:55], v[174:177], v[200:203], v[52:55]
	v_mfma_f32_16x16x32_bf16 v[48:51], v[182:185], v[200:203], v[48:51]
	v_mfma_f32_16x16x32_bf16 v[44:47], v[174:177], v[208:211], v[44:47]
	v_mfma_f32_16x16x32_bf16 v[40:43], v[182:185], v[208:211], v[40:43]
	v_mfma_f32_16x16x32_bf16 v[36:39], v[174:177], v[216:219], v[36:39]
	v_mfma_f32_16x16x32_bf16 v[32:35], v[182:185], v[216:219], v[32:35]
	s_setprio 0
	s_barrier
	s_mov_b32 m0, s78
	v_lshl_add_u64 v[224:225], v[224:225], 0, s[20:21]
	s_add_u32 s58, s58, 0x40080
	ds_read_b128 v[186:189], v164 offset:49152
	ds_read_b128 v[190:193], v164 offset:50176
	ds_read_b128 v[196:199], v164 offset:51200
	ds_read_b128 v[200:203], v164 offset:52224
	ds_read_b128 v[204:207], v164 offset:53248
	ds_read_b128 v[208:211], v164 offset:54272
	ds_read_b128 v[212:215], v164 offset:55296
	ds_read_b128 v[216:219], v164 offset:56320
	global_load_lds_dwordx4 v[224:225], off
	v_lshl_add_u64 v[224:225], v[226:227], 0, s[20:21]
	s_mov_b32 m0, s79
	s_addc_u32 s59, s59, 0
	global_load_lds_dwordx4 v[224:225], off
	v_lshl_add_u64 v[222:223], s[58:59], 0, v[222:223]
	s_mov_b32 m0, s80
	v_lshl_add_u64 v[220:221], s[58:59], 0, v[220:221]
	global_load_lds_dwordx4 v[222:223], off
	s_mov_b32 m0, s81
	s_nop 0
	global_load_lds_dwordx4 v[220:221], off
	v_lshl_add_u64 v[220:221], v[228:229], 0, s[20:21]
	s_mov_b32 m0, s91
	s_nop 0
	global_load_lds_dwordx4 v[220:221], off
	v_lshl_add_u64 v[220:221], v[230:231], 0, s[20:21]
	s_mov_b32 m0, s92
	s_nop 0
	global_load_lds_dwordx4 v[220:221], off
	s_waitcnt vmcnt(8)
	s_waitcnt lgkmcnt(0)
	s_barrier
	s_setprio 1
	s_waitcnt lgkmcnt(0)
	v_mfma_f32_16x16x32_bf16 v[92:95], v[100:103], v[186:189], v[92:95]
	v_mfma_f32_16x16x32_bf16 v[88:91], v[140:143], v[186:189], v[88:91]
	v_mfma_f32_16x16x32_bf16 v[84:87], v[100:103], v[196:199], v[84:87]
	v_mfma_f32_16x16x32_bf16 v[80:83], v[140:143], v[196:199], v[80:83]
	v_mfma_f32_16x16x32_bf16 v[76:79], v[100:103], v[204:207], v[76:79]
	v_mfma_f32_16x16x32_bf16 v[72:75], v[140:143], v[204:207], v[72:75]
	v_mfma_f32_16x16x32_bf16 v[68:71], v[100:103], v[212:215], v[68:71]
	v_mfma_f32_16x16x32_bf16 v[60:63], v[140:143], v[212:215], v[60:63]
	v_mfma_f32_16x16x32_bf16 v[92:95], v[136:139], v[190:193], v[92:95]
	v_mfma_f32_16x16x32_bf16 v[88:91], v[152:155], v[190:193], v[88:91]
	v_mfma_f32_16x16x32_bf16 v[84:87], v[136:139], v[200:203], v[84:87]
	v_mfma_f32_16x16x32_bf16 v[80:83], v[152:155], v[200:203], v[80:83]
	v_mfma_f32_16x16x32_bf16 v[76:79], v[136:139], v[208:211], v[76:79]
	v_mfma_f32_16x16x32_bf16 v[72:75], v[152:155], v[208:211], v[72:75]
	v_mfma_f32_16x16x32_bf16 v[68:71], v[136:139], v[216:219], v[68:71]
	v_mfma_f32_16x16x32_bf16 v[60:63], v[152:155], v[216:219], v[60:63]
	s_setprio 0
	s_setprio 1
	v_mfma_f32_16x16x32_bf16 v[28:31], v[170:173], v[186:189], v[28:31]
	v_mfma_f32_16x16x32_bf16 v[24:27], v[178:181], v[186:189], v[24:27]
	v_mfma_f32_16x16x32_bf16 v[20:23], v[170:173], v[196:199], v[20:23]
	v_mfma_f32_16x16x32_bf16 v[16:19], v[178:181], v[196:199], v[16:19]
	v_mfma_f32_16x16x32_bf16 v[12:15], v[170:173], v[204:207], v[12:15]
	v_mfma_f32_16x16x32_bf16 v[8:11], v[178:181], v[204:207], v[8:11]
	v_mfma_f32_16x16x32_bf16 v[4:7], v[170:173], v[212:215], v[4:7]
	v_mfma_f32_16x16x32_bf16 v[0:3], v[178:181], v[212:215], v[0:3]
	v_mfma_f32_16x16x32_bf16 v[28:31], v[174:177], v[190:193], v[28:31]
	v_mfma_f32_16x16x32_bf16 v[24:27], v[182:185], v[190:193], v[24:27]
	v_mfma_f32_16x16x32_bf16 v[20:23], v[174:177], v[200:203], v[20:23]
	v_mfma_f32_16x16x32_bf16 v[16:19], v[182:185], v[200:203], v[16:19]
	v_mfma_f32_16x16x32_bf16 v[12:15], v[174:177], v[208:211], v[12:15]
	v_mfma_f32_16x16x32_bf16 v[8:11], v[182:185], v[208:211], v[8:11]
	v_mfma_f32_16x16x32_bf16 v[4:7], v[174:177], v[216:219], v[4:7]
	v_mfma_f32_16x16x32_bf16 v[0:3], v[182:185], v[216:219], v[0:3]
	s_setprio 0
	s_barrier
	s_add_i32 s62, s62, 2
	s_add_u32 s4, s4, 0x100
	s_addc_u32 s5, s5, 0
	s_add_u32 s55, s55, 0x100
	s_addc_u32 s57, s57, 0
	s_cmp_gt_u32 s62, 13

.LBB0_343:
	s_mov_b64 s[14:15], 0x80
	v_lshl_add_u64 v[4:5], v[4:5], 0, s[14:15]
	s_add_i32 m0, s67, 0x18000
	s_waitcnt vmcnt(2)
	s_barrier
	global_load_lds_dwordx4 v[4:5], off
	v_lshl_add_u64 v[4:5], v[6:7], 0, s[14:15]
	s_add_i32 m0, s67, 0x1a000
	s_nop 0
	global_load_lds_dwordx4 v[4:5], off
	v_lshl_add_u64 v[4:5], v[10:11], 0, s[14:15]
	s_add_i32 m0, s67, 0x8000
	s_nop 0
	global_load_lds_dwordx4 v[4:5], off
	s_add_i32 m0, s67, 0xa000
	v_lshl_add_u64 v[4:5], v[8:9], 0, s[14:15]
	s_add_u32 s14, s56, 0x40080
	s_addc_u32 s15, s57, 0
	global_load_lds_dwordx4 v[4:5], off
	v_lshl_add_u64 v[4:5], v[0:1], 1, s[14:15]
	s_add_i32 m0, s67, 0x1c000
	s_nop 0
	global_load_lds_dwordx4 v[4:5], off
	v_lshl_add_u64 v[4:5], v[2:3], 1, s[14:15]
	s_add_i32 m0, s67, 0x1e000
	s_nop 0
	global_load_lds_dwordx4 v[4:5], off
	s_waitcnt vmcnt(0)
	s_barrier
	s_branch .LBB0_348

.LBB0_361:
	s_add_u32 s6, s6, 0x40080
	s_addc_u32 s7, s7, 0
	s_add_u32 s1, s56, 0x100
	v_mov_b32_e32 v0, 0
	s_addc_u32 s9, s57, 0
	s_mov_b32 s60, -2
	v_mov_b32_e32 v1, v0
	v_mov_b32_e32 v2, v0
	v_mov_b32_e32 v3, v0
	v_mov_b32_e32 v4, v0
	v_mov_b32_e32 v5, v0
	v_mov_b32_e32 v6, v0
	v_mov_b32_e32 v7, v0
	v_mov_b32_e32 v16, v0
	v_mov_b32_e32 v17, v0
	v_mov_b32_e32 v18, v0
	v_mov_b32_e32 v19, v0
	v_mov_b32_e32 v20, v0
	v_mov_b32_e32 v21, v0
	v_mov_b32_e32 v22, v0
	v_mov_b32_e32 v23, v0
	v_mov_b32_e32 v32, v0
	v_mov_b32_e32 v33, v0
	v_mov_b32_e32 v34, v0
	v_mov_b32_e32 v35, v0
	v_mov_b32_e32 v36, v0
	v_mov_b32_e32 v37, v0
	v_mov_b32_e32 v38, v0
	v_mov_b32_e32 v39, v0
	v_mov_b32_e32 v48, v0
	v_mov_b32_e32 v49, v0
	v_mov_b32_e32 v50, v0
	v_mov_b32_e32 v51, v0
	v_mov_b32_e32 v52, v0
	v_mov_b32_e32 v53, v0
	v_mov_b32_e32 v54, v0
	v_mov_b32_e32 v55, v0
	v_mov_b32_e32 v8, v0
	v_mov_b32_e32 v9, v0
	v_mov_b32_e32 v10, v0
	v_mov_b32_e32 v11, v0
	v_mov_b32_e32 v12, v0
	v_mov_b32_e32 v13, v0
	v_mov_b32_e32 v14, v0
	v_mov_b32_e32 v15, v0
	v_mov_b32_e32 v24, v0
	v_mov_b32_e32 v25, v0
	v_mov_b32_e32 v26, v0
	v_mov_b32_e32 v27, v0
	v_mov_b32_e32 v28, v0
	v_mov_b32_e32 v29, v0
	v_mov_b32_e32 v30, v0
	v_mov_b32_e32 v31, v0
	v_mov_b32_e32 v40, v0
	v_mov_b32_e32 v41, v0
	v_mov_b32_e32 v42, v0
	v_mov_b32_e32 v43, v0
	v_mov_b32_e32 v44, v0
	v_mov_b32_e32 v45, v0
	v_mov_b32_e32 v46, v0
	v_mov_b32_e32 v47, v0
	v_mov_b32_e32 v56, v0
	v_mov_b32_e32 v57, v0
	v_mov_b32_e32 v58, v0
	v_mov_b32_e32 v59, v0
	v_mov_b32_e32 v60, v0
	v_mov_b32_e32 v61, v0
	v_mov_b32_e32 v62, v0
	v_mov_b32_e32 v63, v0
	v_mov_b32_e32 v68, v0
	v_mov_b32_e32 v69, v0
	v_mov_b32_e32 v70, v0
	v_mov_b32_e32 v71, v0
	v_mov_b32_e32 v72, v0
	v_mov_b32_e32 v73, v0
	v_mov_b32_e32 v74, v0
	v_mov_b32_e32 v75, v0
	v_mov_b32_e32 v84, v0
	v_mov_b32_e32 v85, v0
	v_mov_b32_e32 v86, v0
	v_mov_b32_e32 v87, v0
	v_mov_b32_e32 v88, v0
	v_mov_b32_e32 v89, v0
	v_mov_b32_e32 v90, v0
	v_mov_b32_e32 v91, v0
	v_mov_b32_e32 v100, v0
	v_mov_b32_e32 v101, v0
	v_mov_b32_e32 v102, v0
	v_mov_b32_e32 v103, v0
	v_mov_b32_e32 v104, v0
	v_mov_b32_e32 v105, v0
	v_mov_b32_e32 v106, v0
	v_mov_b32_e32 v107, v0
	v_mov_b32_e32 v116, v0
	v_mov_b32_e32 v117, v0
	v_mov_b32_e32 v118, v0
	v_mov_b32_e32 v119, v0
	v_mov_b32_e32 v120, v0
	v_mov_b32_e32 v121, v0
	v_mov_b32_e32 v122, v0
	v_mov_b32_e32 v123, v0
	v_mov_b32_e32 v76, v0
	v_mov_b32_e32 v77, v0
	v_mov_b32_e32 v78, v0
	v_mov_b32_e32 v79, v0
	v_mov_b32_e32 v80, v0
	v_mov_b32_e32 v81, v0
	v_mov_b32_e32 v82, v0
	v_mov_b32_e32 v83, v0
	v_mov_b32_e32 v92, v0
	v_mov_b32_e32 v93, v0
	v_mov_b32_e32 v94, v0
	v_mov_b32_e32 v95, v0
	v_mov_b32_e32 v96, v0
	v_mov_b32_e32 v97, v0
	v_mov_b32_e32 v98, v0
	v_mov_b32_e32 v99, v0
	v_mov_b32_e32 v108, v0
	v_mov_b32_e32 v109, v0
	v_mov_b32_e32 v110, v0
	v_mov_b32_e32 v111, v0
	v_mov_b32_e32 v112, v0
	v_mov_b32_e32 v113, v0
	v_mov_b32_e32 v114, v0
	v_mov_b32_e32 v115, v0
	v_mov_b32_e32 v124, v0
	v_mov_b32_e32 v125, v0
	v_mov_b32_e32 v126, v0
	v_mov_b32_e32 v127, v0
	v_mov_b32_e32 v128, v0
	v_mov_b32_e32 v129, v0
	v_mov_b32_e32 v130, v0
	v_mov_b32_e32 v131, v0
	ds_read_b128 v[64:67], v158
	ds_read_b128 v[132:135], v158 offset:1024
	ds_read_b128 v[136:139], v158 offset:2048
	ds_read_b128 v[140:143], v158 offset:3072
	ds_read_b128 v[152:155], v159
	ds_read_b128 v[168:171], v159 offset:1024
	ds_read_b128 v[172:175], v159 offset:2048
	ds_read_b128 v[176:179], v159 offset:3072
	s_add_u32 s56, s6, 0xfffc0080
	s_addc_u32 s57, s7, -1
	s_cmp_eq_u32 s60, 12
	s_cselect_b32 s59, s53, s57
	s_cselect_b32 s58, s52, s56
	s_cselect_b32 s57, s51, s9
	s_cselect_b32 s56, s50, s1
	s_mov_b32 m0, s81
	v_lshl_add_u64 v[156:157], s[6:7], 0, v[144:145]
	ds_read_b128 v[180:183], v160
	ds_read_b128 v[184:187], v160 offset:1024
	ds_read_b128 v[188:191], v160 offset:2048
	ds_read_b128 v[196:199], v160 offset:3072
	ds_read_b128 v[200:203], v160 offset:4096
	ds_read_b128 v[204:207], v160 offset:5120
	ds_read_b128 v[208:211], v160 offset:6144
	ds_read_b128 v[212:215], v160 offset:7168
	global_load_lds_dwordx4 v[156:157], off
	v_lshl_add_u64 v[156:157], s[6:7], 0, v[146:147]
	s_mov_b32 m0, s82
	s_nop 0
	global_load_lds_dwordx4 v[156:157], off
	s_waitcnt lgkmcnt(0)
	s_barrier
	s_setprio 1
	s_waitcnt lgkmcnt(0)
	v_mfma_f32_16x16x32_bf16 v[128:131], v[64:67], v[180:183], v[128:131]
	v_mfma_f32_16x16x32_bf16 v[124:127], v[136:139], v[180:183], v[124:127]
	v_mfma_f32_16x16x32_bf16 v[112:115], v[64:67], v[188:191], v[112:115]
	v_mfma_f32_16x16x32_bf16 v[108:111], v[136:139], v[188:191], v[108:111]
	v_mfma_f32_16x16x32_bf16 v[96:99], v[64:67], v[200:203], v[96:99]
	v_mfma_f32_16x16x32_bf16 v[92:95], v[136:139], v[200:203], v[92:95]
	v_mfma_f32_16x16x32_bf16 v[80:83], v[64:67], v[208:211], v[80:83]
	v_mfma_f32_16x16x32_bf16 v[76:79], v[136:139], v[208:211], v[76:79]
	v_mfma_f32_16x16x32_bf16 v[128:131], v[132:135], v[184:187], v[128:131]
	v_mfma_f32_16x16x32_bf16 v[124:127], v[140:143], v[184:187], v[124:127]
	v_mfma_f32_16x16x32_bf16 v[112:115], v[132:135], v[196:199], v[112:115]
	v_mfma_f32_16x16x32_bf16 v[108:111], v[140:143], v[196:199], v[108:111]
	v_mfma_f32_16x16x32_bf16 v[96:99], v[132:135], v[204:207], v[96:99]
	v_mfma_f32_16x16x32_bf16 v[92:95], v[140:143], v[204:207], v[92:95]
	v_mfma_f32_16x16x32_bf16 v[80:83], v[132:135], v[212:215], v[80:83]
	v_mfma_f32_16x16x32_bf16 v[76:79], v[140:143], v[212:215], v[76:79]
	s_setprio 0
	s_setprio 1
	v_mfma_f32_16x16x32_bf16 v[120:123], v[152:155], v[180:183], v[120:123]
	v_mfma_f32_16x16x32_bf16 v[116:119], v[172:175], v[180:183], v[116:119]
	v_mfma_f32_16x16x32_bf16 v[104:107], v[152:155], v[188:191], v[104:107]
	v_mfma_f32_16x16x32_bf16 v[100:103], v[172:175], v[188:191], v[100:103]
	v_mfma_f32_16x16x32_bf16 v[88:91], v[152:155], v[200:203], v[88:91]
	v_mfma_f32_16x16x32_bf16 v[84:87], v[172:175], v[200:203], v[84:87]
	v_mfma_f32_16x16x32_bf16 v[72:75], v[152:155], v[208:211], v[72:75]
	v_mfma_f32_16x16x32_bf16 v[68:71], v[172:175], v[208:211], v[68:71]
	v_mfma_f32_16x16x32_bf16 v[120:123], v[168:171], v[184:187], v[120:123]
	v_mfma_f32_16x16x32_bf16 v[116:119], v[176:179], v[184:187], v[116:119]
	v_mfma_f32_16x16x32_bf16 v[104:107], v[168:171], v[196:199], v[104:107]
	v_mfma_f32_16x16x32_bf16 v[100:103], v[176:179], v[196:199], v[100:103]
	v_mfma_f32_16x16x32_bf16 v[88:91], v[168:171], v[204:207], v[88:91]
	v_mfma_f32_16x16x32_bf16 v[84:87], v[176:179], v[204:207], v[84:87]
	v_mfma_f32_16x16x32_bf16 v[72:75], v[168:171], v[212:215], v[72:75]
	v_mfma_f32_16x16x32_bf16 v[68:71], v[176:179], v[212:215], v[68:71]
	s_setprio 0
	s_barrier
	s_mov_b32 m0, s70
	v_lshl_add_u64 v[156:157], s[56:57], 0, v[144:145]
	s_add_u32 s62, s56, 0x40000
	ds_read_b128 v[180:183], v160 offset:16384
	ds_read_b128 v[184:187], v160 offset:17408
	ds_read_b128 v[188:191], v160 offset:18432
	ds_read_b128 v[196:199], v160 offset:19456
	ds_read_b128 v[200:203], v160 offset:20480
	ds_read_b128 v[204:207], v160 offset:21504
	ds_read_b128 v[208:211], v160 offset:22528
	ds_read_b128 v[212:215], v160 offset:23552
	global_load_lds_dwordx4 v[156:157], off
	v_lshl_add_u64 v[192:193], s[56:57], 0, v[146:147]
	s_mov_b32 m0, s71
	s_addc_u32 s63, s57, 0
	global_load_lds_dwordx4 v[192:193], off
	v_lshl_add_u64 v[216:217], s[62:63], 0, v[144:145]
	s_mov_b32 m0, s72
	v_lshl_add_u64 v[218:219], s[58:59], 0, v[146:147]
	global_load_lds_dwordx4 v[216:217], off
	v_lshl_add_u64 v[216:217], s[62:63], 0, v[146:147]
	s_mov_b32 m0, s73
	s_nop 0
	global_load_lds_dwordx4 v[216:217], off
	v_lshl_add_u64 v[216:217], s[58:59], 0, v[144:145]
	s_mov_b32 m0, s67
	s_nop 0
	global_load_lds_dwordx4 v[216:217], off
	s_mov_b32 m0, s83
	s_nop 0
	global_load_lds_dwordx4 v[218:219], off
	s_waitcnt lgkmcnt(0)
	s_barrier
	s_setprio 1
	s_waitcnt lgkmcnt(0)
	v_mfma_f32_16x16x32_bf16 v[60:63], v[64:67], v[180:183], v[60:63]
	v_mfma_f32_16x16x32_bf16 v[56:59], v[136:139], v[180:183], v[56:59]
	v_mfma_f32_16x16x32_bf16 v[44:47], v[64:67], v[188:191], v[44:47]
	v_mfma_f32_16x16x32_bf16 v[40:43], v[136:139], v[188:191], v[40:43]
	v_mfma_f32_16x16x32_bf16 v[28:31], v[64:67], v[200:203], v[28:31]
	v_mfma_f32_16x16x32_bf16 v[24:27], v[136:139], v[200:203], v[24:27]
	v_mfma_f32_16x16x32_bf16 v[12:15], v[64:67], v[208:211], v[12:15]
	v_mfma_f32_16x16x32_bf16 v[8:11], v[136:139], v[208:211], v[8:11]
	v_mfma_f32_16x16x32_bf16 v[60:63], v[132:135], v[184:187], v[60:63]
	v_mfma_f32_16x16x32_bf16 v[56:59], v[140:143], v[184:187], v[56:59]
	v_mfma_f32_16x16x32_bf16 v[44:47], v[132:135], v[196:199], v[44:47]
	v_mfma_f32_16x16x32_bf16 v[40:43], v[140:143], v[196:199], v[40:43]
	v_mfma_f32_16x16x32_bf16 v[28:31], v[132:135], v[204:207], v[28:31]
	v_mfma_f32_16x16x32_bf16 v[24:27], v[140:143], v[204:207], v[24:27]
	v_mfma_f32_16x16x32_bf16 v[12:15], v[132:135], v[212:215], v[12:15]
	v_mfma_f32_16x16x32_bf16 v[8:11], v[140:143], v[212:215], v[8:11]
	s_setprio 0
	s_setprio 1
	v_mfma_f32_16x16x32_bf16 v[52:55], v[152:155], v[180:183], v[52:55]
	v_mfma_f32_16x16x32_bf16 v[48:51], v[172:175], v[180:183], v[48:51]
	v_mfma_f32_16x16x32_bf16 v[36:39], v[152:155], v[188:191], v[36:39]
	v_mfma_f32_16x16x32_bf16 v[32:35], v[172:175], v[188:191], v[32:35]
	v_mfma_f32_16x16x32_bf16 v[20:23], v[152:155], v[200:203], v[20:23]
	v_mfma_f32_16x16x32_bf16 v[16:19], v[172:175], v[200:203], v[16:19]
	v_mfma_f32_16x16x32_bf16 v[4:7], v[152:155], v[208:211], v[4:7]
	v_mfma_f32_16x16x32_bf16 v[0:3], v[172:175], v[208:211], v[0:3]
	v_mfma_f32_16x16x32_bf16 v[52:55], v[168:171], v[184:187], v[52:55]
	v_mfma_f32_16x16x32_bf16 v[48:51], v[176:179], v[184:187], v[48:51]
	v_mfma_f32_16x16x32_bf16 v[36:39], v[168:171], v[196:199], v[36:39]
	v_mfma_f32_16x16x32_bf16 v[32:35], v[176:179], v[196:199], v[32:35]
	v_mfma_f32_16x16x32_bf16 v[20:23], v[168:171], v[204:207], v[20:23]
	v_mfma_f32_16x16x32_bf16 v[16:19], v[176:179], v[204:207], v[16:19]
	v_mfma_f32_16x16x32_bf16 v[4:7], v[168:171], v[212:215], v[4:7]
	v_mfma_f32_16x16x32_bf16 v[0:3], v[176:179], v[212:215], v[0:3]
	s_setprio 0
	s_barrier
	ds_read_b128 v[64:67], v161
	ds_read_b128 v[132:135], v161 offset:1024
	ds_read_b128 v[136:139], v161 offset:2048
	ds_read_b128 v[140:143], v161 offset:3072
	ds_read_b128 v[152:155], v162
	ds_read_b128 v[168:171], v162 offset:1024
	ds_read_b128 v[172:175], v162 offset:2048
	ds_read_b128 v[176:179], v162 offset:3072
	s_add_u32 s58, s58, 0x40000
	s_addc_u32 s59, s59, 0
	s_mov_b32 m0, s84
	v_lshl_add_u64 v[220:221], s[58:59], 0, v[144:145]
	ds_read_b128 v[180:183], v160 offset:32768
	ds_read_b128 v[184:187], v160 offset:33792
	ds_read_b128 v[188:191], v160 offset:34816
	ds_read_b128 v[196:199], v160 offset:35840
	ds_read_b128 v[200:203], v160 offset:36864
	ds_read_b128 v[204:207], v160 offset:37888
	ds_read_b128 v[208:211], v160 offset:38912
	ds_read_b128 v[212:215], v160 offset:39936
	global_load_lds_dwordx4 v[220:221], off
	v_lshl_add_u64 v[220:221], s[58:59], 0, v[146:147]
	s_mov_b32 m0, s85
	s_nop 0
	global_load_lds_dwordx4 v[220:221], off
	s_waitcnt vmcnt(8)
	s_waitcnt lgkmcnt(0)
	s_barrier
	s_setprio 1
	s_waitcnt lgkmcnt(0)
	v_mfma_f32_16x16x32_bf16 v[128:131], v[64:67], v[180:183], v[128:131]
	v_mfma_f32_16x16x32_bf16 v[124:127], v[136:139], v[180:183], v[124:127]
	v_mfma_f32_16x16x32_bf16 v[112:115], v[64:67], v[188:191], v[112:115]
	v_mfma_f32_16x16x32_bf16 v[108:111], v[136:139], v[188:191], v[108:111]
	v_mfma_f32_16x16x32_bf16 v[96:99], v[64:67], v[200:203], v[96:99]
	v_mfma_f32_16x16x32_bf16 v[92:95], v[136:139], v[200:203], v[92:95]
	v_mfma_f32_16x16x32_bf16 v[80:83], v[64:67], v[208:211], v[80:83]
	v_mfma_f32_16x16x32_bf16 v[76:79], v[136:139], v[208:211], v[76:79]
	v_mfma_f32_16x16x32_bf16 v[128:131], v[132:135], v[184:187], v[128:131]
	v_mfma_f32_16x16x32_bf16 v[124:127], v[140:143], v[184:187], v[124:127]
	v_mfma_f32_16x16x32_bf16 v[112:115], v[132:135], v[196:199], v[112:115]
	v_mfma_f32_16x16x32_bf16 v[108:111], v[140:143], v[196:199], v[108:111]
	v_mfma_f32_16x16x32_bf16 v[96:99], v[132:135], v[204:207], v[96:99]
	v_mfma_f32_16x16x32_bf16 v[92:95], v[140:143], v[204:207], v[92:95]
	v_mfma_f32_16x16x32_bf16 v[80:83], v[132:135], v[212:215], v[80:83]
	v_mfma_f32_16x16x32_bf16 v[76:79], v[140:143], v[212:215], v[76:79]
	s_setprio 0
	s_setprio 1
	v_mfma_f32_16x16x32_bf16 v[120:123], v[152:155], v[180:183], v[120:123]
	v_mfma_f32_16x16x32_bf16 v[116:119], v[172:175], v[180:183], v[116:119]
	v_mfma_f32_16x16x32_bf16 v[104:107], v[152:155], v[188:191], v[104:107]
	v_mfma_f32_16x16x32_bf16 v[100:103], v[172:175], v[188:191], v[100:103]
	v_mfma_f32_16x16x32_bf16 v[88:91], v[152:155], v[200:203], v[88:91]
	v_mfma_f32_16x16x32_bf16 v[84:87], v[172:175], v[200:203], v[84:87]
	v_mfma_f32_16x16x32_bf16 v[72:75], v[152:155], v[208:211], v[72:75]
	v_mfma_f32_16x16x32_bf16 v[68:71], v[172:175], v[208:211], v[68:71]
	v_mfma_f32_16x16x32_bf16 v[120:123], v[168:171], v[184:187], v[120:123]
	v_mfma_f32_16x16x32_bf16 v[116:119], v[176:179], v[184:187], v[116:119]
	v_mfma_f32_16x16x32_bf16 v[104:107], v[168:171], v[196:199], v[104:107]
	v_mfma_f32_16x16x32_bf16 v[100:103], v[176:179], v[196:199], v[100:103]
	v_mfma_f32_16x16x32_bf16 v[88:91], v[168:171], v[204:207], v[88:91]
	v_mfma_f32_16x16x32_bf16 v[84:87], v[176:179], v[204:207], v[84:87]
	v_mfma_f32_16x16x32_bf16 v[72:75], v[168:171], v[212:215], v[72:75]
	v_mfma_f32_16x16x32_bf16 v[68:71], v[176:179], v[212:215], v[68:71]
	s_setprio 0
	s_barrier
	s_mov_b32 m0, s74
	v_lshl_add_u64 v[156:157], v[156:157], 0, s[48:49]
	s_add_u32 s56, s56, 0x40080
	ds_read_b128 v[180:183], v160 offset:49152
	ds_read_b128 v[184:187], v160 offset:50176
	ds_read_b128 v[188:191], v160 offset:51200
	ds_read_b128 v[196:199], v160 offset:52224
	ds_read_b128 v[200:203], v160 offset:53248
	ds_read_b128 v[204:207], v160 offset:54272
	ds_read_b128 v[208:211], v160 offset:55296
	ds_read_b128 v[212:215], v160 offset:56320
	global_load_lds_dwordx4 v[156:157], off
	v_lshl_add_u64 v[156:157], v[192:193], 0, s[48:49]
	s_mov_b32 m0, s75
	s_addc_u32 s57, s57, 0
	global_load_lds_dwordx4 v[156:157], off
	v_lshl_add_u64 v[156:157], s[56:57], 0, v[144:145]
	s_mov_b32 m0, s76
	s_nop 0
	global_load_lds_dwordx4 v[156:157], off
	v_lshl_add_u64 v[156:157], s[56:57], 0, v[146:147]
	s_mov_b32 m0, s77
	s_nop 0
	global_load_lds_dwordx4 v[156:157], off
	v_lshl_add_u64 v[156:157], v[216:217], 0, s[48:49]
	s_mov_b32 m0, s86
	s_nop 0
	global_load_lds_dwordx4 v[156:157], off
	v_lshl_add_u64 v[156:157], v[218:219], 0, s[48:49]
	s_mov_b32 m0, s87
	s_nop 0
	global_load_lds_dwordx4 v[156:157], off
	s_waitcnt vmcnt(8)
	s_waitcnt lgkmcnt(0)
	s_barrier
	s_setprio 1
	s_waitcnt lgkmcnt(0)
	v_mfma_f32_16x16x32_bf16 v[60:63], v[64:67], v[180:183], v[60:63]
	v_mfma_f32_16x16x32_bf16 v[56:59], v[136:139], v[180:183], v[56:59]
	v_mfma_f32_16x16x32_bf16 v[44:47], v[64:67], v[188:191], v[44:47]
	v_mfma_f32_16x16x32_bf16 v[40:43], v[136:139], v[188:191], v[40:43]
	v_mfma_f32_16x16x32_bf16 v[28:31], v[64:67], v[200:203], v[28:31]
	v_mfma_f32_16x16x32_bf16 v[24:27], v[136:139], v[200:203], v[24:27]
	v_mfma_f32_16x16x32_bf16 v[12:15], v[64:67], v[208:211], v[12:15]
	v_mfma_f32_16x16x32_bf16 v[8:11], v[136:139], v[208:211], v[8:11]
	v_mfma_f32_16x16x32_bf16 v[60:63], v[132:135], v[184:187], v[60:63]
	v_mfma_f32_16x16x32_bf16 v[56:59], v[140:143], v[184:187], v[56:59]
	v_mfma_f32_16x16x32_bf16 v[44:47], v[132:135], v[196:199], v[44:47]
	v_mfma_f32_16x16x32_bf16 v[40:43], v[140:143], v[196:199], v[40:43]
	v_mfma_f32_16x16x32_bf16 v[28:31], v[132:135], v[204:207], v[28:31]
	v_mfma_f32_16x16x32_bf16 v[24:27], v[140:143], v[204:207], v[24:27]
	v_mfma_f32_16x16x32_bf16 v[12:15], v[132:135], v[212:215], v[12:15]
	v_mfma_f32_16x16x32_bf16 v[8:11], v[140:143], v[212:215], v[8:11]
	s_setprio 0
	s_setprio 1
	v_mfma_f32_16x16x32_bf16 v[52:55], v[152:155], v[180:183], v[52:55]
	v_mfma_f32_16x16x32_bf16 v[48:51], v[172:175], v[180:183], v[48:51]
	v_mfma_f32_16x16x32_bf16 v[36:39], v[152:155], v[188:191], v[36:39]
	v_mfma_f32_16x16x32_bf16 v[32:35], v[172:175], v[188:191], v[32:35]
	v_mfma_f32_16x16x32_bf16 v[20:23], v[152:155], v[200:203], v[20:23]
	v_mfma_f32_16x16x32_bf16 v[16:19], v[172:175], v[200:203], v[16:19]
	v_mfma_f32_16x16x32_bf16 v[4:7], v[152:155], v[208:211], v[4:7]
	v_mfma_f32_16x16x32_bf16 v[0:3], v[172:175], v[208:211], v[0:3]
	v_mfma_f32_16x16x32_bf16 v[52:55], v[168:171], v[184:187], v[52:55]
	v_mfma_f32_16x16x32_bf16 v[48:51], v[176:179], v[184:187], v[48:51]
	v_mfma_f32_16x16x32_bf16 v[36:39], v[168:171], v[196:199], v[36:39]
	v_mfma_f32_16x16x32_bf16 v[32:35], v[176:179], v[196:199], v[32:35]
	v_mfma_f32_16x16x32_bf16 v[20:23], v[168:171], v[204:207], v[20:23]
	v_mfma_f32_16x16x32_bf16 v[16:19], v[176:179], v[204:207], v[16:19]
	v_mfma_f32_16x16x32_bf16 v[4:7], v[168:171], v[212:215], v[4:7]
	v_mfma_f32_16x16x32_bf16 v[0:3], v[176:179], v[212:215], v[0:3]
	s_setprio 0
	s_barrier
	s_add_i32 s60, s60, 2
	s_add_u32 s6, s6, 0x100
	s_addc_u32 s7, s7, 0
	s_add_u32 s1, s1, 0x100
	s_addc_u32 s9, s9, 0
	s_cmp_gt_u32 s60, 13

.LBB0_412:
	s_mov_b64 s[0:1], 0x80
	v_lshl_add_u64 v[4:5], v[4:5], 0, s[0:1]
	s_add_i32 m0, s18, 0x18000
	s_waitcnt vmcnt(2)
	s_barrier
	global_load_lds_dwordx4 v[4:5], off
	v_lshl_add_u64 v[4:5], v[6:7], 0, s[0:1]
	s_add_i32 m0, s18, 0x1a000
	s_nop 0
	global_load_lds_dwordx4 v[4:5], off
	v_lshl_add_u64 v[4:5], v[10:11], 0, s[0:1]
	s_add_i32 m0, s18, 0x8000
	s_nop 0
	global_load_lds_dwordx4 v[4:5], off
	s_add_i32 m0, s18, 0xa000
	v_lshl_add_u64 v[4:5], v[8:9], 0, s[0:1]
	s_add_u32 s0, s48, 0x40080
	s_addc_u32 s1, s49, 0
	global_load_lds_dwordx4 v[4:5], off
	v_lshl_add_u64 v[4:5], v[0:1], 1, s[0:1]
	s_add_i32 m0, s18, 0x1c000
	s_nop 0
	global_load_lds_dwordx4 v[4:5], off
	v_lshl_add_u64 v[4:5], v[2:3], 1, s[0:1]
	s_add_i32 m0, s18, 0x1e000
	s_nop 0
	global_load_lds_dwordx4 v[4:5], off
	s_waitcnt vmcnt(0)
	s_barrier
	s_branch .LBB0_418

.LBB0_431:
	s_add_u32 s46, s46, 0x40080
	s_addc_u32 s47, s47, 0
	s_add_u32 s23, s48, 0x100
	v_mov_b32_e32 v0, 0
	s_addc_u32 s52, s49, 0
	s_mov_b32 s53, -2
	v_mov_b32_e32 v1, v0
	v_mov_b32_e32 v2, v0
	v_mov_b32_e32 v3, v0
	v_mov_b32_e32 v4, v0
	v_mov_b32_e32 v5, v0
	v_mov_b32_e32 v6, v0
	v_mov_b32_e32 v7, v0
	v_mov_b32_e32 v16, v0
	v_mov_b32_e32 v17, v0
	v_mov_b32_e32 v18, v0
	v_mov_b32_e32 v19, v0
	v_mov_b32_e32 v20, v0
	v_mov_b32_e32 v21, v0
	v_mov_b32_e32 v22, v0
	v_mov_b32_e32 v23, v0
	v_mov_b32_e32 v32, v0
	v_mov_b32_e32 v33, v0
	v_mov_b32_e32 v34, v0
	v_mov_b32_e32 v35, v0
	v_mov_b32_e32 v36, v0
	v_mov_b32_e32 v37, v0
	v_mov_b32_e32 v38, v0
	v_mov_b32_e32 v39, v0
	v_mov_b32_e32 v48, v0
	v_mov_b32_e32 v49, v0
	v_mov_b32_e32 v50, v0
	v_mov_b32_e32 v51, v0
	v_mov_b32_e32 v52, v0
	v_mov_b32_e32 v53, v0
	v_mov_b32_e32 v54, v0
	v_mov_b32_e32 v55, v0
	v_mov_b32_e32 v8, v0
	v_mov_b32_e32 v9, v0
	v_mov_b32_e32 v10, v0
	v_mov_b32_e32 v11, v0
	v_mov_b32_e32 v12, v0
	v_mov_b32_e32 v13, v0
	v_mov_b32_e32 v14, v0
	v_mov_b32_e32 v15, v0
	v_mov_b32_e32 v24, v0
	v_mov_b32_e32 v25, v0
	v_mov_b32_e32 v26, v0
	v_mov_b32_e32 v27, v0
	v_mov_b32_e32 v28, v0
	v_mov_b32_e32 v29, v0
	v_mov_b32_e32 v30, v0
	v_mov_b32_e32 v31, v0
	v_mov_b32_e32 v40, v0
	v_mov_b32_e32 v41, v0
	v_mov_b32_e32 v42, v0
	v_mov_b32_e32 v43, v0
	v_mov_b32_e32 v44, v0
	v_mov_b32_e32 v45, v0
	v_mov_b32_e32 v46, v0
	v_mov_b32_e32 v47, v0
	v_mov_b32_e32 v56, v0
	v_mov_b32_e32 v57, v0
	v_mov_b32_e32 v58, v0
	v_mov_b32_e32 v59, v0
	v_mov_b32_e32 v60, v0
	v_mov_b32_e32 v61, v0
	v_mov_b32_e32 v62, v0
	v_mov_b32_e32 v63, v0
	v_mov_b32_e32 v64, v0
	v_mov_b32_e32 v65, v0
	v_mov_b32_e32 v66, v0
	v_mov_b32_e32 v67, v0
	v_mov_b32_e32 v68, v0
	v_mov_b32_e32 v69, v0
	v_mov_b32_e32 v70, v0
	v_mov_b32_e32 v71, v0
	v_mov_b32_e32 v80, v0
	v_mov_b32_e32 v81, v0
	v_mov_b32_e32 v82, v0
	v_mov_b32_e32 v83, v0
	v_mov_b32_e32 v84, v0
	v_mov_b32_e32 v85, v0
	v_mov_b32_e32 v86, v0
	v_mov_b32_e32 v87, v0
	v_mov_b32_e32 v96, v0
	v_mov_b32_e32 v97, v0
	v_mov_b32_e32 v98, v0
	v_mov_b32_e32 v99, v0
	v_mov_b32_e32 v100, v0
	v_mov_b32_e32 v101, v0
	v_mov_b32_e32 v102, v0
	v_mov_b32_e32 v103, v0
	v_mov_b32_e32 v120, v0
	v_mov_b32_e32 v121, v0
	v_mov_b32_e32 v122, v0
	v_mov_b32_e32 v123, v0
	v_mov_b32_e32 v136, v0
	v_mov_b32_e32 v137, v0
	v_mov_b32_e32 v138, v0
	v_mov_b32_e32 v139, v0
	v_mov_b32_e32 v72, v0
	v_mov_b32_e32 v73, v0
	v_mov_b32_e32 v74, v0
	v_mov_b32_e32 v75, v0
	v_mov_b32_e32 v76, v0
	v_mov_b32_e32 v77, v0
	v_mov_b32_e32 v78, v0
	v_mov_b32_e32 v79, v0
	v_mov_b32_e32 v88, v0
	v_mov_b32_e32 v89, v0
	v_mov_b32_e32 v90, v0
	v_mov_b32_e32 v91, v0
	v_mov_b32_e32 v92, v0
	v_mov_b32_e32 v93, v0
	v_mov_b32_e32 v94, v0
	v_mov_b32_e32 v95, v0
	v_mov_b32_e32 v104, v0
	v_mov_b32_e32 v105, v0
	v_mov_b32_e32 v106, v0
	v_mov_b32_e32 v107, v0
	v_mov_b32_e32 v108, v0
	v_mov_b32_e32 v109, v0
	v_mov_b32_e32 v110, v0
	v_mov_b32_e32 v111, v0
	v_mov_b32_e32 v140, v0
	v_mov_b32_e32 v141, v0
	v_mov_b32_e32 v142, v0
	v_mov_b32_e32 v143, v0
	v_mov_b32_e32 v144, v0
	v_mov_b32_e32 v145, v0
	v_mov_b32_e32 v146, v0
	v_mov_b32_e32 v147, v0
	ds_read_b128 v[112:115], v160
	ds_read_b128 v[116:119], v160 offset:1024
	ds_read_b128 v[124:127], v160 offset:2048
	ds_read_b128 v[128:131], v160 offset:3072
	ds_read_b128 v[132:135], v161
	ds_read_b128 v[148:151], v161 offset:1024
	ds_read_b128 v[168:171], v161 offset:2048
	ds_read_b128 v[172:175], v161 offset:3072
	s_add_u32 s48, s46, 0xfffc0080
	s_addc_u32 s49, s47, -1
	s_cmp_eq_u32 s53, 12
	s_cselect_b32 s51, s17, s49
	s_cselect_b32 s50, s16, s48
	s_cselect_b32 s49, s15, s52
	s_cselect_b32 s48, s14, s23
	s_mov_b32 m0, s69
	v_lshl_add_u64 v[192:193], s[46:47], 0, v[152:153]
	ds_read_b128 v[176:179], v162
	ds_read_b128 v[180:183], v162 offset:1024
	ds_read_b128 v[184:187], v162 offset:2048
	ds_read_b128 v[188:191], v162 offset:3072
	ds_read_b128 v[196:199], v162 offset:4096
	ds_read_b128 v[200:203], v162 offset:5120
	ds_read_b128 v[204:207], v162 offset:6144
	ds_read_b128 v[208:211], v162 offset:7168
	global_load_lds_dwordx4 v[192:193], off
	v_lshl_add_u64 v[192:193], s[46:47], 0, v[154:155]
	s_mov_b32 m0, s70
	s_nop 0
	global_load_lds_dwordx4 v[192:193], off
	s_waitcnt lgkmcnt(0)
	s_barrier
	s_setprio 1
	s_waitcnt lgkmcnt(0)
	v_mfma_f32_16x16x32_bf16 v[144:147], v[112:115], v[176:179], v[144:147]
	v_mfma_f32_16x16x32_bf16 v[140:143], v[124:127], v[176:179], v[140:143]
	v_mfma_f32_16x16x32_bf16 v[108:111], v[112:115], v[184:187], v[108:111]
	v_mfma_f32_16x16x32_bf16 v[104:107], v[124:127], v[184:187], v[104:107]
	v_mfma_f32_16x16x32_bf16 v[92:95], v[112:115], v[196:199], v[92:95]
	v_mfma_f32_16x16x32_bf16 v[88:91], v[124:127], v[196:199], v[88:91]
	v_mfma_f32_16x16x32_bf16 v[76:79], v[112:115], v[204:207], v[76:79]
	v_mfma_f32_16x16x32_bf16 v[72:75], v[124:127], v[204:207], v[72:75]
	v_mfma_f32_16x16x32_bf16 v[144:147], v[116:119], v[180:183], v[144:147]
	v_mfma_f32_16x16x32_bf16 v[140:143], v[128:131], v[180:183], v[140:143]
	v_mfma_f32_16x16x32_bf16 v[108:111], v[116:119], v[188:191], v[108:111]
	v_mfma_f32_16x16x32_bf16 v[104:107], v[128:131], v[188:191], v[104:107]
	v_mfma_f32_16x16x32_bf16 v[92:95], v[116:119], v[200:203], v[92:95]
	v_mfma_f32_16x16x32_bf16 v[88:91], v[128:131], v[200:203], v[88:91]
	v_mfma_f32_16x16x32_bf16 v[76:79], v[116:119], v[208:211], v[76:79]
	v_mfma_f32_16x16x32_bf16 v[72:75], v[128:131], v[208:211], v[72:75]
	s_setprio 0
	s_setprio 1
	v_mfma_f32_16x16x32_bf16 v[136:139], v[132:135], v[176:179], v[136:139]
	v_mfma_f32_16x16x32_bf16 v[120:123], v[168:171], v[176:179], v[120:123]
	v_mfma_f32_16x16x32_bf16 v[100:103], v[132:135], v[184:187], v[100:103]
	v_mfma_f32_16x16x32_bf16 v[96:99], v[168:171], v[184:187], v[96:99]
	v_mfma_f32_16x16x32_bf16 v[84:87], v[132:135], v[196:199], v[84:87]
	v_mfma_f32_16x16x32_bf16 v[80:83], v[168:171], v[196:199], v[80:83]
	v_mfma_f32_16x16x32_bf16 v[68:71], v[132:135], v[204:207], v[68:71]
	v_mfma_f32_16x16x32_bf16 v[64:67], v[168:171], v[204:207], v[64:67]
	v_mfma_f32_16x16x32_bf16 v[136:139], v[148:151], v[180:183], v[136:139]
	v_mfma_f32_16x16x32_bf16 v[120:123], v[172:175], v[180:183], v[120:123]
	v_mfma_f32_16x16x32_bf16 v[100:103], v[148:151], v[188:191], v[100:103]
	v_mfma_f32_16x16x32_bf16 v[96:99], v[172:175], v[188:191], v[96:99]
	v_mfma_f32_16x16x32_bf16 v[84:87], v[148:151], v[200:203], v[84:87]
	v_mfma_f32_16x16x32_bf16 v[80:83], v[172:175], v[200:203], v[80:83]
	v_mfma_f32_16x16x32_bf16 v[68:71], v[148:151], v[208:211], v[68:71]
	v_mfma_f32_16x16x32_bf16 v[64:67], v[172:175], v[208:211], v[64:67]
	s_setprio 0
	s_barrier
	s_mov_b32 m0, s56
	v_lshl_add_u64 v[192:193], s[48:49], 0, v[152:153]
	s_add_u32 s54, s48, 0x40000
	ds_read_b128 v[176:179], v162 offset:16384
	ds_read_b128 v[180:183], v162 offset:17408
	ds_read_b128 v[184:187], v162 offset:18432
	ds_read_b128 v[188:191], v162 offset:19456
	ds_read_b128 v[196:199], v162 offset:20480
	ds_read_b128 v[200:203], v162 offset:21504
	ds_read_b128 v[204:207], v162 offset:22528
	ds_read_b128 v[208:211], v162 offset:23552
	global_load_lds_dwordx4 v[192:193], off
	v_lshl_add_u64 v[212:213], s[48:49], 0, v[154:155]
	s_mov_b32 m0, s57
	s_addc_u32 s55, s49, 0
	global_load_lds_dwordx4 v[212:213], off
	v_lshl_add_u64 v[214:215], s[54:55], 0, v[152:153]
	s_mov_b32 m0, s58
	v_lshl_add_u64 v[216:217], s[50:51], 0, v[154:155]
	global_load_lds_dwordx4 v[214:215], off
	v_lshl_add_u64 v[214:215], s[54:55], 0, v[154:155]
	s_mov_b32 m0, s59
	s_nop 0
	global_load_lds_dwordx4 v[214:215], off
	v_lshl_add_u64 v[214:215], s[50:51], 0, v[152:153]
	s_mov_b32 m0, s18
	s_nop 0
	global_load_lds_dwordx4 v[214:215], off
	s_mov_b32 m0, s71
	s_nop 0
	global_load_lds_dwordx4 v[216:217], off
	s_waitcnt lgkmcnt(0)
	s_barrier
	s_setprio 1
	s_waitcnt lgkmcnt(0)
	v_mfma_f32_16x16x32_bf16 v[60:63], v[112:115], v[176:179], v[60:63]
	v_mfma_f32_16x16x32_bf16 v[56:59], v[124:127], v[176:179], v[56:59]
	v_mfma_f32_16x16x32_bf16 v[44:47], v[112:115], v[184:187], v[44:47]
	v_mfma_f32_16x16x32_bf16 v[40:43], v[124:127], v[184:187], v[40:43]
	v_mfma_f32_16x16x32_bf16 v[28:31], v[112:115], v[196:199], v[28:31]
	v_mfma_f32_16x16x32_bf16 v[24:27], v[124:127], v[196:199], v[24:27]
	v_mfma_f32_16x16x32_bf16 v[12:15], v[112:115], v[204:207], v[12:15]
	v_mfma_f32_16x16x32_bf16 v[8:11], v[124:127], v[204:207], v[8:11]
	v_mfma_f32_16x16x32_bf16 v[60:63], v[116:119], v[180:183], v[60:63]
	v_mfma_f32_16x16x32_bf16 v[56:59], v[128:131], v[180:183], v[56:59]
	v_mfma_f32_16x16x32_bf16 v[44:47], v[116:119], v[188:191], v[44:47]
	v_mfma_f32_16x16x32_bf16 v[40:43], v[128:131], v[188:191], v[40:43]
	v_mfma_f32_16x16x32_bf16 v[28:31], v[116:119], v[200:203], v[28:31]
	v_mfma_f32_16x16x32_bf16 v[24:27], v[128:131], v[200:203], v[24:27]
	v_mfma_f32_16x16x32_bf16 v[12:15], v[116:119], v[208:211], v[12:15]
	v_mfma_f32_16x16x32_bf16 v[8:11], v[128:131], v[208:211], v[8:11]
	s_setprio 0
	s_setprio 1
	v_mfma_f32_16x16x32_bf16 v[52:55], v[132:135], v[176:179], v[52:55]
	v_mfma_f32_16x16x32_bf16 v[48:51], v[168:171], v[176:179], v[48:51]
	v_mfma_f32_16x16x32_bf16 v[36:39], v[132:135], v[184:187], v[36:39]
	v_mfma_f32_16x16x32_bf16 v[32:35], v[168:171], v[184:187], v[32:35]
	v_mfma_f32_16x16x32_bf16 v[20:23], v[132:135], v[196:199], v[20:23]
	v_mfma_f32_16x16x32_bf16 v[16:19], v[168:171], v[196:199], v[16:19]
	v_mfma_f32_16x16x32_bf16 v[4:7], v[132:135], v[204:207], v[4:7]
	v_mfma_f32_16x16x32_bf16 v[0:3], v[168:171], v[204:207], v[0:3]
	v_mfma_f32_16x16x32_bf16 v[52:55], v[148:151], v[180:183], v[52:55]
	v_mfma_f32_16x16x32_bf16 v[48:51], v[172:175], v[180:183], v[48:51]
	v_mfma_f32_16x16x32_bf16 v[36:39], v[148:151], v[188:191], v[36:39]
	v_mfma_f32_16x16x32_bf16 v[32:35], v[172:175], v[188:191], v[32:35]
	v_mfma_f32_16x16x32_bf16 v[20:23], v[148:151], v[200:203], v[20:23]
	v_mfma_f32_16x16x32_bf16 v[16:19], v[172:175], v[200:203], v[16:19]
	v_mfma_f32_16x16x32_bf16 v[4:7], v[148:151], v[208:211], v[4:7]
	v_mfma_f32_16x16x32_bf16 v[0:3], v[172:175], v[208:211], v[0:3]
	s_setprio 0
	s_barrier
	ds_read_b128 v[112:115], v163
	ds_read_b128 v[116:119], v163 offset:1024
	ds_read_b128 v[124:127], v163 offset:2048
	ds_read_b128 v[128:131], v163 offset:3072
	ds_read_b128 v[132:135], v164
	ds_read_b128 v[148:151], v164 offset:1024
	ds_read_b128 v[168:171], v164 offset:2048
	ds_read_b128 v[172:175], v164 offset:3072
	s_add_u32 s50, s50, 0x40000
	s_addc_u32 s51, s51, 0
	s_mov_b32 m0, s72
	v_lshl_add_u64 v[218:219], s[50:51], 0, v[152:153]
	ds_read_b128 v[176:179], v162 offset:32768
	ds_read_b128 v[180:183], v162 offset:33792
	ds_read_b128 v[184:187], v162 offset:34816
	ds_read_b128 v[188:191], v162 offset:35840
	ds_read_b128 v[196:199], v162 offset:36864
	ds_read_b128 v[200:203], v162 offset:37888
	ds_read_b128 v[204:207], v162 offset:38912
	ds_read_b128 v[208:211], v162 offset:39936
	global_load_lds_dwordx4 v[218:219], off
	v_lshl_add_u64 v[218:219], s[50:51], 0, v[154:155]
	s_mov_b32 m0, s73
	s_nop 0
	global_load_lds_dwordx4 v[218:219], off
	s_waitcnt vmcnt(8)
	s_waitcnt lgkmcnt(0)
	s_barrier
	s_setprio 1
	s_waitcnt lgkmcnt(0)
	v_mfma_f32_16x16x32_bf16 v[144:147], v[112:115], v[176:179], v[144:147]
	v_mfma_f32_16x16x32_bf16 v[140:143], v[124:127], v[176:179], v[140:143]
	v_mfma_f32_16x16x32_bf16 v[108:111], v[112:115], v[184:187], v[108:111]
	v_mfma_f32_16x16x32_bf16 v[104:107], v[124:127], v[184:187], v[104:107]
	v_mfma_f32_16x16x32_bf16 v[92:95], v[112:115], v[196:199], v[92:95]
	v_mfma_f32_16x16x32_bf16 v[88:91], v[124:127], v[196:199], v[88:91]
	v_mfma_f32_16x16x32_bf16 v[76:79], v[112:115], v[204:207], v[76:79]
	v_mfma_f32_16x16x32_bf16 v[72:75], v[124:127], v[204:207], v[72:75]
	v_mfma_f32_16x16x32_bf16 v[144:147], v[116:119], v[180:183], v[144:147]
	v_mfma_f32_16x16x32_bf16 v[140:143], v[128:131], v[180:183], v[140:143]
	v_mfma_f32_16x16x32_bf16 v[108:111], v[116:119], v[188:191], v[108:111]
	v_mfma_f32_16x16x32_bf16 v[104:107], v[128:131], v[188:191], v[104:107]
	v_mfma_f32_16x16x32_bf16 v[92:95], v[116:119], v[200:203], v[92:95]
	v_mfma_f32_16x16x32_bf16 v[88:91], v[128:131], v[200:203], v[88:91]
	v_mfma_f32_16x16x32_bf16 v[76:79], v[116:119], v[208:211], v[76:79]
	v_mfma_f32_16x16x32_bf16 v[72:75], v[128:131], v[208:211], v[72:75]
	s_setprio 0
	s_setprio 1
	v_mfma_f32_16x16x32_bf16 v[136:139], v[132:135], v[176:179], v[136:139]
	v_mfma_f32_16x16x32_bf16 v[120:123], v[168:171], v[176:179], v[120:123]
	v_mfma_f32_16x16x32_bf16 v[100:103], v[132:135], v[184:187], v[100:103]
	v_mfma_f32_16x16x32_bf16 v[96:99], v[168:171], v[184:187], v[96:99]
	v_mfma_f32_16x16x32_bf16 v[84:87], v[132:135], v[196:199], v[84:87]
	v_mfma_f32_16x16x32_bf16 v[80:83], v[168:171], v[196:199], v[80:83]
	v_mfma_f32_16x16x32_bf16 v[68:71], v[132:135], v[204:207], v[68:71]
	v_mfma_f32_16x16x32_bf16 v[64:67], v[168:171], v[204:207], v[64:67]
	v_mfma_f32_16x16x32_bf16 v[136:139], v[148:151], v[180:183], v[136:139]
	v_mfma_f32_16x16x32_bf16 v[120:123], v[172:175], v[180:183], v[120:123]
	v_mfma_f32_16x16x32_bf16 v[100:103], v[148:151], v[188:191], v[100:103]
	v_mfma_f32_16x16x32_bf16 v[96:99], v[172:175], v[188:191], v[96:99]
	v_mfma_f32_16x16x32_bf16 v[84:87], v[148:151], v[200:203], v[84:87]
	v_mfma_f32_16x16x32_bf16 v[80:83], v[172:175], v[200:203], v[80:83]
	v_mfma_f32_16x16x32_bf16 v[68:71], v[148:151], v[208:211], v[68:71]
	v_mfma_f32_16x16x32_bf16 v[64:67], v[172:175], v[208:211], v[64:67]
	s_setprio 0
	s_barrier
	s_mov_b32 m0, s60
	v_lshl_add_u64 v[192:193], v[192:193], 0, s[10:11]
	s_add_u32 s48, s48, 0x40080
	ds_read_b128 v[176:179], v162 offset:49152
	ds_read_b128 v[180:183], v162 offset:50176
	ds_read_b128 v[184:187], v162 offset:51200
	ds_read_b128 v[188:191], v162 offset:52224
	ds_read_b128 v[196:199], v162 offset:53248
	ds_read_b128 v[200:203], v162 offset:54272
	ds_read_b128 v[204:207], v162 offset:55296
	ds_read_b128 v[208:211], v162 offset:56320
	global_load_lds_dwordx4 v[192:193], off
	v_lshl_add_u64 v[192:193], v[212:213], 0, s[10:11]
	s_mov_b32 m0, s61
	s_addc_u32 s49, s49, 0
	global_load_lds_dwordx4 v[192:193], off
	v_lshl_add_u64 v[192:193], s[48:49], 0, v[152:153]
	s_mov_b32 m0, s62
	s_nop 0
	global_load_lds_dwordx4 v[192:193], off
	v_lshl_add_u64 v[192:193], s[48:49], 0, v[154:155]
	s_mov_b32 m0, s63
	s_nop 0
	global_load_lds_dwordx4 v[192:193], off
	v_lshl_add_u64 v[192:193], v[214:215], 0, s[10:11]
	s_mov_b32 m0, s74
	s_nop 0
	global_load_lds_dwordx4 v[192:193], off
	v_lshl_add_u64 v[192:193], v[216:217], 0, s[10:11]
	s_mov_b32 m0, s75
	s_nop 0
	global_load_lds_dwordx4 v[192:193], off
	s_waitcnt vmcnt(8)
	s_waitcnt lgkmcnt(0)
	s_barrier
	s_setprio 1
	s_waitcnt lgkmcnt(0)
	v_mfma_f32_16x16x32_bf16 v[60:63], v[112:115], v[176:179], v[60:63]
	v_mfma_f32_16x16x32_bf16 v[56:59], v[124:127], v[176:179], v[56:59]
	v_mfma_f32_16x16x32_bf16 v[44:47], v[112:115], v[184:187], v[44:47]
	v_mfma_f32_16x16x32_bf16 v[40:43], v[124:127], v[184:187], v[40:43]
	v_mfma_f32_16x16x32_bf16 v[28:31], v[112:115], v[196:199], v[28:31]
	v_mfma_f32_16x16x32_bf16 v[24:27], v[124:127], v[196:199], v[24:27]
	v_mfma_f32_16x16x32_bf16 v[12:15], v[112:115], v[204:207], v[12:15]
	v_mfma_f32_16x16x32_bf16 v[8:11], v[124:127], v[204:207], v[8:11]
	v_mfma_f32_16x16x32_bf16 v[60:63], v[116:119], v[180:183], v[60:63]
	v_mfma_f32_16x16x32_bf16 v[56:59], v[128:131], v[180:183], v[56:59]
	v_mfma_f32_16x16x32_bf16 v[44:47], v[116:119], v[188:191], v[44:47]
	v_mfma_f32_16x16x32_bf16 v[40:43], v[128:131], v[188:191], v[40:43]
	v_mfma_f32_16x16x32_bf16 v[28:31], v[116:119], v[200:203], v[28:31]
	v_mfma_f32_16x16x32_bf16 v[24:27], v[128:131], v[200:203], v[24:27]
	v_mfma_f32_16x16x32_bf16 v[12:15], v[116:119], v[208:211], v[12:15]
	v_mfma_f32_16x16x32_bf16 v[8:11], v[128:131], v[208:211], v[8:11]
	s_setprio 0
	s_setprio 1
	v_mfma_f32_16x16x32_bf16 v[52:55], v[132:135], v[176:179], v[52:55]
	v_mfma_f32_16x16x32_bf16 v[48:51], v[168:171], v[176:179], v[48:51]
	v_mfma_f32_16x16x32_bf16 v[36:39], v[132:135], v[184:187], v[36:39]
	v_mfma_f32_16x16x32_bf16 v[32:35], v[168:171], v[184:187], v[32:35]
	v_mfma_f32_16x16x32_bf16 v[20:23], v[132:135], v[196:199], v[20:23]
	v_mfma_f32_16x16x32_bf16 v[16:19], v[168:171], v[196:199], v[16:19]
	v_mfma_f32_16x16x32_bf16 v[4:7], v[132:135], v[204:207], v[4:7]
	v_mfma_f32_16x16x32_bf16 v[0:3], v[168:171], v[204:207], v[0:3]
	v_mfma_f32_16x16x32_bf16 v[52:55], v[148:151], v[180:183], v[52:55]
	v_mfma_f32_16x16x32_bf16 v[48:51], v[172:175], v[180:183], v[48:51]
	v_mfma_f32_16x16x32_bf16 v[36:39], v[148:151], v[188:191], v[36:39]
	v_mfma_f32_16x16x32_bf16 v[32:35], v[172:175], v[188:191], v[32:35]
	v_mfma_f32_16x16x32_bf16 v[20:23], v[148:151], v[200:203], v[20:23]
	v_mfma_f32_16x16x32_bf16 v[16:19], v[172:175], v[200:203], v[16:19]
	v_mfma_f32_16x16x32_bf16 v[4:7], v[148:151], v[208:211], v[4:7]
	v_mfma_f32_16x16x32_bf16 v[0:3], v[172:175], v[208:211], v[0:3]
	s_setprio 0
	s_barrier
	s_add_i32 s53, s53, 2
	s_add_u32 s46, s46, 0x100
	s_addc_u32 s47, s47, 0
	s_add_u32 s23, s23, 0x100
	s_addc_u32 s52, s52, 0
	s_cmp_gt_u32 s53, 13

.LBB0_944:
	s_mov_b64 s[10:11], 0x80
	s_add_i32 s87, s30, 0x18000
	s_lshl_b32 s1, s1, 12
	v_lshl_add_u64 v[4:5], v[4:5], 0, s[10:11]
	s_mov_b32 m0, s87
	s_add_i32 s88, s30, 0x1a000
	s_lshl_b32 s7, s7, 13
	s_and_b32 s1, s1, 0x3000
	s_waitcnt vmcnt(2)
	s_barrier
	global_load_lds_dwordx4 v[4:5], off
	v_lshl_add_u64 v[4:5], v[6:7], 0, s[10:11]
	s_mov_b32 m0, s88
	s_add_i32 s89, s30, 0x8000
	s_add_i32 s90, s30, 0xa000
	global_load_lds_dwordx4 v[4:5], off
	v_lshl_add_u64 v[4:5], v[10:11], 0, s[10:11]
	s_mov_b32 m0, s89
	s_add_u32 s14, s64, 0x40080
	global_load_lds_dwordx4 v[4:5], off
	v_lshl_add_u64 v[4:5], v[8:9], 0, s[10:11]
	s_mov_b32 m0, s90
	s_addc_u32 s15, s65, 0
	s_add_i32 s91, s30, 0x1c000
	global_load_lds_dwordx4 v[4:5], off
	v_lshl_add_u64 v[2:3], v[2:3], 1, s[14:15]
	s_mov_b32 m0, s91
	s_add_i32 s92, s30, 0x1e000
	global_load_lds_dwordx4 v[2:3], off
	v_lshl_add_u64 v[0:1], v[0:1], 1, s[14:15]
	s_mov_b32 m0, s92
	v_lshlrev_b32_e32 v3, 2, v12
	global_load_lds_dwordx4 v[0:1], off
	v_and_b32_e32 v0, 15, v12
	v_and_b32_e32 v1, 48, v12
	v_lshlrev_b32_e32 v0, 6, v0
	v_and_b32_e32 v3, 32, v3
	v_or_b32_e32 v2, v0, v1
	v_bitop3_b32 v0, v0, v3, v1 bitop3:0x36
	v_or_b32_e32 v5, s1, v0
	v_lshlrev_b32_e32 v0, 13, v13
	v_and_b32_e32 v0, 0xffffc000, v0
	v_lshl_add_u32 v0, v14, 10, v0
	v_or_b32_e32 v0, v0, v15
	v_add_u32_sdwa v0, v0, sext(v17) dst_sel:DWORD dst_unused:UNUSED_PAD src0_sel:DWORD src1_sel:WORD_0
	v_bitop3_b32 v4, v2, s7, v3 bitop3:0xde
	v_ashrrev_i32_e32 v1, 31, v0
	v_mov_b64_e32 v[2:3], 0x40080
	v_lshl_add_u64 v[180:181], v[0:1], 1, v[2:3]
	v_lshlrev_b32_e32 v0, 13, v16
	v_and_b32_e32 v0, 0xffffc000, v0
	v_lshl_add_u32 v0, v18, 10, v0
	v_or_b32_e32 v0, v0, v19
	v_add_u32_sdwa v0, v0, sext(v20) dst_sel:DWORD dst_unused:UNUSED_PAD src0_sel:DWORD src1_sel:WORD_0
	s_ashr_i32 s93, s28, 31
	s_ashr_i32 s95, s2, 31
	s_ashr_i32 s96, s2, 3
	s_ashr_i32 s97, s28, 3
	s_and_b32 s74, s2, 7
	v_ashrrev_i32_e32 v1, 31, v0
	s_waitcnt vmcnt(0)
	s_cmpk_lt_u32 s12, 0x100
	v_lshl_add_u64 v[182:183], v[0:1], 1, v[2:3]
	v_add_u32_e32 v0, 0, v5
	s_cselect_b64 s[12:13], -1, 0
	s_add_u32 s38, s26, 0x1e720000
	v_add_u32_e32 v195, 0x10000, v0
	v_add_u32_e32 v198, 0x14000, v0
	v_add_u32_e32 v200, 0x18000, v0
	v_add_u32_e32 v201, 0x1c000, v0
	v_mbcnt_lo_u32_b32 v0, -1, 0
	s_mov_b32 s94, s28
	s_addc_u32 s39, s27, 0
	v_add_u32_e32 v199, 0, v4
	s_add_i32 s78, s30, 0xc000
	s_add_i32 s31, s30, 0xe000
	v_mov_b32_e32 v185, 0
	s_mov_b64 s[14:15], 0x20000
	v_mbcnt_hi_u32_b32 v202, -1, v0
	s_mov_b64 s[16:17], 0x80000
	s_mov_b64 s[20:21], 0x80200
	s_mov_b64 s[40:41], 0x90000
	s_mov_b64 s[42:43], 0x90200
	s_mov_b64 s[44:45], 0xa0000
	s_mov_b64 s[46:47], 0xa0200
	s_mov_b64 s[48:49], 0xb0000
	s_mov_b64 s[50:51], 0xb0200
	s_mov_b64 s[52:53], 0x24000
	s_mov_b64 s[54:55], 0x28000
	s_mov_b64 s[56:57], 0x2c000
	v_mov_b64_e32 v[186:187], 0x1ff
	s_barrier
	s_branch .LBB0_947

.LBB0_957:
	s_add_u32 s1, s64, 0x100
	v_mov_b32_e32 v0, 0
	s_addc_u32 s7, s65, 0
	s_mov_b32 s70, -2
	v_mov_b32_e32 v1, v0
	v_mov_b32_e32 v2, v0
	v_mov_b32_e32 v3, v0
	v_mov_b32_e32 v4, v0
	v_mov_b32_e32 v5, v0
	v_mov_b32_e32 v6, v0
	v_mov_b32_e32 v7, v0
	v_mov_b32_e32 v16, v0
	v_mov_b32_e32 v17, v0
	v_mov_b32_e32 v18, v0
	v_mov_b32_e32 v19, v0
	v_mov_b32_e32 v20, v0
	v_mov_b32_e32 v21, v0
	v_mov_b32_e32 v22, v0
	v_mov_b32_e32 v23, v0
	s_waitcnt vmcnt(0)
	v_mov_b32_e32 v32, v0
	v_mov_b32_e32 v33, v0
	v_mov_b32_e32 v34, v0
	v_mov_b32_e32 v35, v0
	v_mov_b32_e32 v36, v0
	v_mov_b32_e32 v37, v0
	v_mov_b32_e32 v38, v0
	v_mov_b32_e32 v39, v0
	v_mov_b32_e32 v48, v0
	v_mov_b32_e32 v49, v0
	v_mov_b32_e32 v50, v0
	v_mov_b32_e32 v51, v0
	v_mov_b32_e32 v52, v0
	v_mov_b32_e32 v53, v0
	v_mov_b32_e32 v54, v0
	v_mov_b32_e32 v55, v0
	v_mov_b32_e32 v8, v0
	v_mov_b32_e32 v9, v0
	v_mov_b32_e32 v10, v0
	v_mov_b32_e32 v11, v0
	v_mov_b32_e32 v12, v0
	v_mov_b32_e32 v13, v0
	v_mov_b32_e32 v14, v0
	v_mov_b32_e32 v15, v0
	v_mov_b32_e32 v24, v0
	v_mov_b32_e32 v25, v0
	v_mov_b32_e32 v26, v0
	v_mov_b32_e32 v27, v0
	v_mov_b32_e32 v28, v0
	v_mov_b32_e32 v29, v0
	v_mov_b32_e32 v30, v0
	v_mov_b32_e32 v31, v0
	v_mov_b32_e32 v40, v0
	v_mov_b32_e32 v41, v0
	v_mov_b32_e32 v42, v0
	v_mov_b32_e32 v43, v0
	v_mov_b32_e32 v44, v0
	v_mov_b32_e32 v45, v0
	v_mov_b32_e32 v46, v0
	v_mov_b32_e32 v47, v0
	v_mov_b32_e32 v56, v0
	v_mov_b32_e32 v57, v0
	v_mov_b32_e32 v58, v0
	v_mov_b32_e32 v59, v0
	v_mov_b32_e32 v60, v0
	v_mov_b32_e32 v61, v0
	v_mov_b32_e32 v62, v0
	v_mov_b32_e32 v63, v0
	v_mov_b32_e32 v64, v0
	v_mov_b32_e32 v65, v0
	v_mov_b32_e32 v66, v0
	v_mov_b32_e32 v67, v0
	v_mov_b32_e32 v68, v0
	v_mov_b32_e32 v69, v0
	v_mov_b32_e32 v70, v0
	v_mov_b32_e32 v71, v0
	v_mov_b32_e32 v80, v0
	v_mov_b32_e32 v81, v0
	v_mov_b32_e32 v82, v0
	v_mov_b32_e32 v83, v0
	v_mov_b32_e32 v84, v0
	v_mov_b32_e32 v85, v0
	v_mov_b32_e32 v86, v0
	v_mov_b32_e32 v87, v0
	v_mov_b32_e32 v96, v0
	v_mov_b32_e32 v97, v0
	v_mov_b32_e32 v98, v0
	v_mov_b32_e32 v99, v0
	v_mov_b32_e32 v100, v0
	v_mov_b32_e32 v101, v0
	v_mov_b32_e32 v102, v0
	v_mov_b32_e32 v103, v0
	v_mov_b32_e32 v112, v0
	v_mov_b32_e32 v113, v0
	v_mov_b32_e32 v114, v0
	v_mov_b32_e32 v115, v0
	v_mov_b32_e32 v116, v0
	v_mov_b32_e32 v117, v0
	v_mov_b32_e32 v118, v0
	v_mov_b32_e32 v119, v0
	v_mov_b32_e32 v72, v0
	v_mov_b32_e32 v73, v0
	v_mov_b32_e32 v74, v0
	v_mov_b32_e32 v75, v0
	v_mov_b32_e32 v76, v0
	v_mov_b32_e32 v77, v0
	v_mov_b32_e32 v78, v0
	v_mov_b32_e32 v79, v0
	v_mov_b32_e32 v88, v0
	v_mov_b32_e32 v89, v0
	v_mov_b32_e32 v90, v0
	v_mov_b32_e32 v91, v0
	v_mov_b32_e32 v92, v0
	v_mov_b32_e32 v93, v0
	v_mov_b32_e32 v94, v0
	v_mov_b32_e32 v95, v0
	v_mov_b32_e32 v104, v0
	v_mov_b32_e32 v105, v0
	v_mov_b32_e32 v106, v0
	v_mov_b32_e32 v107, v0
	v_mov_b32_e32 v108, v0
	v_mov_b32_e32 v109, v0
	v_mov_b32_e32 v110, v0
	v_mov_b32_e32 v111, v0
	v_mov_b32_e32 v120, v0
	v_mov_b32_e32 v121, v0
	v_mov_b32_e32 v122, v0
	v_mov_b32_e32 v123, v0
	v_mov_b32_e32 v124, v0
	v_mov_b32_e32 v125, v0
	v_mov_b32_e32 v126, v0
	v_mov_b32_e32 v127, v0
	ds_read_b128 v[128:131], v195
	ds_read_b128 v[132:135], v195 offset:1024
	ds_read_b128 v[136:139], v195 offset:2048
	ds_read_b128 v[140:143], v195 offset:3072
	ds_read_b128 v[144:147], v198
	ds_read_b128 v[148:151], v198 offset:1024
	ds_read_b128 v[152:155], v198 offset:2048
	ds_read_b128 v[156:159], v198 offset:3072
	s_add_u32 s64, s4, 0x100
	s_addc_u32 s65, s5, 0
	s_cmp_eq_u32 s70, 12
	s_cselect_b32 s69, s61, s65
	s_cselect_b32 s68, s60, s64
	s_cselect_b32 s67, s59, s7
	s_cselect_b32 s66, s58, s1
	s_mov_b32 m0, s78
	v_lshl_add_u64 v[192:193], s[4:5], 0, v[180:181]
	ds_read_b128 v[160:163], v199
	ds_read_b128 v[164:167], v199 offset:1024
	ds_read_b128 v[168:171], v199 offset:2048
	ds_read_b128 v[172:175], v199 offset:3072
	ds_read_b128 v[188:191], v199 offset:4096
	ds_read_b128 v[204:207], v199 offset:5120
	ds_read_b128 v[208:211], v199 offset:6144
	ds_read_b128 v[212:215], v199 offset:7168
	global_load_lds_dwordx4 v[192:193], off
	v_lshl_add_u64 v[192:193], s[4:5], 0, v[182:183]
	s_mov_b32 m0, s31
	s_nop 0
	global_load_lds_dwordx4 v[192:193], off
	s_waitcnt lgkmcnt(0)
	s_barrier
	s_setprio 1
	s_waitcnt lgkmcnt(0)
	v_mfma_f32_16x16x32_bf16 v[124:127], v[128:131], v[160:163], v[124:127]
	v_mfma_f32_16x16x32_bf16 v[120:123], v[136:139], v[160:163], v[120:123]
	v_mfma_f32_16x16x32_bf16 v[108:111], v[128:131], v[168:171], v[108:111]
	v_mfma_f32_16x16x32_bf16 v[104:107], v[136:139], v[168:171], v[104:107]
	v_mfma_f32_16x16x32_bf16 v[92:95], v[128:131], v[188:191], v[92:95]
	v_mfma_f32_16x16x32_bf16 v[88:91], v[136:139], v[188:191], v[88:91]
	v_mfma_f32_16x16x32_bf16 v[76:79], v[128:131], v[208:211], v[76:79]
	v_mfma_f32_16x16x32_bf16 v[72:75], v[136:139], v[208:211], v[72:75]
	v_mfma_f32_16x16x32_bf16 v[124:127], v[132:135], v[164:167], v[124:127]
	v_mfma_f32_16x16x32_bf16 v[120:123], v[140:143], v[164:167], v[120:123]
	v_mfma_f32_16x16x32_bf16 v[108:111], v[132:135], v[172:175], v[108:111]
	v_mfma_f32_16x16x32_bf16 v[104:107], v[140:143], v[172:175], v[104:107]
	v_mfma_f32_16x16x32_bf16 v[92:95], v[132:135], v[204:207], v[92:95]
	v_mfma_f32_16x16x32_bf16 v[88:91], v[140:143], v[204:207], v[88:91]
	v_mfma_f32_16x16x32_bf16 v[76:79], v[132:135], v[212:215], v[76:79]
	v_mfma_f32_16x16x32_bf16 v[72:75], v[140:143], v[212:215], v[72:75]
	s_setprio 0
	s_setprio 1
	v_mfma_f32_16x16x32_bf16 v[116:119], v[144:147], v[160:163], v[116:119]
	v_mfma_f32_16x16x32_bf16 v[112:115], v[152:155], v[160:163], v[112:115]
	v_mfma_f32_16x16x32_bf16 v[100:103], v[144:147], v[168:171], v[100:103]
	v_mfma_f32_16x16x32_bf16 v[96:99], v[152:155], v[168:171], v[96:99]
	v_mfma_f32_16x16x32_bf16 v[84:87], v[144:147], v[188:191], v[84:87]
	v_mfma_f32_16x16x32_bf16 v[80:83], v[152:155], v[188:191], v[80:83]
	v_mfma_f32_16x16x32_bf16 v[68:71], v[144:147], v[208:211], v[68:71]
	v_mfma_f32_16x16x32_bf16 v[64:67], v[152:155], v[208:211], v[64:67]
	v_mfma_f32_16x16x32_bf16 v[116:119], v[148:151], v[164:167], v[116:119]
	v_mfma_f32_16x16x32_bf16 v[112:115], v[156:159], v[164:167], v[112:115]
	v_mfma_f32_16x16x32_bf16 v[100:103], v[148:151], v[172:175], v[100:103]
	v_mfma_f32_16x16x32_bf16 v[96:99], v[156:159], v[172:175], v[96:99]
	v_mfma_f32_16x16x32_bf16 v[84:87], v[148:151], v[204:207], v[84:87]
	v_mfma_f32_16x16x32_bf16 v[80:83], v[156:159], v[204:207], v[80:83]
	v_mfma_f32_16x16x32_bf16 v[68:71], v[148:151], v[212:215], v[68:71]
	v_mfma_f32_16x16x32_bf16 v[64:67], v[156:159], v[212:215], v[64:67]
	s_setprio 0
	s_barrier
	s_mov_b32 m0, s79
	v_lshl_add_u64 v[192:193], s[66:67], 0, v[176:177]
	s_add_u32 s4, s66, 0x40000
	ds_read_b128 v[160:163], v199 offset:16384
	ds_read_b128 v[164:167], v199 offset:17408
	ds_read_b128 v[168:171], v199 offset:18432
	ds_read_b128 v[172:175], v199 offset:19456
	ds_read_b128 v[188:191], v199 offset:20480
	ds_read_b128 v[204:207], v199 offset:21504
	ds_read_b128 v[208:211], v199 offset:22528
	ds_read_b128 v[212:215], v199 offset:23552
	global_load_lds_dwordx4 v[192:193], off
	v_lshl_add_u64 v[196:197], s[66:67], 0, v[178:179]
	s_mov_b32 m0, s80
	s_addc_u32 s5, s67, 0
	global_load_lds_dwordx4 v[196:197], off
	v_lshl_add_u64 v[216:217], s[4:5], 0, v[176:177]
	s_mov_b32 m0, s81
	v_lshl_add_u64 v[218:219], s[68:69], 0, v[178:179]
	global_load_lds_dwordx4 v[216:217], off
	v_lshl_add_u64 v[216:217], s[4:5], 0, v[178:179]
	s_mov_b32 m0, s82
	s_nop 0
	global_load_lds_dwordx4 v[216:217], off
	v_lshl_add_u64 v[216:217], s[68:69], 0, v[176:177]
	s_mov_b32 m0, s30
	s_nop 0
	global_load_lds_dwordx4 v[216:217], off
	s_mov_b32 m0, s83
	s_nop 0
	global_load_lds_dwordx4 v[218:219], off
	s_waitcnt lgkmcnt(0)
	s_barrier
	s_setprio 1
	s_waitcnt lgkmcnt(0)
	v_mfma_f32_16x16x32_bf16 v[60:63], v[128:131], v[160:163], v[60:63]
	v_mfma_f32_16x16x32_bf16 v[56:59], v[136:139], v[160:163], v[56:59]
	v_mfma_f32_16x16x32_bf16 v[44:47], v[128:131], v[168:171], v[44:47]
	v_mfma_f32_16x16x32_bf16 v[40:43], v[136:139], v[168:171], v[40:43]
	v_mfma_f32_16x16x32_bf16 v[28:31], v[128:131], v[188:191], v[28:31]
	v_mfma_f32_16x16x32_bf16 v[24:27], v[136:139], v[188:191], v[24:27]
	v_mfma_f32_16x16x32_bf16 v[12:15], v[128:131], v[208:211], v[12:15]
	v_mfma_f32_16x16x32_bf16 v[8:11], v[136:139], v[208:211], v[8:11]
	v_mfma_f32_16x16x32_bf16 v[60:63], v[132:135], v[164:167], v[60:63]
	v_mfma_f32_16x16x32_bf16 v[56:59], v[140:143], v[164:167], v[56:59]
	v_mfma_f32_16x16x32_bf16 v[44:47], v[132:135], v[172:175], v[44:47]
	v_mfma_f32_16x16x32_bf16 v[40:43], v[140:143], v[172:175], v[40:43]
	v_mfma_f32_16x16x32_bf16 v[28:31], v[132:135], v[204:207], v[28:31]
	v_mfma_f32_16x16x32_bf16 v[24:27], v[140:143], v[204:207], v[24:27]
	v_mfma_f32_16x16x32_bf16 v[12:15], v[132:135], v[212:215], v[12:15]
	v_mfma_f32_16x16x32_bf16 v[8:11], v[140:143], v[212:215], v[8:11]
	s_setprio 0
	s_setprio 1
	v_mfma_f32_16x16x32_bf16 v[52:55], v[144:147], v[160:163], v[52:55]
	v_mfma_f32_16x16x32_bf16 v[48:51], v[152:155], v[160:163], v[48:51]
	v_mfma_f32_16x16x32_bf16 v[36:39], v[144:147], v[168:171], v[36:39]
	v_mfma_f32_16x16x32_bf16 v[32:35], v[152:155], v[168:171], v[32:35]
	v_mfma_f32_16x16x32_bf16 v[20:23], v[144:147], v[188:191], v[20:23]
	v_mfma_f32_16x16x32_bf16 v[16:19], v[152:155], v[188:191], v[16:19]
	v_mfma_f32_16x16x32_bf16 v[4:7], v[144:147], v[208:211], v[4:7]
	v_mfma_f32_16x16x32_bf16 v[0:3], v[152:155], v[208:211], v[0:3]
	v_mfma_f32_16x16x32_bf16 v[52:55], v[148:151], v[164:167], v[52:55]
	v_mfma_f32_16x16x32_bf16 v[48:51], v[156:159], v[164:167], v[48:51]
	v_mfma_f32_16x16x32_bf16 v[36:39], v[148:151], v[172:175], v[36:39]
	v_mfma_f32_16x16x32_bf16 v[32:35], v[156:159], v[172:175], v[32:35]
	v_mfma_f32_16x16x32_bf16 v[20:23], v[148:151], v[204:207], v[20:23]
	v_mfma_f32_16x16x32_bf16 v[16:19], v[156:159], v[204:207], v[16:19]
	v_mfma_f32_16x16x32_bf16 v[4:7], v[148:151], v[212:215], v[4:7]
	v_mfma_f32_16x16x32_bf16 v[0:3], v[156:159], v[212:215], v[0:3]
	s_setprio 0
	s_barrier
	ds_read_b128 v[128:131], v200
	ds_read_b128 v[132:135], v200 offset:1024
	ds_read_b128 v[136:139], v200 offset:2048
	ds_read_b128 v[140:143], v200 offset:3072
	ds_read_b128 v[144:147], v201
	ds_read_b128 v[148:151], v201 offset:1024
	ds_read_b128 v[152:155], v201 offset:2048
	ds_read_b128 v[156:159], v201 offset:3072
	s_add_u32 s4, s68, 0x40000
	s_addc_u32 s5, s69, 0
	s_mov_b32 m0, s84
	v_lshl_add_u64 v[220:221], s[4:5], 0, v[176:177]
	ds_read_b128 v[160:163], v199 offset:32768
	ds_read_b128 v[164:167], v199 offset:33792
	ds_read_b128 v[168:171], v199 offset:34816
	ds_read_b128 v[172:175], v199 offset:35840
	ds_read_b128 v[188:191], v199 offset:36864
	ds_read_b128 v[204:207], v199 offset:37888
	ds_read_b128 v[208:211], v199 offset:38912
	ds_read_b128 v[212:215], v199 offset:39936
	global_load_lds_dwordx4 v[220:221], off
	v_lshl_add_u64 v[220:221], s[4:5], 0, v[178:179]
	s_mov_b32 m0, s85
	s_nop 0
	global_load_lds_dwordx4 v[220:221], off
	s_waitcnt vmcnt(8)
	s_waitcnt lgkmcnt(0)
	s_barrier
	s_setprio 1
	s_waitcnt lgkmcnt(0)
	v_mfma_f32_16x16x32_bf16 v[124:127], v[128:131], v[160:163], v[124:127]
	v_mfma_f32_16x16x32_bf16 v[120:123], v[136:139], v[160:163], v[120:123]
	v_mfma_f32_16x16x32_bf16 v[108:111], v[128:131], v[168:171], v[108:111]
	v_mfma_f32_16x16x32_bf16 v[104:107], v[136:139], v[168:171], v[104:107]
	v_mfma_f32_16x16x32_bf16 v[92:95], v[128:131], v[188:191], v[92:95]
	v_mfma_f32_16x16x32_bf16 v[88:91], v[136:139], v[188:191], v[88:91]
	v_mfma_f32_16x16x32_bf16 v[76:79], v[128:131], v[208:211], v[76:79]
	v_mfma_f32_16x16x32_bf16 v[72:75], v[136:139], v[208:211], v[72:75]
	v_mfma_f32_16x16x32_bf16 v[124:127], v[132:135], v[164:167], v[124:127]
	v_mfma_f32_16x16x32_bf16 v[120:123], v[140:143], v[164:167], v[120:123]
	v_mfma_f32_16x16x32_bf16 v[108:111], v[132:135], v[172:175], v[108:111]
	v_mfma_f32_16x16x32_bf16 v[104:107], v[140:143], v[172:175], v[104:107]
	v_mfma_f32_16x16x32_bf16 v[92:95], v[132:135], v[204:207], v[92:95]
	v_mfma_f32_16x16x32_bf16 v[88:91], v[140:143], v[204:207], v[88:91]
	v_mfma_f32_16x16x32_bf16 v[76:79], v[132:135], v[212:215], v[76:79]
	v_mfma_f32_16x16x32_bf16 v[72:75], v[140:143], v[212:215], v[72:75]
	s_setprio 0
	s_setprio 1
	v_mfma_f32_16x16x32_bf16 v[116:119], v[144:147], v[160:163], v[116:119]
	v_mfma_f32_16x16x32_bf16 v[112:115], v[152:155], v[160:163], v[112:115]
	v_mfma_f32_16x16x32_bf16 v[100:103], v[144:147], v[168:171], v[100:103]
	v_mfma_f32_16x16x32_bf16 v[96:99], v[152:155], v[168:171], v[96:99]
	v_mfma_f32_16x16x32_bf16 v[84:87], v[144:147], v[188:191], v[84:87]
	v_mfma_f32_16x16x32_bf16 v[80:83], v[152:155], v[188:191], v[80:83]
	v_mfma_f32_16x16x32_bf16 v[68:71], v[144:147], v[208:211], v[68:71]
	v_mfma_f32_16x16x32_bf16 v[64:67], v[152:155], v[208:211], v[64:67]
	v_mfma_f32_16x16x32_bf16 v[116:119], v[148:151], v[164:167], v[116:119]
	v_mfma_f32_16x16x32_bf16 v[112:115], v[156:159], v[164:167], v[112:115]
	v_mfma_f32_16x16x32_bf16 v[100:103], v[148:151], v[172:175], v[100:103]
	v_mfma_f32_16x16x32_bf16 v[96:99], v[156:159], v[172:175], v[96:99]
	v_mfma_f32_16x16x32_bf16 v[84:87], v[148:151], v[204:207], v[84:87]
	v_mfma_f32_16x16x32_bf16 v[80:83], v[156:159], v[204:207], v[80:83]
	v_mfma_f32_16x16x32_bf16 v[68:71], v[148:151], v[212:215], v[68:71]
	v_mfma_f32_16x16x32_bf16 v[64:67], v[156:159], v[212:215], v[64:67]
	s_setprio 0
	s_barrier
	s_mov_b32 m0, s87
	v_lshl_add_u64 v[192:193], v[192:193], 0, s[10:11]
	s_add_u32 s4, s66, 0x40080
	ds_read_b128 v[160:163], v199 offset:49152
	ds_read_b128 v[164:167], v199 offset:50176
	ds_read_b128 v[168:171], v199 offset:51200
	ds_read_b128 v[172:175], v199 offset:52224
	ds_read_b128 v[188:191], v199 offset:53248
	ds_read_b128 v[204:207], v199 offset:54272
	ds_read_b128 v[208:211], v199 offset:55296
	ds_read_b128 v[212:215], v199 offset:56320
	global_load_lds_dwordx4 v[192:193], off
	v_lshl_add_u64 v[192:193], v[196:197], 0, s[10:11]
	s_mov_b32 m0, s88
	s_addc_u32 s5, s67, 0
	global_load_lds_dwordx4 v[192:193], off
	v_lshl_add_u64 v[192:193], s[4:5], 0, v[176:177]
	s_mov_b32 m0, s91
	s_nop 0
	global_load_lds_dwordx4 v[192:193], off
	v_lshl_add_u64 v[192:193], s[4:5], 0, v[178:179]
	s_mov_b32 m0, s92
	s_nop 0
	global_load_lds_dwordx4 v[192:193], off
	v_lshl_add_u64 v[192:193], v[216:217], 0, s[10:11]
	s_mov_b32 m0, s89
	s_nop 0
	global_load_lds_dwordx4 v[192:193], off
	v_lshl_add_u64 v[192:193], v[218:219], 0, s[10:11]
	s_mov_b32 m0, s90
	s_nop 0
	global_load_lds_dwordx4 v[192:193], off
	s_waitcnt vmcnt(8)
	s_waitcnt lgkmcnt(0)
	s_barrier
	s_setprio 1
	s_waitcnt lgkmcnt(0)
	v_mfma_f32_16x16x32_bf16 v[60:63], v[128:131], v[160:163], v[60:63]
	v_mfma_f32_16x16x32_bf16 v[56:59], v[136:139], v[160:163], v[56:59]
	v_mfma_f32_16x16x32_bf16 v[44:47], v[128:131], v[168:171], v[44:47]
	v_mfma_f32_16x16x32_bf16 v[40:43], v[136:139], v[168:171], v[40:43]
	v_mfma_f32_16x16x32_bf16 v[28:31], v[128:131], v[188:191], v[28:31]
	v_mfma_f32_16x16x32_bf16 v[24:27], v[136:139], v[188:191], v[24:27]
	v_mfma_f32_16x16x32_bf16 v[12:15], v[128:131], v[208:211], v[12:15]
	v_mfma_f32_16x16x32_bf16 v[8:11], v[136:139], v[208:211], v[8:11]
	v_mfma_f32_16x16x32_bf16 v[60:63], v[132:135], v[164:167], v[60:63]
	v_mfma_f32_16x16x32_bf16 v[56:59], v[140:143], v[164:167], v[56:59]
	v_mfma_f32_16x16x32_bf16 v[44:47], v[132:135], v[172:175], v[44:47]
	v_mfma_f32_16x16x32_bf16 v[40:43], v[140:143], v[172:175], v[40:43]
	v_mfma_f32_16x16x32_bf16 v[28:31], v[132:135], v[204:207], v[28:31]
	v_mfma_f32_16x16x32_bf16 v[24:27], v[140:143], v[204:207], v[24:27]
	v_mfma_f32_16x16x32_bf16 v[12:15], v[132:135], v[212:215], v[12:15]
	v_mfma_f32_16x16x32_bf16 v[8:11], v[140:143], v[212:215], v[8:11]
	s_setprio 0
	s_setprio 1
	v_mfma_f32_16x16x32_bf16 v[52:55], v[144:147], v[160:163], v[52:55]
	v_mfma_f32_16x16x32_bf16 v[48:51], v[152:155], v[160:163], v[48:51]
	v_mfma_f32_16x16x32_bf16 v[36:39], v[144:147], v[168:171], v[36:39]
	v_mfma_f32_16x16x32_bf16 v[32:35], v[152:155], v[168:171], v[32:35]
	v_mfma_f32_16x16x32_bf16 v[20:23], v[144:147], v[188:191], v[20:23]
	v_mfma_f32_16x16x32_bf16 v[16:19], v[152:155], v[188:191], v[16:19]
	v_mfma_f32_16x16x32_bf16 v[4:7], v[144:147], v[208:211], v[4:7]
	v_mfma_f32_16x16x32_bf16 v[0:3], v[152:155], v[208:211], v[0:3]
	v_mfma_f32_16x16x32_bf16 v[52:55], v[148:151], v[164:167], v[52:55]
	v_mfma_f32_16x16x32_bf16 v[48:51], v[156:159], v[164:167], v[48:51]
	v_mfma_f32_16x16x32_bf16 v[36:39], v[148:151], v[172:175], v[36:39]
	v_mfma_f32_16x16x32_bf16 v[32:35], v[156:159], v[172:175], v[32:35]
	v_mfma_f32_16x16x32_bf16 v[20:23], v[148:151], v[204:207], v[20:23]
	v_mfma_f32_16x16x32_bf16 v[16:19], v[156:159], v[204:207], v[16:19]
	v_mfma_f32_16x16x32_bf16 v[4:7], v[148:151], v[212:215], v[4:7]
	v_mfma_f32_16x16x32_bf16 v[0:3], v[156:159], v[212:215], v[0:3]
	s_setprio 0
	s_barrier
	s_add_i32 s70, s70, 2
	s_add_u32 s1, s1, 0x100
	s_addc_u32 s7, s7, 0
	s_cmp_gt_u32 s70, 13
	s_mov_b64 s[4:5], s[64:65]

.LBB0_1046:
	s_lshl_b32 s4, s4, 12
	s_lshl_b32 s7, s5, 13
	s_and_b32 s10, s4, 0x3000
	s_mov_b64 s[4:5], 0x80
	s_add_i32 s54, s3, 0x18000
	v_lshl_add_u64 v[4:5], v[4:5], 0, s[4:5]
	s_mov_b32 m0, s54
	s_add_i32 s55, s3, 0x1a000
	s_waitcnt vmcnt(2)
	s_barrier
	global_load_lds_dwordx4 v[4:5], off
	v_lshl_add_u64 v[4:5], v[6:7], 0, s[4:5]
	s_mov_b32 m0, s55
	s_add_i32 s56, s3, 0x8000
	s_add_i32 s57, s3, 0xa000
	global_load_lds_dwordx4 v[4:5], off
	v_lshl_add_u64 v[4:5], v[10:11], 0, s[4:5]
	s_mov_b32 m0, s56
	s_add_u32 s8, s40, 0x40080
	global_load_lds_dwordx4 v[4:5], off
	v_lshl_add_u64 v[4:5], v[8:9], 0, s[4:5]
	s_mov_b32 m0, s57
	s_addc_u32 s9, s41, 0
	s_add_i32 s58, s3, 0x1c000
	global_load_lds_dwordx4 v[4:5], off
	v_lshl_add_u64 v[2:3], v[2:3], 1, s[8:9]
	s_mov_b32 m0, s58
	s_add_i32 s59, s3, 0x1e000
	global_load_lds_dwordx4 v[2:3], off
	v_lshl_add_u64 v[0:1], v[0:1], 1, s[8:9]
	s_mov_b32 m0, s59
	v_lshlrev_b32_e32 v3, 2, v12
	global_load_lds_dwordx4 v[0:1], off
	v_and_b32_e32 v0, 15, v12
	v_and_b32_e32 v1, 48, v12
	v_lshlrev_b32_e32 v0, 6, v0
	v_and_b32_e32 v3, 32, v3
	v_or_b32_e32 v2, v0, v1
	v_bitop3_b32 v0, v0, v3, v1 bitop3:0x36
	v_or_b32_e32 v5, s10, v0
	v_lshlrev_b32_e32 v0, 13, v13
	v_and_b32_e32 v0, 0xffffc000, v0
	v_lshl_add_u32 v0, v14, 10, v0
	v_or_b32_e32 v0, v0, v15
	v_add_u32_sdwa v0, v0, sext(v17) dst_sel:DWORD dst_unused:UNUSED_PAD src0_sel:DWORD src1_sel:WORD_0
	v_bitop3_b32 v4, v2, s7, v3 bitop3:0xde
	v_ashrrev_i32_e32 v1, 31, v0
	v_mov_b64_e32 v[2:3], 0x40080
	v_lshl_add_u64 v[132:133], v[0:1], 1, v[2:3]
	v_lshlrev_b32_e32 v0, 13, v16
	v_and_b32_e32 v0, 0xffffc000, v0
	s_ashr_i32 s60, s28, 31
	s_ashr_i32 s62, s2, 31
	s_ashr_i32 s63, s2, 3
	s_ashr_i32 s64, s28, 3
	s_and_b32 s65, s2, 7
	v_lshl_add_u32 v0, v18, 10, v0
	s_cmpk_lt_u32 s6, 0x100
	v_or_b32_e32 v0, v0, v19
	s_cselect_b64 s[6:7], -1, 0
	s_add_u32 s8, s26, 0x1e720000
	v_add_u32_sdwa v0, v0, sext(v20) dst_sel:DWORD dst_unused:UNUSED_PAD src0_sel:DWORD src1_sel:WORD_0
	s_waitcnt vmcnt(0)
	s_addc_u32 s9, s27, 0
	v_ashrrev_i32_e32 v1, 31, v0
	s_add_u32 s66, s26, 0x6300000
	v_lshl_add_u64 v[134:135], v[0:1], 1, v[2:3]
	v_add_u32_e32 v0, 0, v5
	s_mov_b32 s61, s28
	s_addc_u32 s67, s27, 0
	v_add_u32_e32 v141, 0x10000, v0
	v_add_u32_e32 v143, 0x14000, v0
	v_add_u32_e32 v145, 0, v4
	s_add_i32 s68, s3, 0xc000
	s_add_i32 s69, s3, 0xe000
	v_add_u32_e32 v149, 0x18000, v0
	v_add_u32_e32 v150, 0x1c000, v0
	v_mov_b32_e32 v151, 0x358637bd
	v_mov_b32_e32 v137, 0
	s_movk_i32 s70, 0x1600
	s_mov_b32 s71, 0x2c000
	s_mov_b32 s72, 0x42000
	s_mov_b32 s73, 0xb0000
	s_mov_b32 s74, 0xc6000
	s_mov_b32 s75, 0xdc000
	v_mov_b64_e32 v[138:139], 0xaff
	s_barrier
	s_branch .LBB0_1049

.LBB0_1059:
	s_add_u32 s21, s40, 0x100
	v_mov_b32_e32 v0, 0
	s_addc_u32 s46, s41, 0
	s_mov_b32 s47, -2
	v_mov_b32_e32 v1, v0
	v_mov_b32_e32 v2, v0
	v_mov_b32_e32 v3, v0
	v_mov_b32_e32 v4, v0
	v_mov_b32_e32 v5, v0
	v_mov_b32_e32 v6, v0
	v_mov_b32_e32 v7, v0
	v_mov_b32_e32 v16, v0
	v_mov_b32_e32 v17, v0
	v_mov_b32_e32 v18, v0
	v_mov_b32_e32 v19, v0
	v_mov_b32_e32 v20, v0
	v_mov_b32_e32 v21, v0
	v_mov_b32_e32 v22, v0
	v_mov_b32_e32 v23, v0
	s_waitcnt vmcnt(0)
	v_mov_b32_e32 v32, v0
	v_mov_b32_e32 v33, v0
	v_mov_b32_e32 v34, v0
	v_mov_b32_e32 v35, v0
	v_mov_b32_e32 v36, v0
	v_mov_b32_e32 v37, v0
	v_mov_b32_e32 v38, v0
	v_mov_b32_e32 v39, v0
	v_mov_b32_e32 v48, v0
	v_mov_b32_e32 v49, v0
	v_mov_b32_e32 v50, v0
	v_mov_b32_e32 v51, v0
	v_mov_b32_e32 v52, v0
	v_mov_b32_e32 v53, v0
	v_mov_b32_e32 v54, v0
	v_mov_b32_e32 v55, v0
	v_mov_b32_e32 v8, v0
	v_mov_b32_e32 v9, v0
	v_mov_b32_e32 v10, v0
	v_mov_b32_e32 v11, v0
	v_mov_b32_e32 v12, v0
	v_mov_b32_e32 v13, v0
	v_mov_b32_e32 v14, v0
	v_mov_b32_e32 v15, v0
	v_mov_b32_e32 v24, v0
	v_mov_b32_e32 v25, v0
	v_mov_b32_e32 v26, v0
	v_mov_b32_e32 v27, v0
	v_mov_b32_e32 v28, v0
	v_mov_b32_e32 v29, v0
	v_mov_b32_e32 v30, v0
	v_mov_b32_e32 v31, v0
	v_mov_b32_e32 v40, v0
	v_mov_b32_e32 v41, v0
	v_mov_b32_e32 v42, v0
	v_mov_b32_e32 v43, v0
	v_mov_b32_e32 v44, v0
	v_mov_b32_e32 v45, v0
	v_mov_b32_e32 v46, v0
	v_mov_b32_e32 v47, v0
	v_mov_b32_e32 v56, v0
	v_mov_b32_e32 v57, v0
	v_mov_b32_e32 v58, v0
	v_mov_b32_e32 v59, v0
	v_mov_b32_e32 v60, v0
	v_mov_b32_e32 v61, v0
	v_mov_b32_e32 v62, v0
	v_mov_b32_e32 v63, v0
	v_mov_b32_e32 v64, v0
	v_mov_b32_e32 v65, v0
	v_mov_b32_e32 v66, v0
	v_mov_b32_e32 v67, v0
	v_mov_b32_e32 v68, v0
	v_mov_b32_e32 v69, v0
	v_mov_b32_e32 v70, v0
	v_mov_b32_e32 v71, v0
	v_mov_b32_e32 v80, v0
	v_mov_b32_e32 v81, v0
	v_mov_b32_e32 v82, v0
	v_mov_b32_e32 v83, v0
	v_mov_b32_e32 v84, v0
	v_mov_b32_e32 v85, v0
	v_mov_b32_e32 v86, v0
	v_mov_b32_e32 v87, v0
	v_mov_b32_e32 v96, v0
	v_mov_b32_e32 v97, v0
	v_mov_b32_e32 v98, v0
	v_mov_b32_e32 v99, v0
	v_mov_b32_e32 v100, v0
	v_mov_b32_e32 v101, v0
	v_mov_b32_e32 v102, v0
	v_mov_b32_e32 v103, v0
	v_mov_b32_e32 v112, v0
	v_mov_b32_e32 v113, v0
	v_mov_b32_e32 v114, v0
	v_mov_b32_e32 v115, v0
	v_mov_b32_e32 v116, v0
	v_mov_b32_e32 v117, v0
	v_mov_b32_e32 v118, v0
	v_mov_b32_e32 v119, v0
	v_mov_b32_e32 v72, v0
	v_mov_b32_e32 v73, v0
	v_mov_b32_e32 v74, v0
	v_mov_b32_e32 v75, v0
	v_mov_b32_e32 v76, v0
	v_mov_b32_e32 v77, v0
	v_mov_b32_e32 v78, v0
	v_mov_b32_e32 v79, v0
	v_mov_b32_e32 v88, v0
	v_mov_b32_e32 v89, v0
	v_mov_b32_e32 v90, v0
	v_mov_b32_e32 v91, v0
	v_mov_b32_e32 v92, v0
	v_mov_b32_e32 v93, v0
	v_mov_b32_e32 v94, v0
	v_mov_b32_e32 v95, v0
	v_mov_b32_e32 v104, v0
	v_mov_b32_e32 v105, v0
	v_mov_b32_e32 v106, v0
	v_mov_b32_e32 v107, v0
	v_mov_b32_e32 v108, v0
	v_mov_b32_e32 v109, v0
	v_mov_b32_e32 v110, v0
	v_mov_b32_e32 v111, v0
	v_mov_b32_e32 v120, v0
	v_mov_b32_e32 v121, v0
	v_mov_b32_e32 v122, v0
	v_mov_b32_e32 v123, v0
	v_mov_b32_e32 v124, v0
	v_mov_b32_e32 v125, v0
	v_mov_b32_e32 v126, v0
	v_mov_b32_e32 v127, v0
	ds_read_b128 v[152:155], v141
	ds_read_b128 v[156:159], v141 offset:1024
	ds_read_b128 v[160:163], v141 offset:2048
	ds_read_b128 v[164:167], v141 offset:3072
	ds_read_b128 v[168:171], v143
	ds_read_b128 v[172:175], v143 offset:1024
	ds_read_b128 v[176:179], v143 offset:2048
	ds_read_b128 v[180:183], v143 offset:3072
	s_add_u32 s40, s36, 0x100
	s_addc_u32 s41, s37, 0
	s_cmp_eq_u32 s47, 12
	s_cselect_b32 s45, s13, s41
	s_cselect_b32 s44, s12, s40
	s_cselect_b32 s43, s11, s46
	s_cselect_b32 s42, s10, s21
	s_mov_b32 m0, s68
	v_lshl_add_u64 v[146:147], s[36:37], 0, v[132:133]
	ds_read_b128 v[184:187], v145
	ds_read_b128 v[188:191], v145 offset:1024
	ds_read_b128 v[196:199], v145 offset:2048
	ds_read_b128 v[200:203], v145 offset:3072
	ds_read_b128 v[204:207], v145 offset:4096
	ds_read_b128 v[208:211], v145 offset:5120
	ds_read_b128 v[212:215], v145 offset:6144
	ds_read_b128 v[216:219], v145 offset:7168
	global_load_lds_dwordx4 v[146:147], off
	v_lshl_add_u64 v[146:147], s[36:37], 0, v[134:135]
	s_mov_b32 m0, s69
	s_nop 0
	global_load_lds_dwordx4 v[146:147], off
	s_waitcnt lgkmcnt(0)
	s_barrier
	s_setprio 1
	s_waitcnt lgkmcnt(0)
	v_mfma_f32_16x16x32_bf16 v[124:127], v[152:155], v[184:187], v[124:127]
	v_mfma_f32_16x16x32_bf16 v[120:123], v[160:163], v[184:187], v[120:123]
	v_mfma_f32_16x16x32_bf16 v[108:111], v[152:155], v[196:199], v[108:111]
	v_mfma_f32_16x16x32_bf16 v[104:107], v[160:163], v[196:199], v[104:107]
	v_mfma_f32_16x16x32_bf16 v[92:95], v[152:155], v[204:207], v[92:95]
	v_mfma_f32_16x16x32_bf16 v[88:91], v[160:163], v[204:207], v[88:91]
	v_mfma_f32_16x16x32_bf16 v[76:79], v[152:155], v[212:215], v[76:79]
	v_mfma_f32_16x16x32_bf16 v[72:75], v[160:163], v[212:215], v[72:75]
	v_mfma_f32_16x16x32_bf16 v[124:127], v[156:159], v[188:191], v[124:127]
	v_mfma_f32_16x16x32_bf16 v[120:123], v[164:167], v[188:191], v[120:123]
	v_mfma_f32_16x16x32_bf16 v[108:111], v[156:159], v[200:203], v[108:111]
	v_mfma_f32_16x16x32_bf16 v[104:107], v[164:167], v[200:203], v[104:107]
	v_mfma_f32_16x16x32_bf16 v[92:95], v[156:159], v[208:211], v[92:95]
	v_mfma_f32_16x16x32_bf16 v[88:91], v[164:167], v[208:211], v[88:91]
	v_mfma_f32_16x16x32_bf16 v[76:79], v[156:159], v[216:219], v[76:79]
	v_mfma_f32_16x16x32_bf16 v[72:75], v[164:167], v[216:219], v[72:75]
	s_setprio 0
	s_setprio 1
	v_mfma_f32_16x16x32_bf16 v[116:119], v[168:171], v[184:187], v[116:119]
	v_mfma_f32_16x16x32_bf16 v[112:115], v[176:179], v[184:187], v[112:115]
	v_mfma_f32_16x16x32_bf16 v[100:103], v[168:171], v[196:199], v[100:103]
	v_mfma_f32_16x16x32_bf16 v[96:99], v[176:179], v[196:199], v[96:99]
	v_mfma_f32_16x16x32_bf16 v[84:87], v[168:171], v[204:207], v[84:87]
	v_mfma_f32_16x16x32_bf16 v[80:83], v[176:179], v[204:207], v[80:83]
	v_mfma_f32_16x16x32_bf16 v[68:71], v[168:171], v[212:215], v[68:71]
	v_mfma_f32_16x16x32_bf16 v[64:67], v[176:179], v[212:215], v[64:67]
	v_mfma_f32_16x16x32_bf16 v[116:119], v[172:175], v[188:191], v[116:119]
	v_mfma_f32_16x16x32_bf16 v[112:115], v[180:183], v[188:191], v[112:115]
	v_mfma_f32_16x16x32_bf16 v[100:103], v[172:175], v[200:203], v[100:103]
	v_mfma_f32_16x16x32_bf16 v[96:99], v[180:183], v[200:203], v[96:99]
	v_mfma_f32_16x16x32_bf16 v[84:87], v[172:175], v[208:211], v[84:87]
	v_mfma_f32_16x16x32_bf16 v[80:83], v[180:183], v[208:211], v[80:83]
	v_mfma_f32_16x16x32_bf16 v[68:71], v[172:175], v[216:219], v[68:71]
	v_mfma_f32_16x16x32_bf16 v[64:67], v[180:183], v[216:219], v[64:67]
	s_setprio 0
	s_barrier
	s_mov_b32 m0, s17
	v_lshl_add_u64 v[146:147], s[42:43], 0, v[128:129]
	s_add_u32 s36, s42, 0x40000
	ds_read_b128 v[184:187], v145 offset:16384
	ds_read_b128 v[188:191], v145 offset:17408
	ds_read_b128 v[196:199], v145 offset:18432
	ds_read_b128 v[200:203], v145 offset:19456
	ds_read_b128 v[204:207], v145 offset:20480
	ds_read_b128 v[208:211], v145 offset:21504
	ds_read_b128 v[212:215], v145 offset:22528
	ds_read_b128 v[216:219], v145 offset:23552
	global_load_lds_dwordx4 v[146:147], off
	v_lshl_add_u64 v[192:193], s[42:43], 0, v[130:131]
	s_mov_b32 m0, s30
	s_addc_u32 s37, s43, 0
	global_load_lds_dwordx4 v[192:193], off
	v_lshl_add_u64 v[220:221], s[36:37], 0, v[128:129]
	s_mov_b32 m0, s31
	v_lshl_add_u64 v[222:223], s[44:45], 0, v[130:131]
	global_load_lds_dwordx4 v[220:221], off
	v_lshl_add_u64 v[220:221], s[36:37], 0, v[130:131]
	s_mov_b32 m0, s38
	s_nop 0
	global_load_lds_dwordx4 v[220:221], off
	v_lshl_add_u64 v[220:221], s[44:45], 0, v[128:129]
	s_mov_b32 m0, s3
	s_nop 0
	global_load_lds_dwordx4 v[220:221], off
	s_mov_b32 m0, s39
	s_nop 0
	global_load_lds_dwordx4 v[222:223], off
	s_waitcnt lgkmcnt(0)
	s_barrier
	s_setprio 1
	s_waitcnt lgkmcnt(0)
	v_mfma_f32_16x16x32_bf16 v[60:63], v[152:155], v[184:187], v[60:63]
	v_mfma_f32_16x16x32_bf16 v[56:59], v[160:163], v[184:187], v[56:59]
	v_mfma_f32_16x16x32_bf16 v[44:47], v[152:155], v[196:199], v[44:47]
	v_mfma_f32_16x16x32_bf16 v[40:43], v[160:163], v[196:199], v[40:43]
	v_mfma_f32_16x16x32_bf16 v[28:31], v[152:155], v[204:207], v[28:31]
	v_mfma_f32_16x16x32_bf16 v[24:27], v[160:163], v[204:207], v[24:27]
	v_mfma_f32_16x16x32_bf16 v[12:15], v[152:155], v[212:215], v[12:15]
	v_mfma_f32_16x16x32_bf16 v[8:11], v[160:163], v[212:215], v[8:11]
	v_mfma_f32_16x16x32_bf16 v[60:63], v[156:159], v[188:191], v[60:63]
	v_mfma_f32_16x16x32_bf16 v[56:59], v[164:167], v[188:191], v[56:59]
	v_mfma_f32_16x16x32_bf16 v[44:47], v[156:159], v[200:203], v[44:47]
	v_mfma_f32_16x16x32_bf16 v[40:43], v[164:167], v[200:203], v[40:43]
	v_mfma_f32_16x16x32_bf16 v[28:31], v[156:159], v[208:211], v[28:31]
	v_mfma_f32_16x16x32_bf16 v[24:27], v[164:167], v[208:211], v[24:27]
	v_mfma_f32_16x16x32_bf16 v[12:15], v[156:159], v[216:219], v[12:15]
	v_mfma_f32_16x16x32_bf16 v[8:11], v[164:167], v[216:219], v[8:11]
	s_setprio 0
	s_setprio 1
	v_mfma_f32_16x16x32_bf16 v[52:55], v[168:171], v[184:187], v[52:55]
	v_mfma_f32_16x16x32_bf16 v[48:51], v[176:179], v[184:187], v[48:51]
	v_mfma_f32_16x16x32_bf16 v[36:39], v[168:171], v[196:199], v[36:39]
	v_mfma_f32_16x16x32_bf16 v[32:35], v[176:179], v[196:199], v[32:35]
	v_mfma_f32_16x16x32_bf16 v[20:23], v[168:171], v[204:207], v[20:23]
	v_mfma_f32_16x16x32_bf16 v[16:19], v[176:179], v[204:207], v[16:19]
	v_mfma_f32_16x16x32_bf16 v[4:7], v[168:171], v[212:215], v[4:7]
	v_mfma_f32_16x16x32_bf16 v[0:3], v[176:179], v[212:215], v[0:3]
	v_mfma_f32_16x16x32_bf16 v[52:55], v[172:175], v[188:191], v[52:55]
	v_mfma_f32_16x16x32_bf16 v[48:51], v[180:183], v[188:191], v[48:51]
	v_mfma_f32_16x16x32_bf16 v[36:39], v[172:175], v[200:203], v[36:39]
	v_mfma_f32_16x16x32_bf16 v[32:35], v[180:183], v[200:203], v[32:35]
	v_mfma_f32_16x16x32_bf16 v[20:23], v[172:175], v[208:211], v[20:23]
	v_mfma_f32_16x16x32_bf16 v[16:19], v[180:183], v[208:211], v[16:19]
	v_mfma_f32_16x16x32_bf16 v[4:7], v[172:175], v[216:219], v[4:7]
	v_mfma_f32_16x16x32_bf16 v[0:3], v[180:183], v[216:219], v[0:3]
	s_setprio 0
	s_barrier
	ds_read_b128 v[152:155], v149
	ds_read_b128 v[156:159], v149 offset:1024
	ds_read_b128 v[160:163], v149 offset:2048
	ds_read_b128 v[164:167], v149 offset:3072
	ds_read_b128 v[168:171], v150
	ds_read_b128 v[172:175], v150 offset:1024
	ds_read_b128 v[176:179], v150 offset:2048
	ds_read_b128 v[180:183], v150 offset:3072
	s_add_u32 s36, s44, 0x40000
	s_addc_u32 s37, s45, 0
	s_mov_b32 m0, s50
	v_lshl_add_u64 v[224:225], s[36:37], 0, v[128:129]
	ds_read_b128 v[184:187], v145 offset:32768
	ds_read_b128 v[188:191], v145 offset:33792
	ds_read_b128 v[196:199], v145 offset:34816
	ds_read_b128 v[200:203], v145 offset:35840
	ds_read_b128 v[204:207], v145 offset:36864
	ds_read_b128 v[208:211], v145 offset:37888
	ds_read_b128 v[212:215], v145 offset:38912
	ds_read_b128 v[216:219], v145 offset:39936
	global_load_lds_dwordx4 v[224:225], off
	v_lshl_add_u64 v[224:225], s[36:37], 0, v[130:131]
	s_mov_b32 m0, s51
	s_nop 0
	global_load_lds_dwordx4 v[224:225], off
	s_waitcnt vmcnt(8)
	s_waitcnt lgkmcnt(0)
	s_barrier
	s_setprio 1
	s_waitcnt lgkmcnt(0)
	v_mfma_f32_16x16x32_bf16 v[124:127], v[152:155], v[184:187], v[124:127]
	v_mfma_f32_16x16x32_bf16 v[120:123], v[160:163], v[184:187], v[120:123]
	v_mfma_f32_16x16x32_bf16 v[108:111], v[152:155], v[196:199], v[108:111]
	v_mfma_f32_16x16x32_bf16 v[104:107], v[160:163], v[196:199], v[104:107]
	v_mfma_f32_16x16x32_bf16 v[92:95], v[152:155], v[204:207], v[92:95]
	v_mfma_f32_16x16x32_bf16 v[88:91], v[160:163], v[204:207], v[88:91]
	v_mfma_f32_16x16x32_bf16 v[76:79], v[152:155], v[212:215], v[76:79]
	v_mfma_f32_16x16x32_bf16 v[72:75], v[160:163], v[212:215], v[72:75]
	v_mfma_f32_16x16x32_bf16 v[124:127], v[156:159], v[188:191], v[124:127]
	v_mfma_f32_16x16x32_bf16 v[120:123], v[164:167], v[188:191], v[120:123]
	v_mfma_f32_16x16x32_bf16 v[108:111], v[156:159], v[200:203], v[108:111]
	v_mfma_f32_16x16x32_bf16 v[104:107], v[164:167], v[200:203], v[104:107]
	v_mfma_f32_16x16x32_bf16 v[92:95], v[156:159], v[208:211], v[92:95]
	v_mfma_f32_16x16x32_bf16 v[88:91], v[164:167], v[208:211], v[88:91]
	v_mfma_f32_16x16x32_bf16 v[76:79], v[156:159], v[216:219], v[76:79]
	v_mfma_f32_16x16x32_bf16 v[72:75], v[164:167], v[216:219], v[72:75]
	s_setprio 0
	s_setprio 1
	v_mfma_f32_16x16x32_bf16 v[116:119], v[168:171], v[184:187], v[116:119]
	v_mfma_f32_16x16x32_bf16 v[112:115], v[176:179], v[184:187], v[112:115]
	v_mfma_f32_16x16x32_bf16 v[100:103], v[168:171], v[196:199], v[100:103]
	v_mfma_f32_16x16x32_bf16 v[96:99], v[176:179], v[196:199], v[96:99]
	v_mfma_f32_16x16x32_bf16 v[84:87], v[168:171], v[204:207], v[84:87]
	v_mfma_f32_16x16x32_bf16 v[80:83], v[176:179], v[204:207], v[80:83]
	v_mfma_f32_16x16x32_bf16 v[68:71], v[168:171], v[212:215], v[68:71]
	v_mfma_f32_16x16x32_bf16 v[64:67], v[176:179], v[212:215], v[64:67]
	v_mfma_f32_16x16x32_bf16 v[116:119], v[172:175], v[188:191], v[116:119]
	v_mfma_f32_16x16x32_bf16 v[112:115], v[180:183], v[188:191], v[112:115]
	v_mfma_f32_16x16x32_bf16 v[100:103], v[172:175], v[200:203], v[100:103]
	v_mfma_f32_16x16x32_bf16 v[96:99], v[180:183], v[200:203], v[96:99]
	v_mfma_f32_16x16x32_bf16 v[84:87], v[172:175], v[208:211], v[84:87]
	v_mfma_f32_16x16x32_bf16 v[80:83], v[180:183], v[208:211], v[80:83]
	v_mfma_f32_16x16x32_bf16 v[68:71], v[172:175], v[216:219], v[68:71]
	v_mfma_f32_16x16x32_bf16 v[64:67], v[180:183], v[216:219], v[64:67]
	s_setprio 0
	s_barrier
	s_mov_b32 m0, s54
	v_lshl_add_u64 v[146:147], v[146:147], 0, s[4:5]
	s_add_u32 s36, s42, 0x40080
	ds_read_b128 v[184:187], v145 offset:49152
	ds_read_b128 v[188:191], v145 offset:50176
	ds_read_b128 v[196:199], v145 offset:51200
	ds_read_b128 v[200:203], v145 offset:52224
	ds_read_b128 v[204:207], v145 offset:53248
	ds_read_b128 v[208:211], v145 offset:54272
	ds_read_b128 v[212:215], v145 offset:55296
	ds_read_b128 v[216:219], v145 offset:56320
	global_load_lds_dwordx4 v[146:147], off
	v_lshl_add_u64 v[146:147], v[192:193], 0, s[4:5]
	s_mov_b32 m0, s55
	s_addc_u32 s37, s43, 0
	global_load_lds_dwordx4 v[146:147], off
	v_lshl_add_u64 v[146:147], s[36:37], 0, v[128:129]
	s_mov_b32 m0, s58
	s_nop 0
	global_load_lds_dwordx4 v[146:147], off
	v_lshl_add_u64 v[146:147], s[36:37], 0, v[130:131]
	s_mov_b32 m0, s59
	s_nop 0
	global_load_lds_dwordx4 v[146:147], off
	v_lshl_add_u64 v[146:147], v[220:221], 0, s[4:5]
	s_mov_b32 m0, s56
	s_nop 0
	global_load_lds_dwordx4 v[146:147], off
	v_lshl_add_u64 v[146:147], v[222:223], 0, s[4:5]
	s_mov_b32 m0, s57
	s_nop 0
	global_load_lds_dwordx4 v[146:147], off
	s_waitcnt vmcnt(8)
	s_waitcnt lgkmcnt(0)
	s_barrier
	s_setprio 1
	s_waitcnt lgkmcnt(0)
	v_mfma_f32_16x16x32_bf16 v[60:63], v[152:155], v[184:187], v[60:63]
	v_mfma_f32_16x16x32_bf16 v[56:59], v[160:163], v[184:187], v[56:59]
	v_mfma_f32_16x16x32_bf16 v[44:47], v[152:155], v[196:199], v[44:47]
	v_mfma_f32_16x16x32_bf16 v[40:43], v[160:163], v[196:199], v[40:43]
	v_mfma_f32_16x16x32_bf16 v[28:31], v[152:155], v[204:207], v[28:31]
	v_mfma_f32_16x16x32_bf16 v[24:27], v[160:163], v[204:207], v[24:27]
	v_mfma_f32_16x16x32_bf16 v[12:15], v[152:155], v[212:215], v[12:15]
	v_mfma_f32_16x16x32_bf16 v[8:11], v[160:163], v[212:215], v[8:11]
	v_mfma_f32_16x16x32_bf16 v[60:63], v[156:159], v[188:191], v[60:63]
	v_mfma_f32_16x16x32_bf16 v[56:59], v[164:167], v[188:191], v[56:59]
	v_mfma_f32_16x16x32_bf16 v[44:47], v[156:159], v[200:203], v[44:47]
	v_mfma_f32_16x16x32_bf16 v[40:43], v[164:167], v[200:203], v[40:43]
	v_mfma_f32_16x16x32_bf16 v[28:31], v[156:159], v[208:211], v[28:31]
	v_mfma_f32_16x16x32_bf16 v[24:27], v[164:167], v[208:211], v[24:27]
	v_mfma_f32_16x16x32_bf16 v[12:15], v[156:159], v[216:219], v[12:15]
	v_mfma_f32_16x16x32_bf16 v[8:11], v[164:167], v[216:219], v[8:11]
	s_setprio 0
	s_setprio 1
	v_mfma_f32_16x16x32_bf16 v[52:55], v[168:171], v[184:187], v[52:55]
	v_mfma_f32_16x16x32_bf16 v[48:51], v[176:179], v[184:187], v[48:51]
	v_mfma_f32_16x16x32_bf16 v[36:39], v[168:171], v[196:199], v[36:39]
	v_mfma_f32_16x16x32_bf16 v[32:35], v[176:179], v[196:199], v[32:35]
	v_mfma_f32_16x16x32_bf16 v[20:23], v[168:171], v[204:207], v[20:23]
	v_mfma_f32_16x16x32_bf16 v[16:19], v[176:179], v[204:207], v[16:19]
	v_mfma_f32_16x16x32_bf16 v[4:7], v[168:171], v[212:215], v[4:7]
	v_mfma_f32_16x16x32_bf16 v[0:3], v[176:179], v[212:215], v[0:3]
	v_mfma_f32_16x16x32_bf16 v[52:55], v[172:175], v[188:191], v[52:55]
	v_mfma_f32_16x16x32_bf16 v[48:51], v[180:183], v[188:191], v[48:51]
	v_mfma_f32_16x16x32_bf16 v[36:39], v[172:175], v[200:203], v[36:39]
	v_mfma_f32_16x16x32_bf16 v[32:35], v[180:183], v[200:203], v[32:35]
	v_mfma_f32_16x16x32_bf16 v[20:23], v[172:175], v[208:211], v[20:23]
	v_mfma_f32_16x16x32_bf16 v[16:19], v[180:183], v[208:211], v[16:19]
	v_mfma_f32_16x16x32_bf16 v[4:7], v[172:175], v[216:219], v[4:7]
	v_mfma_f32_16x16x32_bf16 v[0:3], v[180:183], v[216:219], v[0:3]
	s_setprio 0
	s_barrier
	s_add_i32 s47, s47, 2
	s_add_u32 s21, s21, 0x100
	s_addc_u32 s46, s46, 0
	s_cmp_gt_u32 s47, 13
	s_mov_b64 s[36:37], s[40:41]

.LBB0_1129:
	s_lshl_b32 s4, s4, 12
	s_lshl_b32 s7, s5, 13
	s_and_b32 s9, s4, 0x3000
	s_mov_b64 s[4:5], 0x80
	s_add_i32 s45, s3, 0x18000
	v_lshl_add_u64 v[4:5], v[4:5], 0, s[4:5]
	s_mov_b32 m0, s45
	s_add_i32 s46, s3, 0x1a000
	s_waitcnt vmcnt(2)
	s_barrier
	global_load_lds_dwordx4 v[4:5], off
	v_lshl_add_u64 v[4:5], v[6:7], 0, s[4:5]
	s_mov_b32 m0, s46
	s_add_i32 s47, s3, 0x8000
	s_add_i32 s48, s3, 0xa000
	global_load_lds_dwordx4 v[4:5], off
	v_lshl_add_u64 v[4:5], v[10:11], 0, s[4:5]
	s_mov_b32 m0, s47
	s_add_u32 s10, s18, 0xb0080
	global_load_lds_dwordx4 v[4:5], off
	v_lshl_add_u64 v[4:5], v[8:9], 0, s[4:5]
	s_mov_b32 m0, s48
	s_addc_u32 s11, s19, 0
	s_add_i32 s49, s3, 0x1c000
	global_load_lds_dwordx4 v[4:5], off
	v_lshl_add_u64 v[2:3], v[2:3], 1, s[10:11]
	s_mov_b32 m0, s49
	s_add_i32 s50, s3, 0x1e000
	global_load_lds_dwordx4 v[2:3], off
	v_lshl_add_u64 v[0:1], v[0:1], 1, s[10:11]
	s_mov_b32 m0, s50
	v_lshlrev_b32_e32 v3, 2, v12
	global_load_lds_dwordx4 v[0:1], off
	v_and_b32_e32 v0, 15, v12
	v_and_b32_e32 v1, 48, v12
	v_lshlrev_b32_e32 v0, 6, v0
	v_and_b32_e32 v3, 32, v3
	v_or_b32_e32 v2, v0, v1
	v_bitop3_b32 v0, v0, v3, v1 bitop3:0x36
	v_or_b32_e32 v5, s9, v0
	v_lshrrev_b32_e32 v1, 1, v13
	v_mul_lo_u32 v0, v15, s8
	s_mov_b32 s9, 0xb000
	v_mad_u64_u32 v[0:1], s[10:11], v1, s9, v[0:1]
	v_or_b32_e32 v0, v0, v14
	v_add_u32_sdwa v0, v0, sext(v17) dst_sel:DWORD dst_unused:UNUSED_PAD src0_sel:DWORD src1_sel:WORD_0
	v_bitop3_b32 v4, v2, s7, v3 bitop3:0xde
	v_ashrrev_i32_e32 v1, 31, v0
	v_mov_b64_e32 v[2:3], 0xb0080
	v_lshl_add_u64 v[132:133], v[0:1], 1, v[2:3]
	v_lshrrev_b32_e32 v1, 1, v16
	v_mul_lo_u32 v0, v18, s8
	v_mad_u64_u32 v[0:1], s[8:9], v1, s9, v[0:1]
	v_or_b32_e32 v0, v0, v19
	v_add_u32_sdwa v0, v0, sext(v20) dst_sel:DWORD dst_unused:UNUSED_PAD src0_sel:DWORD src1_sel:WORD_0
	s_waitcnt vmcnt(0)
	s_ashr_i32 s51, s28, 31
	s_ashr_i32 s52, s2, 31
	s_ashr_i32 s53, s2, 3
	s_ashr_i32 s54, s28, 3
	s_and_b32 s55, s2, 7
	v_ashrrev_i32_e32 v1, 31, v0
	s_cmpk_lt_u32 s6, 0x100
	v_lshl_add_u64 v[134:135], v[0:1], 1, v[2:3]
	v_add_u32_e32 v0, 0, v5
	s_cselect_b64 s[6:7], -1, 0
	v_add_u32_e32 v140, 0x10000, v0
	v_add_u32_e32 v141, 0x14000, v0
	v_add_u32_e32 v142, 0, v4
	s_add_i32 s56, s3, 0xc000
	s_add_i32 s57, s3, 0xe000
	v_add_u32_e32 v143, 0x18000, v0
	v_add_u32_e32 v144, 0x1c000, v0
	v_mov_b32_e32 v137, 0
	s_mov_b32 s58, 0x20000
	s_mov_b32 s59, 0x30000
	s_mov_b32 s60, 0x80000
	s_mov_b32 s61, 0x90000
	s_mov_b32 s62, 0xa0000
	s_mov_b32 s63, 0xb0000
	v_mov_b64_e32 v[138:139], 0x1ff
	s_barrier
	s_branch .LBB0_1132

.LBB0_1142:
	s_add_u32 s15, s18, 0x100
	v_mov_b32_e32 v0, 0
	s_addc_u32 s26, s19, 0
	s_mov_b32 s27, -2
	v_mov_b32_e32 v1, v0
	v_mov_b32_e32 v2, v0
	v_mov_b32_e32 v3, v0
	v_mov_b32_e32 v4, v0
	v_mov_b32_e32 v5, v0
	v_mov_b32_e32 v6, v0
	v_mov_b32_e32 v7, v0
	v_mov_b32_e32 v8, v0
	v_mov_b32_e32 v9, v0
	v_mov_b32_e32 v10, v0
	v_mov_b32_e32 v11, v0
	v_mov_b32_e32 v16, v0
	v_mov_b32_e32 v17, v0
	v_mov_b32_e32 v18, v0
	v_mov_b32_e32 v19, v0
	v_mov_b32_e32 v24, v0
	v_mov_b32_e32 v25, v0
	v_mov_b32_e32 v26, v0
	v_mov_b32_e32 v27, v0
	s_waitcnt vmcnt(0)
	v_mov_b32_e32 v32, v0
	v_mov_b32_e32 v33, v0
	v_mov_b32_e32 v34, v0
	v_mov_b32_e32 v35, v0
	v_mov_b32_e32 v40, v0
	v_mov_b32_e32 v41, v0
	v_mov_b32_e32 v42, v0
	v_mov_b32_e32 v43, v0
	v_mov_b32_e32 v48, v0
	v_mov_b32_e32 v49, v0
	v_mov_b32_e32 v50, v0
	v_mov_b32_e32 v51, v0
	v_mov_b32_e32 v12, v0
	v_mov_b32_e32 v13, v0
	v_mov_b32_e32 v14, v0
	v_mov_b32_e32 v15, v0
	v_mov_b32_e32 v20, v0
	v_mov_b32_e32 v21, v0
	v_mov_b32_e32 v22, v0
	v_mov_b32_e32 v23, v0
	v_mov_b32_e32 v28, v0
	v_mov_b32_e32 v29, v0
	v_mov_b32_e32 v30, v0
	v_mov_b32_e32 v31, v0
	v_mov_b32_e32 v36, v0
	v_mov_b32_e32 v37, v0
	v_mov_b32_e32 v38, v0
	v_mov_b32_e32 v39, v0
	v_mov_b32_e32 v44, v0
	v_mov_b32_e32 v45, v0
	v_mov_b32_e32 v46, v0
	v_mov_b32_e32 v47, v0
	v_mov_b32_e32 v52, v0
	v_mov_b32_e32 v53, v0
	v_mov_b32_e32 v54, v0
	v_mov_b32_e32 v55, v0
	v_mov_b32_e32 v56, v0
	v_mov_b32_e32 v57, v0
	v_mov_b32_e32 v58, v0
	v_mov_b32_e32 v59, v0
	v_mov_b32_e32 v60, v0
	v_mov_b32_e32 v61, v0
	v_mov_b32_e32 v62, v0
	v_mov_b32_e32 v63, v0
	v_mov_b32_e32 v64, v0
	v_mov_b32_e32 v65, v0
	v_mov_b32_e32 v66, v0
	v_mov_b32_e32 v67, v0
	v_mov_b32_e32 v68, v0
	v_mov_b32_e32 v69, v0
	v_mov_b32_e32 v70, v0
	v_mov_b32_e32 v71, v0
	v_mov_b32_e32 v72, v0
	v_mov_b32_e32 v73, v0
	v_mov_b32_e32 v74, v0
	v_mov_b32_e32 v75, v0
	v_mov_b32_e32 v80, v0
	v_mov_b32_e32 v81, v0
	v_mov_b32_e32 v82, v0
	v_mov_b32_e32 v83, v0
	v_mov_b32_e32 v88, v0
	v_mov_b32_e32 v89, v0
	v_mov_b32_e32 v90, v0
	v_mov_b32_e32 v91, v0
	v_mov_b32_e32 v96, v0
	v_mov_b32_e32 v97, v0
	v_mov_b32_e32 v98, v0
	v_mov_b32_e32 v99, v0
	v_mov_b32_e32 v108, v0
	v_mov_b32_e32 v109, v0
	v_mov_b32_e32 v110, v0
	v_mov_b32_e32 v111, v0
	v_mov_b32_e32 v116, v0
	v_mov_b32_e32 v117, v0
	v_mov_b32_e32 v118, v0
	v_mov_b32_e32 v119, v0
	v_mov_b32_e32 v76, v0
	v_mov_b32_e32 v77, v0
	v_mov_b32_e32 v78, v0
	v_mov_b32_e32 v79, v0
	v_mov_b32_e32 v84, v0
	v_mov_b32_e32 v85, v0
	v_mov_b32_e32 v86, v0
	v_mov_b32_e32 v87, v0
	v_mov_b32_e32 v92, v0
	v_mov_b32_e32 v93, v0
	v_mov_b32_e32 v94, v0
	v_mov_b32_e32 v95, v0
	v_mov_b32_e32 v100, v0
	v_mov_b32_e32 v101, v0
	v_mov_b32_e32 v102, v0
	v_mov_b32_e32 v103, v0
	v_mov_b32_e32 v104, v0
	v_mov_b32_e32 v105, v0
	v_mov_b32_e32 v106, v0
	v_mov_b32_e32 v107, v0
	v_mov_b32_e32 v112, v0
	v_mov_b32_e32 v113, v0
	v_mov_b32_e32 v114, v0
	v_mov_b32_e32 v115, v0
	v_mov_b32_e32 v120, v0
	v_mov_b32_e32 v121, v0
	v_mov_b32_e32 v122, v0
	v_mov_b32_e32 v123, v0
	v_mov_b32_e32 v124, v0
	v_mov_b32_e32 v125, v0
	v_mov_b32_e32 v126, v0
	v_mov_b32_e32 v127, v0
	ds_read_b128 v[146:149], v140
	ds_read_b128 v[150:153], v140 offset:1024
	ds_read_b128 v[154:157], v140 offset:2048
	ds_read_b128 v[158:161], v140 offset:3072
	ds_read_b128 v[162:165], v141
	ds_read_b128 v[166:169], v141 offset:1024
	ds_read_b128 v[170:173], v141 offset:2048
	ds_read_b128 v[174:177], v141 offset:3072
	s_add_u32 s18, s16, 0x100
	s_addc_u32 s19, s17, 0
	s_cmp_eq_u32 s27, 40
	s_cselect_b32 s23, s9, s19
	s_cselect_b32 s22, s8, s18
	s_cselect_b32 s21, s11, s26
	s_cselect_b32 s20, s10, s15
	s_mov_b32 m0, s56
	v_lshl_add_u64 v[212:213], s[16:17], 0, v[132:133]
	ds_read_b128 v[178:181], v142
	ds_read_b128 v[182:185], v142 offset:1024
	ds_read_b128 v[186:189], v142 offset:2048
	ds_read_b128 v[190:193], v142 offset:3072
	ds_read_b128 v[196:199], v142 offset:4096
	ds_read_b128 v[200:203], v142 offset:5120
	ds_read_b128 v[204:207], v142 offset:6144
	ds_read_b128 v[208:211], v142 offset:7168
	global_load_lds_dwordx4 v[212:213], off
	v_lshl_add_u64 v[212:213], s[16:17], 0, v[134:135]
	s_mov_b32 m0, s57
	s_nop 0
	global_load_lds_dwordx4 v[212:213], off
	s_waitcnt lgkmcnt(0)
	s_barrier
	s_setprio 1
	s_waitcnt lgkmcnt(0)
	v_mfma_f32_16x16x32_bf16 v[124:127], v[146:149], v[178:181], v[124:127]
	v_mfma_f32_16x16x32_bf16 v[120:123], v[154:157], v[178:181], v[120:123]
	v_mfma_f32_16x16x32_bf16 v[112:115], v[146:149], v[186:189], v[112:115]
	v_mfma_f32_16x16x32_bf16 v[104:107], v[154:157], v[186:189], v[104:107]
	v_mfma_f32_16x16x32_bf16 v[100:103], v[146:149], v[196:199], v[100:103]
	v_mfma_f32_16x16x32_bf16 v[92:95], v[154:157], v[196:199], v[92:95]
	v_mfma_f32_16x16x32_bf16 v[84:87], v[146:149], v[204:207], v[84:87]
	v_mfma_f32_16x16x32_bf16 v[76:79], v[154:157], v[204:207], v[76:79]
	v_mfma_f32_16x16x32_bf16 v[124:127], v[150:153], v[182:185], v[124:127]
	v_mfma_f32_16x16x32_bf16 v[120:123], v[158:161], v[182:185], v[120:123]
	v_mfma_f32_16x16x32_bf16 v[112:115], v[150:153], v[190:193], v[112:115]
	v_mfma_f32_16x16x32_bf16 v[104:107], v[158:161], v[190:193], v[104:107]
	v_mfma_f32_16x16x32_bf16 v[100:103], v[150:153], v[200:203], v[100:103]
	v_mfma_f32_16x16x32_bf16 v[92:95], v[158:161], v[200:203], v[92:95]
	v_mfma_f32_16x16x32_bf16 v[84:87], v[150:153], v[208:211], v[84:87]
	v_mfma_f32_16x16x32_bf16 v[76:79], v[158:161], v[208:211], v[76:79]
	s_setprio 0
	s_setprio 1
	v_mfma_f32_16x16x32_bf16 v[116:119], v[162:165], v[178:181], v[116:119]
	v_mfma_f32_16x16x32_bf16 v[108:111], v[170:173], v[178:181], v[108:111]
	v_mfma_f32_16x16x32_bf16 v[96:99], v[162:165], v[186:189], v[96:99]
	v_mfma_f32_16x16x32_bf16 v[88:91], v[170:173], v[186:189], v[88:91]
	v_mfma_f32_16x16x32_bf16 v[80:83], v[162:165], v[196:199], v[80:83]
	v_mfma_f32_16x16x32_bf16 v[72:75], v[170:173], v[196:199], v[72:75]
	v_mfma_f32_16x16x32_bf16 v[68:71], v[162:165], v[204:207], v[68:71]
	v_mfma_f32_16x16x32_bf16 v[64:67], v[170:173], v[204:207], v[64:67]
	v_mfma_f32_16x16x32_bf16 v[116:119], v[166:169], v[182:185], v[116:119]
	v_mfma_f32_16x16x32_bf16 v[108:111], v[174:177], v[182:185], v[108:111]
	v_mfma_f32_16x16x32_bf16 v[96:99], v[166:169], v[190:193], v[96:99]
	v_mfma_f32_16x16x32_bf16 v[88:91], v[174:177], v[190:193], v[88:91]
	v_mfma_f32_16x16x32_bf16 v[80:83], v[166:169], v[200:203], v[80:83]
	v_mfma_f32_16x16x32_bf16 v[72:75], v[174:177], v[200:203], v[72:75]
	v_mfma_f32_16x16x32_bf16 v[68:71], v[166:169], v[208:211], v[68:71]
	v_mfma_f32_16x16x32_bf16 v[64:67], v[174:177], v[208:211], v[64:67]
	s_setprio 0
	s_barrier
	s_mov_b32 m0, s36
	v_lshl_add_u64 v[212:213], s[20:21], 0, v[128:129]
	s_add_u32 s16, s20, 0xb0000
	ds_read_b128 v[178:181], v142 offset:16384
	ds_read_b128 v[182:185], v142 offset:17408
	ds_read_b128 v[186:189], v142 offset:18432
	ds_read_b128 v[190:193], v142 offset:19456
	ds_read_b128 v[196:199], v142 offset:20480
	ds_read_b128 v[200:203], v142 offset:21504
	ds_read_b128 v[204:207], v142 offset:22528
	ds_read_b128 v[208:211], v142 offset:23552
	global_load_lds_dwordx4 v[212:213], off
	v_lshl_add_u64 v[214:215], s[20:21], 0, v[130:131]
	s_mov_b32 m0, s37
	s_addc_u32 s17, s21, 0
	global_load_lds_dwordx4 v[214:215], off
	v_lshl_add_u64 v[216:217], s[16:17], 0, v[128:129]
	s_mov_b32 m0, s38
	v_lshl_add_u64 v[218:219], s[22:23], 0, v[130:131]
	global_load_lds_dwordx4 v[216:217], off
	v_lshl_add_u64 v[216:217], s[16:17], 0, v[130:131]
	s_mov_b32 m0, s39
	s_nop 0
	global_load_lds_dwordx4 v[216:217], off
	v_lshl_add_u64 v[216:217], s[22:23], 0, v[128:129]
	s_mov_b32 m0, s3
	s_nop 0
	global_load_lds_dwordx4 v[216:217], off
	s_mov_b32 m0, s40
	s_nop 0
	global_load_lds_dwordx4 v[218:219], off
	s_waitcnt lgkmcnt(0)
	s_barrier
	s_setprio 1
	s_waitcnt lgkmcnt(0)
	v_mfma_f32_16x16x32_bf16 v[60:63], v[146:149], v[178:181], v[60:63]
	v_mfma_f32_16x16x32_bf16 v[56:59], v[154:157], v[178:181], v[56:59]
	v_mfma_f32_16x16x32_bf16 v[52:55], v[146:149], v[186:189], v[52:55]
	v_mfma_f32_16x16x32_bf16 v[44:47], v[154:157], v[186:189], v[44:47]
	v_mfma_f32_16x16x32_bf16 v[36:39], v[146:149], v[196:199], v[36:39]
	v_mfma_f32_16x16x32_bf16 v[28:31], v[154:157], v[196:199], v[28:31]
	v_mfma_f32_16x16x32_bf16 v[20:23], v[146:149], v[204:207], v[20:23]
	v_mfma_f32_16x16x32_bf16 v[12:15], v[154:157], v[204:207], v[12:15]
	v_mfma_f32_16x16x32_bf16 v[60:63], v[150:153], v[182:185], v[60:63]
	v_mfma_f32_16x16x32_bf16 v[56:59], v[158:161], v[182:185], v[56:59]
	v_mfma_f32_16x16x32_bf16 v[52:55], v[150:153], v[190:193], v[52:55]
	v_mfma_f32_16x16x32_bf16 v[44:47], v[158:161], v[190:193], v[44:47]
	v_mfma_f32_16x16x32_bf16 v[36:39], v[150:153], v[200:203], v[36:39]
	v_mfma_f32_16x16x32_bf16 v[28:31], v[158:161], v[200:203], v[28:31]
	v_mfma_f32_16x16x32_bf16 v[20:23], v[150:153], v[208:211], v[20:23]
	v_mfma_f32_16x16x32_bf16 v[12:15], v[158:161], v[208:211], v[12:15]
	s_setprio 0
	s_setprio 1
	v_mfma_f32_16x16x32_bf16 v[48:51], v[162:165], v[178:181], v[48:51]
	v_mfma_f32_16x16x32_bf16 v[40:43], v[170:173], v[178:181], v[40:43]
	v_mfma_f32_16x16x32_bf16 v[32:35], v[162:165], v[186:189], v[32:35]
	v_mfma_f32_16x16x32_bf16 v[24:27], v[170:173], v[186:189], v[24:27]
	v_mfma_f32_16x16x32_bf16 v[16:19], v[162:165], v[196:199], v[16:19]
	v_mfma_f32_16x16x32_bf16 v[8:11], v[170:173], v[196:199], v[8:11]
	v_mfma_f32_16x16x32_bf16 v[4:7], v[162:165], v[204:207], v[4:7]
	v_mfma_f32_16x16x32_bf16 v[0:3], v[170:173], v[204:207], v[0:3]
	v_mfma_f32_16x16x32_bf16 v[48:51], v[166:169], v[182:185], v[48:51]
	v_mfma_f32_16x16x32_bf16 v[40:43], v[174:177], v[182:185], v[40:43]
	v_mfma_f32_16x16x32_bf16 v[32:35], v[166:169], v[190:193], v[32:35]
	v_mfma_f32_16x16x32_bf16 v[24:27], v[174:177], v[190:193], v[24:27]
	v_mfma_f32_16x16x32_bf16 v[16:19], v[166:169], v[200:203], v[16:19]
	v_mfma_f32_16x16x32_bf16 v[8:11], v[174:177], v[200:203], v[8:11]
	v_mfma_f32_16x16x32_bf16 v[4:7], v[166:169], v[208:211], v[4:7]
	v_mfma_f32_16x16x32_bf16 v[0:3], v[174:177], v[208:211], v[0:3]
	s_setprio 0
	s_barrier
	ds_read_b128 v[146:149], v143
	ds_read_b128 v[150:153], v143 offset:1024
	ds_read_b128 v[154:157], v143 offset:2048
	ds_read_b128 v[158:161], v143 offset:3072
	ds_read_b128 v[162:165], v144
	ds_read_b128 v[166:169], v144 offset:1024
	ds_read_b128 v[170:173], v144 offset:2048
	ds_read_b128 v[174:177], v144 offset:3072
	s_add_u32 s16, s22, 0xb0000
	s_addc_u32 s17, s23, 0
	s_mov_b32 m0, s41
	v_lshl_add_u64 v[220:221], s[16:17], 0, v[128:129]
	ds_read_b128 v[178:181], v142 offset:32768
	ds_read_b128 v[182:185], v142 offset:33792
	ds_read_b128 v[186:189], v142 offset:34816
	ds_read_b128 v[190:193], v142 offset:35840
	ds_read_b128 v[196:199], v142 offset:36864
	ds_read_b128 v[200:203], v142 offset:37888
	ds_read_b128 v[204:207], v142 offset:38912
	ds_read_b128 v[208:211], v142 offset:39936
	global_load_lds_dwordx4 v[220:221], off
	v_lshl_add_u64 v[220:221], s[16:17], 0, v[130:131]
	s_mov_b32 m0, s42
	s_nop 0
	global_load_lds_dwordx4 v[220:221], off
	s_waitcnt vmcnt(8)
	s_waitcnt lgkmcnt(0)
	s_barrier
	s_setprio 1
	s_waitcnt lgkmcnt(0)
	v_mfma_f32_16x16x32_bf16 v[124:127], v[146:149], v[178:181], v[124:127]
	v_mfma_f32_16x16x32_bf16 v[120:123], v[154:157], v[178:181], v[120:123]
	v_mfma_f32_16x16x32_bf16 v[112:115], v[146:149], v[186:189], v[112:115]
	v_mfma_f32_16x16x32_bf16 v[104:107], v[154:157], v[186:189], v[104:107]
	v_mfma_f32_16x16x32_bf16 v[100:103], v[146:149], v[196:199], v[100:103]
	v_mfma_f32_16x16x32_bf16 v[92:95], v[154:157], v[196:199], v[92:95]
	v_mfma_f32_16x16x32_bf16 v[84:87], v[146:149], v[204:207], v[84:87]
	v_mfma_f32_16x16x32_bf16 v[76:79], v[154:157], v[204:207], v[76:79]
	v_mfma_f32_16x16x32_bf16 v[124:127], v[150:153], v[182:185], v[124:127]
	v_mfma_f32_16x16x32_bf16 v[120:123], v[158:161], v[182:185], v[120:123]
	v_mfma_f32_16x16x32_bf16 v[112:115], v[150:153], v[190:193], v[112:115]
	v_mfma_f32_16x16x32_bf16 v[104:107], v[158:161], v[190:193], v[104:107]
	v_mfma_f32_16x16x32_bf16 v[100:103], v[150:153], v[200:203], v[100:103]
	v_mfma_f32_16x16x32_bf16 v[92:95], v[158:161], v[200:203], v[92:95]
	v_mfma_f32_16x16x32_bf16 v[84:87], v[150:153], v[208:211], v[84:87]
	v_mfma_f32_16x16x32_bf16 v[76:79], v[158:161], v[208:211], v[76:79]
	s_setprio 0
	s_setprio 1
	v_mfma_f32_16x16x32_bf16 v[116:119], v[162:165], v[178:181], v[116:119]
	v_mfma_f32_16x16x32_bf16 v[108:111], v[170:173], v[178:181], v[108:111]
	v_mfma_f32_16x16x32_bf16 v[96:99], v[162:165], v[186:189], v[96:99]
	v_mfma_f32_16x16x32_bf16 v[88:91], v[170:173], v[186:189], v[88:91]
	v_mfma_f32_16x16x32_bf16 v[80:83], v[162:165], v[196:199], v[80:83]
	v_mfma_f32_16x16x32_bf16 v[72:75], v[170:173], v[196:199], v[72:75]
	v_mfma_f32_16x16x32_bf16 v[68:71], v[162:165], v[204:207], v[68:71]
	v_mfma_f32_16x16x32_bf16 v[64:67], v[170:173], v[204:207], v[64:67]
	v_mfma_f32_16x16x32_bf16 v[116:119], v[166:169], v[182:185], v[116:119]
	v_mfma_f32_16x16x32_bf16 v[108:111], v[174:177], v[182:185], v[108:111]
	v_mfma_f32_16x16x32_bf16 v[96:99], v[166:169], v[190:193], v[96:99]
	v_mfma_f32_16x16x32_bf16 v[88:91], v[174:177], v[190:193], v[88:91]
	v_mfma_f32_16x16x32_bf16 v[80:83], v[166:169], v[200:203], v[80:83]
	v_mfma_f32_16x16x32_bf16 v[72:75], v[174:177], v[200:203], v[72:75]
	v_mfma_f32_16x16x32_bf16 v[68:71], v[166:169], v[208:211], v[68:71]
	v_mfma_f32_16x16x32_bf16 v[64:67], v[174:177], v[208:211], v[64:67]
	s_setprio 0
	s_barrier
	s_mov_b32 m0, s45
	v_lshl_add_u64 v[212:213], v[212:213], 0, s[4:5]
	s_add_u32 s16, s20, 0xb0080
	ds_read_b128 v[178:181], v142 offset:49152
	ds_read_b128 v[182:185], v142 offset:50176
	ds_read_b128 v[186:189], v142 offset:51200
	ds_read_b128 v[190:193], v142 offset:52224
	ds_read_b128 v[196:199], v142 offset:53248
	ds_read_b128 v[200:203], v142 offset:54272
	ds_read_b128 v[204:207], v142 offset:55296
	ds_read_b128 v[208:211], v142 offset:56320
	global_load_lds_dwordx4 v[212:213], off
	v_lshl_add_u64 v[212:213], v[214:215], 0, s[4:5]
	s_mov_b32 m0, s46
	s_addc_u32 s17, s21, 0
	global_load_lds_dwordx4 v[212:213], off
	v_lshl_add_u64 v[212:213], s[16:17], 0, v[128:129]
	s_mov_b32 m0, s49
	s_nop 0
	global_load_lds_dwordx4 v[212:213], off
	v_lshl_add_u64 v[212:213], s[16:17], 0, v[130:131]
	s_mov_b32 m0, s50
	s_nop 0
	global_load_lds_dwordx4 v[212:213], off
	v_lshl_add_u64 v[212:213], v[216:217], 0, s[4:5]
	s_mov_b32 m0, s47
	s_nop 0
	global_load_lds_dwordx4 v[212:213], off
	v_lshl_add_u64 v[212:213], v[218:219], 0, s[4:5]
	s_mov_b32 m0, s48
	s_nop 0
	global_load_lds_dwordx4 v[212:213], off
	s_waitcnt vmcnt(8)
	s_waitcnt lgkmcnt(0)
	s_barrier
	s_setprio 1
	s_waitcnt lgkmcnt(0)
	v_mfma_f32_16x16x32_bf16 v[60:63], v[146:149], v[178:181], v[60:63]
	v_mfma_f32_16x16x32_bf16 v[56:59], v[154:157], v[178:181], v[56:59]
	v_mfma_f32_16x16x32_bf16 v[52:55], v[146:149], v[186:189], v[52:55]
	v_mfma_f32_16x16x32_bf16 v[44:47], v[154:157], v[186:189], v[44:47]
	v_mfma_f32_16x16x32_bf16 v[36:39], v[146:149], v[196:199], v[36:39]
	v_mfma_f32_16x16x32_bf16 v[28:31], v[154:157], v[196:199], v[28:31]
	v_mfma_f32_16x16x32_bf16 v[20:23], v[146:149], v[204:207], v[20:23]
	v_mfma_f32_16x16x32_bf16 v[12:15], v[154:157], v[204:207], v[12:15]
	v_mfma_f32_16x16x32_bf16 v[60:63], v[150:153], v[182:185], v[60:63]
	v_mfma_f32_16x16x32_bf16 v[56:59], v[158:161], v[182:185], v[56:59]
	v_mfma_f32_16x16x32_bf16 v[52:55], v[150:153], v[190:193], v[52:55]
	v_mfma_f32_16x16x32_bf16 v[44:47], v[158:161], v[190:193], v[44:47]
	v_mfma_f32_16x16x32_bf16 v[36:39], v[150:153], v[200:203], v[36:39]
	v_mfma_f32_16x16x32_bf16 v[28:31], v[158:161], v[200:203], v[28:31]
	v_mfma_f32_16x16x32_bf16 v[20:23], v[150:153], v[208:211], v[20:23]
	v_mfma_f32_16x16x32_bf16 v[12:15], v[158:161], v[208:211], v[12:15]
	s_setprio 0
	s_setprio 1
	v_mfma_f32_16x16x32_bf16 v[48:51], v[162:165], v[178:181], v[48:51]
	v_mfma_f32_16x16x32_bf16 v[40:43], v[170:173], v[178:181], v[40:43]
	v_mfma_f32_16x16x32_bf16 v[32:35], v[162:165], v[186:189], v[32:35]
	v_mfma_f32_16x16x32_bf16 v[24:27], v[170:173], v[186:189], v[24:27]
	v_mfma_f32_16x16x32_bf16 v[16:19], v[162:165], v[196:199], v[16:19]
	v_mfma_f32_16x16x32_bf16 v[8:11], v[170:173], v[196:199], v[8:11]
	v_mfma_f32_16x16x32_bf16 v[4:7], v[162:165], v[204:207], v[4:7]
	v_mfma_f32_16x16x32_bf16 v[0:3], v[170:173], v[204:207], v[0:3]
	v_mfma_f32_16x16x32_bf16 v[48:51], v[166:169], v[182:185], v[48:51]
	v_mfma_f32_16x16x32_bf16 v[40:43], v[174:177], v[182:185], v[40:43]
	v_mfma_f32_16x16x32_bf16 v[32:35], v[166:169], v[190:193], v[32:35]
	v_mfma_f32_16x16x32_bf16 v[24:27], v[174:177], v[190:193], v[24:27]
	v_mfma_f32_16x16x32_bf16 v[16:19], v[166:169], v[200:203], v[16:19]
	v_mfma_f32_16x16x32_bf16 v[8:11], v[174:177], v[200:203], v[8:11]
	v_mfma_f32_16x16x32_bf16 v[4:7], v[166:169], v[208:211], v[4:7]
	v_mfma_f32_16x16x32_bf16 v[0:3], v[174:177], v[208:211], v[0:3]
	s_setprio 0
	s_barrier
	s_add_i32 s27, s27, 2
	s_add_u32 s15, s15, 0x100
	s_addc_u32 s26, s26, 0
	s_cmp_gt_u32 s27, 41
	s_mov_b64 s[16:17], s[18:19]
